# GEMM epilogues (q/k rope loads, Wo residual, merge gates, down residual): loads prefetched into dead K-loop registers with counted vmcnt waits instead of per-load full drains
# speedup vs baseline: 1.0167x; 1.0167x over previous
;     __device__ __forceinline__ void operator()(const f32x4 (&acc)[2][2][4][2], const Unit& u, int wr, int wc, int fr, int fq) const {
;     ...
;             const bool isk = colt >= 4096; const int cb0 = colt - (isk ? 4096 : 2560); const int grp = cb0 >> 9; const int gh = (cb0 >> 6) + wc;
;             const float* gp = (isk ? kg : qg) + grp * 64 + 8 * fq;
;             f32x4 gn[2][2];
; #pragma unroll
;             for (int bj = 0; bj < 2; ++bj)
; #pragma unroll
;                 for (int n = 0; n < 2; ++n) gn[bj][n] = *(const f32x4*)(gp + 32 * bj + 4 * n);
;             const float sc = isk ? 1.0f : qscale;
;             bf16_t* OB = isk ? KB : QB;
; #pragma unroll
;             for (int ai = 0; ai < 2; ++ai)
; #pragma unroll
;                 for (int m = 0; m < 4; ++m) { const int lrow = row0 + ai * HALF + m * 16; const int pos = lrow & 2047, bb = lrow >> 11;
;                     f32x4 y[2][2]; float ss = 0.f;
; #pragma unroll
;                     for (int bj = 0; bj < 2; ++bj)
; #pragma unroll
;                         for (int n = 0; n < 2; ++n) { y[bj][n] = acc[ai][bj][m][n]; ss += (y[bj][n][0] * y[bj][n][0] + y[bj][n][1] * y[bj][n][1]) + (y[bj][n][2] * y[bj][n][2] + y[bj][n][3] * y[bj][n][3]); }
;                     ss += __shfl_xor(ss, 16); ss += __shfl_xor(ss, 32);
;                     const float rs = __builtin_amdgcn_rsqf(ss * (1.0f / 64.0f) + 1e-6f);
; #pragma unroll
;                     for (int bj = 0; bj < 2; ++bj)
; #pragma unroll
;                         for (int n = 0; n < 2; ++n) y[bj][n] = y[bj][n] * gn[bj][n] * rs;
; #pragma unroll
;                     for (int n = 0; n < 2; ++n) { f32x4 pr;
; #pragma unroll
;                         for (int e = 0; e < 4; ++e) pr[e] = __shfl_xor(y[0][n][e], 16);
;                         if (fq < 2) { const f32x4 t0 = *(const f32x4*)(RT + (size_t)pos * 16 + 8 * n), t1 = *(const f32x4*)(RT + (size_t)pos * 16 + 8 * n + 4);
;                             const float co[4] = {t0[0], t0[2], t1[0], t1[2]}, si[4] = {t0[1], t0[3], t1[1], t1[3]};
; #pragma unroll
;                             for (int e = 0; e < 4; ++e) y[0][n][e] = (fq == 0) ? (y[0][n][e] * co[e] - pr[e] * si[e]) : (y[0][n][e] * co[e] + pr[e] * si[e]); } }
.LBB0_342:
	s_cmp_gt_u32 s74, 15
	s_cselect_b64 s[10:11], -1, 0
	s_and_b64 s[12:13], s[10:11], exec
	s_movk_i32 s12, 0xf600
	s_cselect_b32 s23, 0xfffff000, s12
	s_add_i32 s23, s23, s67
	s_ashr_i32 s40, s23, 9
	s_and_b64 s[12:13], s[10:11], exec
	s_cselect_b32 s41, s19, s17
	s_cselect_b32 s67, s18, s16
	s_lshl_b32 s12, s40, 6
	s_ashr_i32 s13, s12, 31
	s_lshl_b64 s[12:13], s[12:13], 2
	s_add_u32 s12, s67, s12
	s_addc_u32 s13, s41, s13
	global_load_dwordx4 v[142:145], v181, s[12:13] offset:16
	global_load_dwordx4 v[146:149], v181, s[12:13]
	global_load_dwordx4 v[134:137], v181, s[12:13] offset:144
	global_load_dwordx4 v[138:141], v181, s[12:13] offset:128
	v_and_b32_e32 v168, 64, v194
	v_xor_b32_e32 v167, 16, v194
	v_add_u32_e32 v168, 64, v168
	v_cmp_lt_i32_e32 vcc, v167, v168
	v_xor_b32_e32 v169, 32, v194
	v_pk_mul_f32 v[170:171], v[130:131], v[130:131]
	v_cndmask_b32_e32 v167, v194, v167, vcc
	v_cmp_lt_i32_e32 vcc, v169, v168
	v_lshlrev_b32_e32 v167, 2, v167
	s_waitcnt vmcnt(0)
	v_pk_mul_f32 v[130:131], v[130:131], v[146:147]
	v_cndmask_b32_e32 v168, v194, v169, vcc
	v_lshlrev_b32_e32 v183, 2, v168
	v_pk_mul_f32 v[168:169], v[132:133], v[132:133]
	v_pk_mul_f32 v[132:133], v[132:133], v[148:149]
	v_pk_mov_b32 v[172:173], v[170:171], v[168:169] op_sel:[1,0]
	v_mov_b32_e32 v171, v169
	v_pk_add_f32 v[168:169], v[172:173], v[170:171]
	v_pk_mul_f32 v[170:171], v[128:129], v[128:129]
	v_pk_mul_f32 v[172:173], v[126:127], v[126:127]
	v_pk_add_f32 v[168:169], v[168:169], v[168:169] op_sel:[0,1] op_sel_hi:[1,0]
	v_pk_mov_b32 v[174:175], v[172:173], v[170:171] op_sel:[1,0]
	v_mov_b32_e32 v173, v171
	v_pk_add_f32 v[170:171], v[174:175], v[172:173]
	v_mul_f32_e32 v172, v118, v118
	v_mul_f32_e32 v173, v119, v119
	v_pk_add_f32 v[170:171], v[170:171], v[170:171] op_sel:[0,1] op_sel_hi:[1,0]
	v_mov_b32_e32 v169, v172
	v_mov_b32_e32 v171, v173
	v_pk_add_f32 v[168:169], v[168:169], v[170:171]
	v_mul_f32_e32 v170, v123, v123
	v_mul_f32_e32 v172, v125, v125
	v_mul_f32_e32 v174, v120, v120
	v_mul_f32_e32 v175, v121, v121
	v_pk_fma_f32 v[170:171], v[122:123], v[122:123], v[170:171] op_sel_hi:[1,1,0]
	v_pk_fma_f32 v[172:173], v[124:125], v[124:125], v[172:173] op_sel_hi:[1,1,0]
	v_mov_b32_e32 v171, v174
	v_mov_b32_e32 v173, v175
	v_pk_add_f32 v[170:171], v[170:171], v[172:173]
	s_nop 0
	v_pk_add_f32 v[168:169], v[168:169], v[170:171]
	s_nop 0
	v_add_f32_e32 v168, v168, v169
	ds_bpermute_b32 v169, v167, v168
	s_waitcnt lgkmcnt(0)
	v_add_f32_e32 v168, v168, v169
	ds_bpermute_b32 v169, v183, v168
	s_waitcnt lgkmcnt(0)
	v_add_f32_e32 v168, v168, v169
	v_fmamk_f32 v168, v168, 0x3c800000, v188
	v_rsq_f32_e32 v170, v168
	s_nop 0
	v_pk_mul_f32 v[168:169], v[132:133], v[170:171] op_sel_hi:[1,0]
	v_pk_mul_f32 v[132:133], v[130:131], v[170:171] op_sel_hi:[1,0]
	ds_bpermute_b32 v174, v167, v132
	ds_bpermute_b32 v175, v167, v133
	ds_bpermute_b32 v172, v167, v168
	ds_bpermute_b32 v173, v167, v169
	v_lshlrev_b32_e32 v130, 6, v182
	v_mov_b32_e32 v131, v0
	v_lshl_add_u64 v[130:131], s[62:63], 0, v[130:131]
	v_mov_b32_e32 v252, v130
	v_mov_b32_e32 v253, v131
	v_mov_b32_e32 v248, 0x2000
	v_mov_b32_e32 v249, 0
	v_lshl_add_u64 v[250:251], v[130:131], 0, v[248:249]
	s_and_saveexec_b64 s[12:13], s[4:5]
	s_cbranch_execz .LBB0_344
	global_load_dwordx4 v[204:207], v[252:253], off
	global_load_dwordx4 v[208:211], v[252:253], off offset:16
	global_load_dwordx4 v[212:215], v[252:253], off offset:32
	global_load_dwordx4 v[216:219], v[252:253], off offset:48
	global_load_dwordx4 v[220:223], v[252:253], off offset:1024
	global_load_dwordx4 v[224:227], v[252:253], off offset:1040
	global_load_dwordx4 v[228:231], v[252:253], off offset:1056
	global_load_dwordx4 v[232:235], v[252:253], off offset:1072
	s_waitcnt vmcnt(4)
	v_mov_b32_e32 v184, v208
	v_mov_b32_e32 v185, v209
	v_mov_b32_e32 v186, v210
	v_mov_b32_e32 v187, v211
	v_mov_b32_e32 v200, v204
	v_mov_b32_e32 v201, v205
	v_mov_b32_e32 v202, v206
	v_mov_b32_e32 v203, v207
	v_mov_b32_e32 v177, v202
	v_mov_b32_e32 v202, v201
	s_waitcnt lgkmcnt(2)
	v_pk_mul_f32 v[174:175], v[202:203], v[174:175]
	v_mov_b32_e32 v176, v200
	v_cndmask_b32_e64 v175, v175, -v175, s[6:7]
	v_cndmask_b32_e64 v174, v174, -v174, s[6:7]
	v_pk_fma_f32 v[132:133], v[132:133], v[176:177], v[174:175]
	v_mov_b32_e32 v175, v186
	v_mov_b32_e32 v186, v185
	s_waitcnt lgkmcnt(0)
	v_pk_mul_f32 v[172:173], v[186:187], v[172:173]
	v_mov_b32_e32 v174, v184
	v_cndmask_b32_e64 v173, v173, -v173, s[6:7]
	v_cndmask_b32_e64 v172, v172, -v172, s[6:7]
	v_pk_fma_f32 v[168:169], v[168:169], v[174:175], v[172:173]
.LBB0_344:
	s_or_b64 exec, exec, s[12:13]
	v_mov_b32_e32 v171, v170
	v_pk_mul_f32 v[128:129], v[128:129], v[144:145]
	v_pk_mul_f32 v[126:127], v[126:127], v[142:143]
	v_mov_b32_e32 v176, v170
	v_mov_b32_e32 v177, v170
	s_waitcnt lgkmcnt(2)
	v_pk_mul_f32 v[174:175], v[128:129], v[176:177]
	s_waitcnt lgkmcnt(0)
	v_pk_mul_f32 v[172:173], v[126:127], v[170:171]
	ds_bpermute_b32 v128, v167, v172
	ds_bpermute_b32 v129, v167, v173
	ds_bpermute_b32 v126, v167, v174
	ds_bpermute_b32 v127, v167, v175
	s_and_saveexec_b64 s[12:13], s[4:5]
	s_cbranch_execz .LBB0_346
	v_mov_b32_e32 v184, v216
	v_mov_b32_e32 v185, v217
	v_mov_b32_e32 v186, v218
	v_mov_b32_e32 v187, v219
	v_mov_b32_e32 v200, v212
	v_mov_b32_e32 v201, v213
	v_mov_b32_e32 v202, v214
	v_mov_b32_e32 v203, v215
	v_mov_b32_e32 v131, v202
	v_mov_b32_e32 v202, v201
	s_waitcnt lgkmcnt(2)
	v_pk_mul_f32 v[128:129], v[202:203], v[128:129]
	v_mov_b32_e32 v130, v200
	v_cndmask_b32_e64 v129, v129, -v129, s[6:7]
	v_cndmask_b32_e64 v128, v128, -v128, s[6:7]
	v_pk_fma_f32 v[172:173], v[172:173], v[130:131], v[128:129]
	v_mov_b32_e32 v129, v186
	v_mov_b32_e32 v186, v185
	s_waitcnt lgkmcnt(0)
	v_pk_mul_f32 v[126:127], v[186:187], v[126:127]
	v_mov_b32_e32 v128, v184
	v_cndmask_b32_e64 v127, v127, -v127, s[6:7]
	v_cndmask_b32_e64 v126, v126, -v126, s[6:7]
	v_pk_fma_f32 v[174:175], v[174:175], v[128:129], v[126:127]
; __device__ __forceinline__ unsigned cvt_pk_bf16(float lo, float hi) { unsigned r; asm volatile("v_cvt_pk_bf16_f32 %0, %1, %2" : "=v"(r) : "v"(lo), "v"(hi)); return r; }
;     __device__ __forceinline__ static int permpos(int t, int g) { const int dsh = 2 * g; return (t & ((1 << dsh) - 1)) * (2048 >> dsh) + (t >> dsh); }
;     __device__ __forceinline__ void operator()(const f32x4 (&acc)[2][2][4][2], const Unit& u, int wr, int wc, int fr, int fq) const {
;     ...
;                 for (int m = 0; m < 4; ++m) { const int lrow = row0 + ai * HALF + m * 16; const int pos = lrow & 2047, bb = lrow >> 11;
;                     f32x4 y[2][2]; float ss = 0.f;
; #pragma unroll
;                     for (int bj = 0; bj < 2; ++bj)
; #pragma unroll
;                         for (int n = 0; n < 2; ++n) { y[bj][n] = acc[ai][bj][m][n]; ss += (y[bj][n][0] * y[bj][n][0] + y[bj][n][1] * y[bj][n][1]) + (y[bj][n][2] * y[bj][n][2] + y[bj][n][3] * y[bj][n][3]); }
;                     ss += __shfl_xor(ss, 16); ss += __shfl_xor(ss, 32);
;                     const float rs = __builtin_amdgcn_rsqf(ss * (1.0f / 64.0f) + 1e-6f);
; #pragma unroll
;                     for (int bj = 0; bj < 2; ++bj)
; #pragma unroll
;                         for (int n = 0; n < 2; ++n) y[bj][n] = y[bj][n] * gn[bj][n] * rs;
; #pragma unroll
;                     for (int n = 0; n < 2; ++n) { f32x4 pr;
; #pragma unroll
;                         for (int e = 0; e < 4; ++e) pr[e] = __shfl_xor(y[0][n][e], 16);
;                         if (fq < 2) { const f32x4 t0 = *(const f32x4*)(RT + (size_t)pos * 16 + 8 * n), t1 = *(const f32x4*)(RT + (size_t)pos * 16 + 8 * n + 4);
;                             const float co[4] = {t0[0], t0[2], t1[0], t1[2]}, si[4] = {t0[1], t0[3], t1[1], t1[3]};
; #pragma unroll
;                             for (int e = 0; e < 4; ++e) y[0][n][e] = (fq == 0) ? (y[0][n][e] * co[e] - pr[e] * si[e]) : (y[0][n][e] * co[e] + pr[e] * si[e]); } }
;                     bf16_t* rowp = OB + ((size_t)(bb * 24 + gh) * 2048 + permpos(pos, grp)) * 64 + 8 * fq;
; #pragma unroll
;                     for (int bj = 0; bj < 2; ++bj) { const f32x4 v0 = y[bj][0] * sc, v1 = y[bj][1] * sc;
;                         u32x4 w; w.x = cvt_pk_bf16(v0[0], v0[1]); w.y = cvt_pk_bf16(v0[2], v0[3]); w.z = cvt_pk_bf16(v1[0], v1[1]); w.w = cvt_pk_bf16(v1[2], v1[3]);
;                         *(u32x4*)(rowp + 32 * bj) = w; }
.LBB0_346:
	s_or_b64 exec, exec, s[12:13]
	s_ashr_i32 s12, s23, 6
	s_or_b32 s23, s12, s54
	s_waitcnt lgkmcnt(1)
	v_mov_b32_e32 v126, 0x3e38aa3b
	v_cndmask_b32_e64 v126, v126, 1.0, s[10:11]
	s_and_b64 s[10:11], s[10:11], exec
	s_cselect_b32 s11, s27, s82
	s_cselect_b32 s10, s26, s83
	v_lshl_add_u64 v[128:129], v[160:161], 0, s[10:11]
	s_ashr_i32 s10, s22, 11
	s_lshl_b32 s12, s40, 1
	s_mul_i32 s10, s10, 24
	s_lshl_b32 s40, -1, s12
	s_add_i32 s10, s23, s10
	v_pk_mul_f32 v[122:123], v[122:123], v[138:139]
	v_pk_mul_f32 v[118:119], v[118:119], v[134:135]
	s_lshr_b32 s13, 0x800, s12
	s_ashr_i32 s11, s10, 31
	v_pk_mul_f32 v[122:123], v[122:123], v[170:171]
	v_pk_mul_f32 v[170:171], v[118:119], v[170:171]
	v_bitop3_b32 v118, v182, s40, v182 bitop3:0x30
	s_lshl_b64 s[10:11], s[10:11], 18
	v_mul_u32_u24_e32 v118, s13, v118
	v_lshrrev_b32_e32 v119, s12, v182
	v_lshl_add_u64 v[130:131], v[128:129], 0, s[10:11]
	v_pk_mul_f32 v[124:125], v[124:125], v[140:141]
	v_pk_mul_f32 v[120:121], v[120:121], v[136:137]
	v_add_lshl_u32 v118, v118, v119, 7
	v_mov_b32_e32 v119, v0
	v_pk_mul_f32 v[124:125], v[124:125], v[176:177]
	v_pk_mul_f32 v[176:177], v[120:121], v[176:177]
	v_lshl_add_u64 v[184:185], v[130:131], 0, v[118:119]
	s_waitcnt lgkmcnt(0)
	v_pk_mul_f32 v[120:121], v[126:127], v[168:169] op_sel_hi:[0,1]
	v_pk_mul_f32 v[118:119], v[126:127], v[132:133] op_sel_hi:[0,1]
	v_pk_mul_f32 v[132:133], v[126:127], v[174:175] op_sel_hi:[0,1]
	v_pk_mul_f32 v[168:169], v[126:127], v[172:173] op_sel_hi:[0,1]
	v_cvt_pk_bf16_f32 v118, v118, v119
	v_cvt_pk_bf16_f32 v119, v120, v121
	v_cvt_pk_bf16_f32 v120, v168, v169
	v_cvt_pk_bf16_f32 v121, v132, v133
	global_store_dwordx4 v[184:185], v[118:121], off
	s_nop 1
	v_pk_mul_f32 v[120:121], v[126:127], v[124:125] op_sel_hi:[0,1]
	v_pk_mul_f32 v[118:119], v[116:117], v[116:117]
	v_pk_mul_f32 v[124:125], v[114:115], v[114:115]
	v_mul_f32_e32 v127, v102, v102
	v_pk_mov_b32 v[132:133], v[124:125], v[118:119] op_sel:[1,0]
	v_mov_b32_e32 v125, v119
	v_pk_add_f32 v[118:119], v[132:133], v[124:125]
	v_pk_mul_f32 v[124:125], v[112:113], v[112:113]
	v_pk_mul_f32 v[132:133], v[110:111], v[110:111]
	v_pk_add_f32 v[118:119], v[118:119], v[118:119] op_sel:[0,1] op_sel_hi:[1,0]
	v_pk_mov_b32 v[168:169], v[132:133], v[124:125] op_sel:[1,0]
	v_mov_b32_e32 v133, v125
	v_pk_add_f32 v[124:125], v[168:169], v[132:133]
	v_mul_f32_e32 v132, v103, v103
	v_pk_add_f32 v[124:125], v[124:125], v[124:125] op_sel:[0,1] op_sel_hi:[1,0]
	v_mov_b32_e32 v119, v127
	v_mov_b32_e32 v125, v132
	v_pk_add_f32 v[118:119], v[118:119], v[124:125]
	v_mul_f32_e32 v124, v107, v107
	v_mul_f32_e32 v133, v104, v104
	v_pk_fma_f32 v[124:125], v[106:107], v[106:107], v[124:125] op_sel_hi:[1,1,0]
	v_mul_f32_e32 v132, v109, v109
	v_mul_f32_e32 v168, v105, v105
	v_mov_b32_e32 v125, v133
	v_pk_fma_f32 v[132:133], v[108:109], v[108:109], v[132:133] op_sel_hi:[1,1,0]
	v_pk_mul_f32 v[116:117], v[116:117], v[148:149]
	v_mov_b32_e32 v133, v168
	v_pk_add_f32 v[124:125], v[124:125], v[132:133]
	v_pk_mul_f32 v[114:115], v[114:115], v[146:147]
	v_pk_add_f32 v[118:119], v[118:119], v[124:125]
	v_or_b32_e32 v168, 16, v182
	v_add_f32_e32 v127, v118, v119
	ds_bpermute_b32 v132, v167, v127
	v_pk_mul_f32 v[118:119], v[126:127], v[122:123] op_sel_hi:[0,1]
	v_pk_mul_f32 v[122:123], v[126:127], v[176:177] op_sel_hi:[0,1]
	v_pk_mul_f32 v[124:125], v[126:127], v[170:171] op_sel_hi:[0,1]
	v_cvt_pk_bf16_f32 v118, v118, v119
	s_waitcnt lgkmcnt(0)
	v_add_f32_e32 v127, v127, v132
	ds_bpermute_b32 v132, v183, v127
	v_cvt_pk_bf16_f32 v119, v120, v121
	v_cvt_pk_bf16_f32 v120, v124, v125
	v_cvt_pk_bf16_f32 v121, v122, v123
	global_store_dwordx4 v[184:185], v[118:121], off offset:64
	s_waitcnt lgkmcnt(0)
	s_nop 0
	v_add_f32_e32 v118, v127, v132
	v_fmamk_f32 v118, v118, 0x3c800000, v188
	v_rsq_f32_e32 v118, v118
	v_lshlrev_b32_e32 v120, 6, v168
	v_mov_b32_e32 v121, v0
	v_lshl_add_u64 v[120:121], s[62:63], 0, v[120:121]
	v_pk_mul_f32 v[116:117], v[116:117], v[118:119] op_sel_hi:[1,0]
	v_pk_mul_f32 v[114:115], v[114:115], v[118:119] op_sel_hi:[1,0]
	ds_bpermute_b32 v124, v167, v114
	ds_bpermute_b32 v125, v167, v115
	ds_bpermute_b32 v122, v167, v116
	ds_bpermute_b32 v123, v167, v117
	s_and_saveexec_b64 s[10:11], s[4:5]
	s_cbranch_execz .LBB0_348
	global_load_dwordx4 v[204:207], v[252:253], off offset:2048
	global_load_dwordx4 v[208:211], v[252:253], off offset:2064
	global_load_dwordx4 v[212:215], v[252:253], off offset:2080
	global_load_dwordx4 v[216:219], v[252:253], off offset:2096
	s_waitcnt vmcnt(6)
	v_mov_b32_e32 v170, v224
	v_mov_b32_e32 v171, v225
	v_mov_b32_e32 v172, v226
	v_mov_b32_e32 v173, v227
	v_mov_b32_e32 v174, v220
	v_mov_b32_e32 v175, v221
	v_mov_b32_e32 v176, v222
	v_mov_b32_e32 v177, v223
	v_mov_b32_e32 v133, v176
	v_mov_b32_e32 v176, v175
	s_waitcnt lgkmcnt(2)
	v_pk_mul_f32 v[124:125], v[176:177], v[124:125]
	v_mov_b32_e32 v132, v174
	v_cndmask_b32_e64 v125, v125, -v125, s[6:7]
	v_cndmask_b32_e64 v124, v124, -v124, s[6:7]
	v_pk_fma_f32 v[114:115], v[114:115], v[132:133], v[124:125]
	v_mov_b32_e32 v125, v172
	v_mov_b32_e32 v172, v171
	s_waitcnt lgkmcnt(0)
	v_pk_mul_f32 v[122:123], v[172:173], v[122:123]
	v_mov_b32_e32 v124, v170
	v_cndmask_b32_e64 v123, v123, -v123, s[6:7]
	v_cndmask_b32_e64 v122, v122, -v122, s[6:7]
	v_pk_fma_f32 v[116:117], v[116:117], v[124:125], v[122:123]
; __device__ __forceinline__ unsigned cvt_pk_bf16(float lo, float hi) { unsigned r; asm volatile("v_cvt_pk_bf16_f32 %0, %1, %2" : "=v"(r) : "v"(lo), "v"(hi)); return r; }
;     __device__ __forceinline__ void operator()(const f32x4 (&acc)[2][2][4][2], const Unit& u, int wr, int wc, int fr, int fq) const {
;     ...
;                 for (int m = 0; m < 4; ++m) { const int lrow = row0 + ai * HALF + m * 16; const int pos = lrow & 2047, bb = lrow >> 11;
;                     f32x4 y[2][2]; float ss = 0.f;
; #pragma unroll
;                     for (int bj = 0; bj < 2; ++bj)
; #pragma unroll
;                         for (int n = 0; n < 2; ++n) { y[bj][n] = acc[ai][bj][m][n]; ss += (y[bj][n][0] * y[bj][n][0] + y[bj][n][1] * y[bj][n][1]) + (y[bj][n][2] * y[bj][n][2] + y[bj][n][3] * y[bj][n][3]); }
;                     ss += __shfl_xor(ss, 16); ss += __shfl_xor(ss, 32);
;                     const float rs = __builtin_amdgcn_rsqf(ss * (1.0f / 64.0f) + 1e-6f);
; #pragma unroll
;                     for (int bj = 0; bj < 2; ++bj)
; #pragma unroll
;                         for (int n = 0; n < 2; ++n) y[bj][n] = y[bj][n] * gn[bj][n] * rs;
; #pragma unroll
;                     for (int n = 0; n < 2; ++n) { f32x4 pr;
; #pragma unroll
;                         for (int e = 0; e < 4; ++e) pr[e] = __shfl_xor(y[0][n][e], 16);
;                         if (fq < 2) { const f32x4 t0 = *(const f32x4*)(RT + (size_t)pos * 16 + 8 * n), t1 = *(const f32x4*)(RT + (size_t)pos * 16 + 8 * n + 4);
;                             const float co[4] = {t0[0], t0[2], t1[0], t1[2]}, si[4] = {t0[1], t0[3], t1[1], t1[3]};
; #pragma unroll
;                             for (int e = 0; e < 4; ++e) y[0][n][e] = (fq == 0) ? (y[0][n][e] * co[e] - pr[e] * si[e]) : (y[0][n][e] * co[e] + pr[e] * si[e]); } }
;                     bf16_t* rowp = OB + ((size_t)(bb * 24 + gh) * 2048 + permpos(pos, grp)) * 64 + 8 * fq;
; #pragma unroll
;                     for (int bj = 0; bj < 2; ++bj) { const f32x4 v0 = y[bj][0] * sc, v1 = y[bj][1] * sc;
;                         u32x4 w; w.x = cvt_pk_bf16(v0[0], v0[1]); w.y = cvt_pk_bf16(v0[2], v0[3]); w.z = cvt_pk_bf16(v1[0], v1[1]); w.w = cvt_pk_bf16(v1[2], v1[3]);
;                         *(u32x4*)(rowp + 32 * bj) = w; }
;                     asm volatile("" ::: "memory"); }
.LBB0_348:
	s_or_b64 exec, exec, s[10:11]
	v_mov_b32_e32 v119, v118
	v_pk_mul_f32 v[112:113], v[112:113], v[144:145]
	v_pk_mul_f32 v[110:111], v[110:111], v[142:143]
	s_waitcnt lgkmcnt(1)
	v_mov_b32_e32 v122, v118
	s_waitcnt lgkmcnt(0)
	v_mov_b32_e32 v123, v118
	v_pk_mul_f32 v[112:113], v[112:113], v[122:123]
	v_pk_mul_f32 v[110:111], v[110:111], v[118:119]
	ds_bpermute_b32 v132, v167, v110
	ds_bpermute_b32 v133, v167, v111
	ds_bpermute_b32 v124, v167, v112
	ds_bpermute_b32 v125, v167, v113
	s_and_saveexec_b64 s[10:11], s[4:5]
	s_cbranch_execz .LBB0_350
	v_mov_b32_e32 v170, v232
	v_mov_b32_e32 v171, v233
	v_mov_b32_e32 v172, v234
	v_mov_b32_e32 v173, v235
	v_mov_b32_e32 v174, v228
	v_mov_b32_e32 v175, v229
	v_mov_b32_e32 v176, v230
	v_mov_b32_e32 v177, v231
	v_mov_b32_e32 v121, v176
	v_mov_b32_e32 v176, v175
	s_waitcnt lgkmcnt(2)
	v_pk_mul_f32 v[132:133], v[176:177], v[132:133]
	v_mov_b32_e32 v120, v174
	v_cndmask_b32_e64 v133, v133, -v133, s[6:7]
	v_cndmask_b32_e64 v132, v132, -v132, s[6:7]
	v_pk_fma_f32 v[110:111], v[110:111], v[120:121], v[132:133]
	v_mov_b32_e32 v121, v172
	v_mov_b32_e32 v172, v171
	s_waitcnt lgkmcnt(0)
	v_pk_mul_f32 v[124:125], v[172:173], v[124:125]
	v_mov_b32_e32 v120, v170
	v_cndmask_b32_e64 v125, v125, -v125, s[6:7]
	v_cndmask_b32_e64 v124, v124, -v124, s[6:7]
	v_pk_fma_f32 v[112:113], v[112:113], v[120:121], v[124:125]
.LBB0_350:
	s_or_b64 exec, exec, s[10:11]
	s_not_b32 s22, s40
	v_pk_mul_f32 v[106:107], v[106:107], v[138:139]
	v_pk_mul_f32 v[102:103], v[102:103], v[134:135]
	v_pk_mul_f32 v[106:107], v[106:107], v[118:119]
	v_pk_mul_f32 v[118:119], v[102:103], v[118:119]
	v_and_b32_e32 v102, s22, v168
	v_mul_u32_u24_e32 v102, s13, v102
	v_lshrrev_b32_e32 v103, s12, v168
	v_mov_b32_e32 v127, v126
	v_pk_mul_f32 v[108:109], v[108:109], v[140:141]
	v_pk_mul_f32 v[104:105], v[104:105], v[136:137]
	v_add_lshl_u32 v102, v102, v103, 7
	v_mov_b32_e32 v103, v0
	s_waitcnt lgkmcnt(1)
	v_mov_b32_e32 v124, v126
	s_waitcnt lgkmcnt(0)
	v_mov_b32_e32 v125, v126
	v_pk_mul_f32 v[108:109], v[108:109], v[122:123]
	v_pk_mul_f32 v[120:121], v[104:105], v[122:123]
	v_lshl_add_u64 v[122:123], v[130:131], 0, v[102:103]
	v_pk_mul_f32 v[104:105], v[124:125], v[116:117]
	v_pk_mul_f32 v[102:103], v[126:127], v[114:115]
	v_pk_mul_f32 v[112:113], v[124:125], v[112:113]
	v_pk_mul_f32 v[110:111], v[126:127], v[110:111]
	v_cvt_pk_bf16_f32 v102, v102, v103
	v_cvt_pk_bf16_f32 v103, v104, v105
	s_nop 0
	v_cvt_pk_bf16_f32 v104, v110, v111
	v_cvt_pk_bf16_f32 v105, v112, v113
	global_store_dwordx4 v[122:123], v[102:105], off
	s_nop 1
	v_pk_mul_f32 v[104:105], v[124:125], v[108:109]
	v_pk_mul_f32 v[102:103], v[100:101], v[100:101]
	v_pk_mul_f32 v[108:109], v[98:99], v[98:99]
	v_pk_mul_f32 v[100:101], v[100:101], v[148:149]
	v_pk_mov_b32 v[110:111], v[108:109], v[102:103] op_sel:[1,0]
	v_mov_b32_e32 v109, v103
	v_pk_add_f32 v[102:103], v[110:111], v[108:109]
	v_pk_mul_f32 v[108:109], v[96:97], v[96:97]
	v_pk_mul_f32 v[110:111], v[94:95], v[94:95]
	v_pk_add_f32 v[102:103], v[102:103], v[102:103] op_sel:[0,1] op_sel_hi:[1,0]
	v_pk_mov_b32 v[112:113], v[110:111], v[108:109] op_sel:[1,0]
	v_mov_b32_e32 v111, v109
	v_pk_add_f32 v[108:109], v[112:113], v[110:111]
	v_mul_f32_e32 v110, v86, v86
	v_mul_f32_e32 v111, v87, v87
	v_pk_add_f32 v[108:109], v[108:109], v[108:109] op_sel:[0,1] op_sel_hi:[1,0]
	v_mov_b32_e32 v103, v110
	v_mov_b32_e32 v109, v111
	v_pk_add_f32 v[102:103], v[102:103], v[108:109]
	v_mul_f32_e32 v108, v91, v91
	v_mul_f32_e32 v110, v93, v93
	v_mul_f32_e32 v112, v88, v88
	v_mul_f32_e32 v113, v89, v89
	v_pk_fma_f32 v[108:109], v[90:91], v[90:91], v[108:109] op_sel_hi:[1,1,0]
	v_pk_fma_f32 v[110:111], v[92:93], v[92:93], v[110:111] op_sel_hi:[1,1,0]
	v_mov_b32_e32 v109, v112
	v_mov_b32_e32 v111, v113
	v_pk_add_f32 v[108:109], v[108:109], v[110:111]
	v_pk_mul_f32 v[98:99], v[98:99], v[146:147]
	v_pk_add_f32 v[102:103], v[102:103], v[108:109]
	v_pk_mul_f32 v[108:109], v[126:127], v[118:119]
	v_add_f32_e32 v110, v102, v103
	ds_bpermute_b32 v111, v167, v110
	v_pk_mul_f32 v[102:103], v[126:127], v[106:107]
	v_pk_mul_f32 v[106:107], v[124:125], v[120:121]
	v_cvt_pk_bf16_f32 v102, v102, v103
	v_cvt_pk_bf16_f32 v103, v104, v105
	s_waitcnt lgkmcnt(0)
	v_add_f32_e32 v110, v110, v111
	ds_bpermute_b32 v111, v183, v110
	v_cvt_pk_bf16_f32 v104, v108, v109
	v_cvt_pk_bf16_f32 v105, v106, v107
	global_store_dwordx4 v[122:123], v[102:105], off offset:64
	v_or_b32_e32 v112, 32, v182
	s_waitcnt lgkmcnt(0)
	v_add_f32_e32 v102, v110, v111
	v_fmamk_f32 v102, v102, 0x3c800000, v188
	v_rsq_f32_e32 v102, v102
	v_lshlrev_b32_e32 v104, 6, v112
	v_mov_b32_e32 v105, v0
	v_lshl_add_u64 v[104:105], s[62:63], 0, v[104:105]
	v_pk_mul_f32 v[100:101], v[100:101], v[102:103] op_sel_hi:[1,0]
	v_pk_mul_f32 v[98:99], v[98:99], v[102:103] op_sel_hi:[1,0]
	ds_bpermute_b32 v108, v167, v98
	ds_bpermute_b32 v109, v167, v99
	ds_bpermute_b32 v106, v167, v100
	ds_bpermute_b32 v107, v167, v101
	s_and_saveexec_b64 s[10:11], s[4:5]
	s_cbranch_execz .LBB0_352
	global_load_dwordx4 v[220:223], v[252:253], off offset:3072
	global_load_dwordx4 v[224:227], v[252:253], off offset:3088
	global_load_dwordx4 v[228:231], v[252:253], off offset:3104
	global_load_dwordx4 v[232:235], v[252:253], off offset:3120
	s_waitcnt vmcnt(6)
	v_mov_b32_e32 v114, v208
	v_mov_b32_e32 v115, v209
	v_mov_b32_e32 v116, v210
	v_mov_b32_e32 v117, v211
	v_mov_b32_e32 v118, v204
	v_mov_b32_e32 v119, v205
	v_mov_b32_e32 v120, v206
	v_mov_b32_e32 v121, v207
	v_mov_b32_e32 v111, v120
	v_mov_b32_e32 v120, v119
	s_waitcnt lgkmcnt(2)
	v_pk_mul_f32 v[108:109], v[120:121], v[108:109]
	v_mov_b32_e32 v110, v118
	v_cndmask_b32_e64 v109, v109, -v109, s[6:7]
	v_cndmask_b32_e64 v108, v108, -v108, s[6:7]
	v_pk_fma_f32 v[98:99], v[98:99], v[110:111], v[108:109]
	v_mov_b32_e32 v109, v116
	v_mov_b32_e32 v116, v115
	s_waitcnt lgkmcnt(0)
	v_pk_mul_f32 v[106:107], v[116:117], v[106:107]
	v_mov_b32_e32 v108, v114
	v_cndmask_b32_e64 v107, v107, -v107, s[6:7]
	v_cndmask_b32_e64 v106, v106, -v106, s[6:7]
	v_pk_fma_f32 v[100:101], v[100:101], v[108:109], v[106:107]
; __device__ __forceinline__ unsigned cvt_pk_bf16(float lo, float hi) { unsigned r; asm volatile("v_cvt_pk_bf16_f32 %0, %1, %2" : "=v"(r) : "v"(lo), "v"(hi)); return r; }
;     __device__ __forceinline__ void operator()(const f32x4 (&acc)[2][2][4][2], const Unit& u, int wr, int wc, int fr, int fq) const {
;     ...
;                 for (int m = 0; m < 4; ++m) { const int lrow = row0 + ai * HALF + m * 16; const int pos = lrow & 2047, bb = lrow >> 11;
;                     f32x4 y[2][2]; float ss = 0.f;
; #pragma unroll
;                     for (int bj = 0; bj < 2; ++bj)
; #pragma unroll
;                         for (int n = 0; n < 2; ++n) { y[bj][n] = acc[ai][bj][m][n]; ss += (y[bj][n][0] * y[bj][n][0] + y[bj][n][1] * y[bj][n][1]) + (y[bj][n][2] * y[bj][n][2] + y[bj][n][3] * y[bj][n][3]); }
;                     ss += __shfl_xor(ss, 16); ss += __shfl_xor(ss, 32);
;                     const float rs = __builtin_amdgcn_rsqf(ss * (1.0f / 64.0f) + 1e-6f);
; #pragma unroll
;                     for (int bj = 0; bj < 2; ++bj)
; #pragma unroll
;                         for (int n = 0; n < 2; ++n) y[bj][n] = y[bj][n] * gn[bj][n] * rs;
; #pragma unroll
;                     for (int n = 0; n < 2; ++n) { f32x4 pr;
; #pragma unroll
;                         for (int e = 0; e < 4; ++e) pr[e] = __shfl_xor(y[0][n][e], 16);
;                         if (fq < 2) { const f32x4 t0 = *(const f32x4*)(RT + (size_t)pos * 16 + 8 * n), t1 = *(const f32x4*)(RT + (size_t)pos * 16 + 8 * n + 4);
;                             const float co[4] = {t0[0], t0[2], t1[0], t1[2]}, si[4] = {t0[1], t0[3], t1[1], t1[3]};
; #pragma unroll
;                             for (int e = 0; e < 4; ++e) y[0][n][e] = (fq == 0) ? (y[0][n][e] * co[e] - pr[e] * si[e]) : (y[0][n][e] * co[e] + pr[e] * si[e]); } }
;                     bf16_t* rowp = OB + ((size_t)(bb * 24 + gh) * 2048 + permpos(pos, grp)) * 64 + 8 * fq;
; #pragma unroll
;                     for (int bj = 0; bj < 2; ++bj) { const f32x4 v0 = y[bj][0] * sc, v1 = y[bj][1] * sc;
;                         u32x4 w; w.x = cvt_pk_bf16(v0[0], v0[1]); w.y = cvt_pk_bf16(v0[2], v0[3]); w.z = cvt_pk_bf16(v1[0], v1[1]); w.w = cvt_pk_bf16(v1[2], v1[3]);
;                         *(u32x4*)(rowp + 32 * bj) = w; }
;                     asm volatile("" ::: "memory"); }
.LBB0_352:
	s_or_b64 exec, exec, s[10:11]
	v_mov_b32_e32 v103, v102
	v_pk_mul_f32 v[96:97], v[96:97], v[144:145]
	v_pk_mul_f32 v[94:95], v[94:95], v[142:143]
	s_waitcnt lgkmcnt(1)
	v_mov_b32_e32 v106, v102
	s_waitcnt lgkmcnt(0)
	v_mov_b32_e32 v107, v102
	v_pk_mul_f32 v[96:97], v[96:97], v[106:107]
	v_pk_mul_f32 v[94:95], v[94:95], v[102:103]
	ds_bpermute_b32 v110, v167, v94
	ds_bpermute_b32 v111, v167, v95
	ds_bpermute_b32 v108, v167, v96
	ds_bpermute_b32 v109, v167, v97
	s_and_saveexec_b64 s[10:11], s[4:5]
	s_cbranch_execz .LBB0_354
	v_mov_b32_e32 v114, v216
	v_mov_b32_e32 v115, v217
	v_mov_b32_e32 v116, v218
	v_mov_b32_e32 v117, v219
	v_mov_b32_e32 v118, v212
	v_mov_b32_e32 v119, v213
	v_mov_b32_e32 v120, v214
	v_mov_b32_e32 v121, v215
	v_mov_b32_e32 v105, v120
	v_mov_b32_e32 v120, v119
	s_waitcnt lgkmcnt(2)
	v_pk_mul_f32 v[110:111], v[120:121], v[110:111]
	v_mov_b32_e32 v104, v118
	v_cndmask_b32_e64 v111, v111, -v111, s[6:7]
	v_cndmask_b32_e64 v110, v110, -v110, s[6:7]
	v_pk_fma_f32 v[94:95], v[94:95], v[104:105], v[110:111]
	v_mov_b32_e32 v105, v116
	v_mov_b32_e32 v116, v115
	s_waitcnt lgkmcnt(0)
	v_pk_mul_f32 v[108:109], v[116:117], v[108:109]
	v_mov_b32_e32 v104, v114
	v_cndmask_b32_e64 v109, v109, -v109, s[6:7]
	v_cndmask_b32_e64 v108, v108, -v108, s[6:7]
	v_pk_fma_f32 v[96:97], v[96:97], v[104:105], v[108:109]
.LBB0_354:
	s_or_b64 exec, exec, s[10:11]
	v_pk_mul_f32 v[90:91], v[90:91], v[138:139]
	v_pk_mul_f32 v[86:87], v[86:87], v[134:135]
	v_pk_mul_f32 v[90:91], v[90:91], v[102:103]
	v_pk_mul_f32 v[102:103], v[86:87], v[102:103]
	v_and_b32_e32 v86, s22, v112
	v_mul_u32_u24_e32 v86, s13, v86
	v_lshrrev_b32_e32 v87, s12, v112
	v_pk_mul_f32 v[92:93], v[92:93], v[140:141]
	v_pk_mul_f32 v[88:89], v[88:89], v[136:137]
	v_add_lshl_u32 v86, v86, v87, 7
	v_mov_b32_e32 v87, v0
	s_waitcnt lgkmcnt(1)
	v_mov_b32_e32 v108, v126
	s_waitcnt lgkmcnt(0)
	v_mov_b32_e32 v109, v126
	v_pk_mul_f32 v[92:93], v[92:93], v[106:107]
	v_pk_mul_f32 v[104:105], v[88:89], v[106:107]
	v_lshl_add_u64 v[106:107], v[130:131], 0, v[86:87]
	v_pk_mul_f32 v[88:89], v[108:109], v[100:101]
	v_pk_mul_f32 v[86:87], v[126:127], v[98:99]
	v_pk_mul_f32 v[96:97], v[108:109], v[96:97]
	v_pk_mul_f32 v[94:95], v[126:127], v[94:95]
	v_cvt_pk_bf16_f32 v86, v86, v87
	v_cvt_pk_bf16_f32 v87, v88, v89
	s_nop 0
	v_cvt_pk_bf16_f32 v88, v94, v95
	v_cvt_pk_bf16_f32 v89, v96, v97
	global_store_dwordx4 v[106:107], v[86:89], off
	s_nop 1
	v_pk_mul_f32 v[88:89], v[108:109], v[92:93]
	v_pk_mul_f32 v[86:87], v[80:81], v[80:81]
	v_pk_mul_f32 v[92:93], v[78:79], v[78:79]
	v_pk_mul_f32 v[80:81], v[80:81], v[148:149]
	v_pk_mov_b32 v[94:95], v[92:93], v[86:87] op_sel:[1,0]
	v_mov_b32_e32 v93, v87
	v_pk_add_f32 v[86:87], v[94:95], v[92:93]
	v_pk_mul_f32 v[92:93], v[76:77], v[76:77]
	v_pk_mul_f32 v[94:95], v[74:75], v[74:75]
	v_pk_add_f32 v[86:87], v[86:87], v[86:87] op_sel:[0,1] op_sel_hi:[1,0]
	v_pk_mov_b32 v[96:97], v[94:95], v[92:93] op_sel:[1,0]
	v_mov_b32_e32 v95, v93
	v_pk_add_f32 v[92:93], v[96:97], v[94:95]
	v_mul_f32_e32 v94, v66, v66
	v_mul_f32_e32 v95, v67, v67
	v_pk_add_f32 v[92:93], v[92:93], v[92:93] op_sel:[0,1] op_sel_hi:[1,0]
	v_mov_b32_e32 v87, v94
	v_mov_b32_e32 v93, v95
	v_pk_add_f32 v[86:87], v[86:87], v[92:93]
	v_mul_f32_e32 v92, v71, v71
	v_mul_f32_e32 v94, v73, v73
	v_mul_f32_e32 v96, v68, v68
	v_mul_f32_e32 v97, v69, v69
	v_pk_fma_f32 v[92:93], v[70:71], v[70:71], v[92:93] op_sel_hi:[1,1,0]
	v_pk_fma_f32 v[94:95], v[72:73], v[72:73], v[94:95] op_sel_hi:[1,1,0]
	v_mov_b32_e32 v93, v96
	v_mov_b32_e32 v95, v97
	v_pk_add_f32 v[92:93], v[92:93], v[94:95]
	v_pk_mul_f32 v[78:79], v[78:79], v[146:147]
	v_pk_add_f32 v[86:87], v[86:87], v[92:93]
	v_pk_mul_f32 v[92:93], v[126:127], v[102:103]
	v_add_f32_e32 v94, v86, v87
	ds_bpermute_b32 v95, v167, v94
	v_pk_mul_f32 v[86:87], v[126:127], v[90:91]
	v_pk_mul_f32 v[90:91], v[108:109], v[104:105]
	v_cvt_pk_bf16_f32 v86, v86, v87
	v_cvt_pk_bf16_f32 v87, v88, v89
	s_waitcnt lgkmcnt(0)
	v_add_f32_e32 v94, v94, v95
	ds_bpermute_b32 v95, v183, v94
	v_cvt_pk_bf16_f32 v88, v92, v93
	v_cvt_pk_bf16_f32 v89, v90, v91
	global_store_dwordx4 v[106:107], v[86:89], off offset:64
	v_or_b32_e32 v96, 48, v182
	s_waitcnt lgkmcnt(0)
	v_add_f32_e32 v86, v94, v95
	v_fmamk_f32 v86, v86, 0x3c800000, v188
	v_rsq_f32_e32 v86, v86
	v_lshlrev_b32_e32 v88, 6, v96
	v_mov_b32_e32 v89, v0
	v_lshl_add_u64 v[88:89], s[62:63], 0, v[88:89]
	v_pk_mul_f32 v[80:81], v[80:81], v[86:87] op_sel_hi:[1,0]
	v_pk_mul_f32 v[78:79], v[78:79], v[86:87] op_sel_hi:[1,0]
	ds_bpermute_b32 v92, v167, v78
	ds_bpermute_b32 v93, v167, v79
	ds_bpermute_b32 v90, v167, v80
	ds_bpermute_b32 v91, v167, v81
	s_and_saveexec_b64 s[10:11], s[4:5]
	s_cbranch_execz .LBB0_356
	global_load_dwordx4 v[204:207], v[250:251], off
	global_load_dwordx4 v[208:211], v[250:251], off offset:16
	global_load_dwordx4 v[212:215], v[250:251], off offset:32
	global_load_dwordx4 v[216:219], v[250:251], off offset:48
	s_waitcnt vmcnt(6)
	v_mov_b32_e32 v98, v224
	v_mov_b32_e32 v99, v225
	v_mov_b32_e32 v100, v226
	v_mov_b32_e32 v101, v227
	v_mov_b32_e32 v102, v220
	v_mov_b32_e32 v103, v221
	v_mov_b32_e32 v104, v222
	v_mov_b32_e32 v105, v223
	v_mov_b32_e32 v95, v104
	v_mov_b32_e32 v104, v103
	s_waitcnt lgkmcnt(2)
	v_pk_mul_f32 v[92:93], v[104:105], v[92:93]
	v_mov_b32_e32 v94, v102
	v_cndmask_b32_e64 v93, v93, -v93, s[6:7]
	v_cndmask_b32_e64 v92, v92, -v92, s[6:7]
	v_pk_fma_f32 v[78:79], v[78:79], v[94:95], v[92:93]
	v_mov_b32_e32 v93, v100
	v_mov_b32_e32 v100, v99
	s_waitcnt lgkmcnt(0)
	v_pk_mul_f32 v[90:91], v[100:101], v[90:91]
	v_mov_b32_e32 v92, v98
	v_cndmask_b32_e64 v91, v91, -v91, s[6:7]
	v_cndmask_b32_e64 v90, v90, -v90, s[6:7]
	v_pk_fma_f32 v[80:81], v[80:81], v[92:93], v[90:91]
; __device__ __forceinline__ unsigned cvt_pk_bf16(float lo, float hi) { unsigned r; asm volatile("v_cvt_pk_bf16_f32 %0, %1, %2" : "=v"(r) : "v"(lo), "v"(hi)); return r; }
;     __device__ __forceinline__ void operator()(const f32x4 (&acc)[2][2][4][2], const Unit& u, int wr, int wc, int fr, int fq) const {
;     ...
;                 for (int m = 0; m < 4; ++m) { const int lrow = row0 + ai * HALF + m * 16; const int pos = lrow & 2047, bb = lrow >> 11;
;                     f32x4 y[2][2]; float ss = 0.f;
; #pragma unroll
;                     for (int bj = 0; bj < 2; ++bj)
; #pragma unroll
;                         for (int n = 0; n < 2; ++n) { y[bj][n] = acc[ai][bj][m][n]; ss += (y[bj][n][0] * y[bj][n][0] + y[bj][n][1] * y[bj][n][1]) + (y[bj][n][2] * y[bj][n][2] + y[bj][n][3] * y[bj][n][3]); }
;                     ss += __shfl_xor(ss, 16); ss += __shfl_xor(ss, 32);
;                     const float rs = __builtin_amdgcn_rsqf(ss * (1.0f / 64.0f) + 1e-6f);
; #pragma unroll
;                     for (int bj = 0; bj < 2; ++bj)
; #pragma unroll
;                         for (int n = 0; n < 2; ++n) y[bj][n] = y[bj][n] * gn[bj][n] * rs;
; #pragma unroll
;                     for (int n = 0; n < 2; ++n) { f32x4 pr;
; #pragma unroll
;                         for (int e = 0; e < 4; ++e) pr[e] = __shfl_xor(y[0][n][e], 16);
;                         if (fq < 2) { const f32x4 t0 = *(const f32x4*)(RT + (size_t)pos * 16 + 8 * n), t1 = *(const f32x4*)(RT + (size_t)pos * 16 + 8 * n + 4);
;                             const float co[4] = {t0[0], t0[2], t1[0], t1[2]}, si[4] = {t0[1], t0[3], t1[1], t1[3]};
; #pragma unroll
;                             for (int e = 0; e < 4; ++e) y[0][n][e] = (fq == 0) ? (y[0][n][e] * co[e] - pr[e] * si[e]) : (y[0][n][e] * co[e] + pr[e] * si[e]); } }
;                     bf16_t* rowp = OB + ((size_t)(bb * 24 + gh) * 2048 + permpos(pos, grp)) * 64 + 8 * fq;
; #pragma unroll
;                     for (int bj = 0; bj < 2; ++bj) { const f32x4 v0 = y[bj][0] * sc, v1 = y[bj][1] * sc;
;                         u32x4 w; w.x = cvt_pk_bf16(v0[0], v0[1]); w.y = cvt_pk_bf16(v0[2], v0[3]); w.z = cvt_pk_bf16(v1[0], v1[1]); w.w = cvt_pk_bf16(v1[2], v1[3]);
;                         *(u32x4*)(rowp + 32 * bj) = w; }
;                     asm volatile("" ::: "memory"); }
.LBB0_356:
	s_or_b64 exec, exec, s[10:11]
	v_mov_b32_e32 v87, v86
	v_pk_mul_f32 v[76:77], v[76:77], v[144:145]
	v_pk_mul_f32 v[74:75], v[74:75], v[142:143]
	s_waitcnt lgkmcnt(1)
	v_mov_b32_e32 v90, v86
	s_waitcnt lgkmcnt(0)
	v_mov_b32_e32 v91, v86
	v_pk_mul_f32 v[76:77], v[76:77], v[90:91]
	v_pk_mul_f32 v[74:75], v[74:75], v[86:87]
	ds_bpermute_b32 v94, v167, v74
	ds_bpermute_b32 v95, v167, v75
	ds_bpermute_b32 v92, v167, v76
	ds_bpermute_b32 v93, v167, v77
	s_and_saveexec_b64 s[10:11], s[4:5]
	s_cbranch_execz .LBB0_358
	v_mov_b32_e32 v98, v232
	v_mov_b32_e32 v99, v233
	v_mov_b32_e32 v100, v234
	v_mov_b32_e32 v101, v235
	v_mov_b32_e32 v102, v228
	v_mov_b32_e32 v103, v229
	v_mov_b32_e32 v104, v230
	v_mov_b32_e32 v105, v231
	v_mov_b32_e32 v89, v104
	v_mov_b32_e32 v104, v103
	s_waitcnt lgkmcnt(2)
	v_pk_mul_f32 v[94:95], v[104:105], v[94:95]
	v_mov_b32_e32 v88, v102
	v_cndmask_b32_e64 v95, v95, -v95, s[6:7]
	v_cndmask_b32_e64 v94, v94, -v94, s[6:7]
	v_pk_fma_f32 v[74:75], v[74:75], v[88:89], v[94:95]
	v_mov_b32_e32 v89, v100
	v_mov_b32_e32 v100, v99
	s_waitcnt lgkmcnt(0)
	v_pk_mul_f32 v[92:93], v[100:101], v[92:93]
	v_mov_b32_e32 v88, v98
	v_cndmask_b32_e64 v93, v93, -v93, s[6:7]
	v_cndmask_b32_e64 v92, v92, -v92, s[6:7]
	v_pk_fma_f32 v[76:77], v[76:77], v[88:89], v[92:93]
.LBB0_358:
	s_or_b64 exec, exec, s[10:11]
	v_pk_mul_f32 v[70:71], v[70:71], v[138:139]
	v_pk_mul_f32 v[66:67], v[66:67], v[134:135]
	v_pk_mul_f32 v[70:71], v[70:71], v[86:87]
	v_pk_mul_f32 v[86:87], v[66:67], v[86:87]
	v_and_b32_e32 v66, s22, v96
	v_mul_u32_u24_e32 v66, s13, v66
	v_lshrrev_b32_e32 v67, s12, v96
	v_pk_mul_f32 v[72:73], v[72:73], v[140:141]
	v_pk_mul_f32 v[68:69], v[68:69], v[136:137]
	v_add_lshl_u32 v66, v66, v67, 7
	v_mov_b32_e32 v67, v0
	s_waitcnt lgkmcnt(1)
	v_mov_b32_e32 v92, v126
	s_waitcnt lgkmcnt(0)
	v_mov_b32_e32 v93, v126
	v_pk_mul_f32 v[72:73], v[72:73], v[90:91]
	v_pk_mul_f32 v[88:89], v[68:69], v[90:91]
	v_lshl_add_u64 v[90:91], v[130:131], 0, v[66:67]
	v_pk_mul_f32 v[68:69], v[92:93], v[80:81]
	v_pk_mul_f32 v[66:67], v[126:127], v[78:79]
	v_pk_mul_f32 v[76:77], v[92:93], v[76:77]
	v_pk_mul_f32 v[74:75], v[126:127], v[74:75]
	v_cvt_pk_bf16_f32 v66, v66, v67
	v_cvt_pk_bf16_f32 v67, v68, v69
	s_nop 0
	v_cvt_pk_bf16_f32 v68, v74, v75
	v_cvt_pk_bf16_f32 v69, v76, v77
	global_store_dwordx4 v[90:91], v[66:69], off
	s_nop 1
	v_pk_mul_f32 v[68:69], v[92:93], v[72:73]
	v_pk_mul_f32 v[66:67], v[126:127], v[70:71]
	v_pk_mul_f32 v[70:71], v[64:65], v[64:65]
	v_pk_mul_f32 v[72:73], v[62:63], v[62:63]
	v_cvt_pk_bf16_f32 v66, v66, v67
	v_cvt_pk_bf16_f32 v67, v68, v69
	v_pk_mul_f32 v[64:65], v[64:65], v[148:149]
	v_pk_mov_b32 v[74:75], v[72:73], v[70:71] op_sel:[1,0]
	v_mov_b32_e32 v73, v71
	v_pk_add_f32 v[70:71], v[74:75], v[72:73]
	v_pk_mul_f32 v[72:73], v[60:61], v[60:61]
	v_pk_mul_f32 v[74:75], v[58:59], v[58:59]
	v_pk_add_f32 v[70:71], v[70:71], v[70:71] op_sel:[0,1] op_sel_hi:[1,0]
	v_pk_mov_b32 v[76:77], v[74:75], v[72:73] op_sel:[1,0]
	v_mov_b32_e32 v75, v73
	v_pk_add_f32 v[72:73], v[76:77], v[74:75]
	v_mul_f32_e32 v74, v50, v50
	v_mul_f32_e32 v75, v51, v51
	v_pk_add_f32 v[72:73], v[72:73], v[72:73] op_sel:[0,1] op_sel_hi:[1,0]
	v_mov_b32_e32 v71, v74
	v_mov_b32_e32 v73, v75
	v_pk_add_f32 v[70:71], v[70:71], v[72:73]
	v_mul_f32_e32 v72, v55, v55
	v_mul_f32_e32 v74, v57, v57
	v_mul_f32_e32 v76, v52, v52
	v_mul_f32_e32 v77, v53, v53
	v_pk_fma_f32 v[72:73], v[54:55], v[54:55], v[72:73] op_sel_hi:[1,1,0]
	v_pk_fma_f32 v[74:75], v[56:57], v[56:57], v[74:75] op_sel_hi:[1,1,0]
	v_mov_b32_e32 v73, v76
	v_mov_b32_e32 v75, v77
	v_pk_add_f32 v[72:73], v[72:73], v[74:75]
	v_pk_mul_f32 v[62:63], v[62:63], v[146:147]
	v_pk_add_f32 v[70:71], v[70:71], v[72:73]
	v_pk_mul_f32 v[72:73], v[126:127], v[86:87]
	v_add_f32_e32 v74, v70, v71
	ds_bpermute_b32 v75, v167, v74
	v_pk_mul_f32 v[70:71], v[92:93], v[88:89]
	v_cvt_pk_bf16_f32 v68, v72, v73
	v_add_u32_e32 v77, 0x80, v166
	v_cvt_pk_bf16_f32 v69, v70, v71
	s_waitcnt lgkmcnt(0)
	v_add_f32_e32 v74, v74, v75
	ds_bpermute_b32 v75, v183, v74
	global_store_dwordx4 v[90:91], v[66:69], off offset:64
	v_and_b32_e32 v76, 0x7cf, v77
	v_lshlrev_b32_e32 v70, 6, v76
	s_waitcnt lgkmcnt(0)
	v_add_f32_e32 v66, v74, v75
	v_fmamk_f32 v66, v66, 0x3c800000, v188
	v_rsq_f32_e32 v66, v66
	v_mov_b32_e32 v71, v0
	v_lshl_add_u64 v[70:71], s[62:63], 0, v[70:71]
	v_pk_mul_f32 v[64:65], v[64:65], v[66:67] op_sel_hi:[1,0]
	v_pk_mul_f32 v[62:63], v[62:63], v[66:67] op_sel_hi:[1,0]
	ds_bpermute_b32 v72, v167, v62
	ds_bpermute_b32 v73, v167, v63
	ds_bpermute_b32 v68, v167, v64
	ds_bpermute_b32 v69, v167, v65
	s_and_saveexec_b64 s[10:11], s[4:5]
	s_cbranch_execz .LBB0_360
	global_load_dwordx4 v[220:223], v[250:251], off offset:1024
	global_load_dwordx4 v[224:227], v[250:251], off offset:1040
	global_load_dwordx4 v[228:231], v[250:251], off offset:1056
	global_load_dwordx4 v[232:235], v[250:251], off offset:1072
	s_waitcnt vmcnt(6)
	v_mov_b32_e32 v78, v208
	v_mov_b32_e32 v79, v209
	v_mov_b32_e32 v80, v210
	v_mov_b32_e32 v81, v211
	v_mov_b32_e32 v86, v204
	v_mov_b32_e32 v87, v205
	v_mov_b32_e32 v88, v206
	v_mov_b32_e32 v89, v207
	v_mov_b32_e32 v75, v88
	v_mov_b32_e32 v88, v87
	s_waitcnt lgkmcnt(2)
	v_pk_mul_f32 v[72:73], v[88:89], v[72:73]
	v_mov_b32_e32 v74, v86
	v_cndmask_b32_e64 v73, v73, -v73, s[6:7]
	v_cndmask_b32_e64 v72, v72, -v72, s[6:7]
	v_pk_fma_f32 v[62:63], v[62:63], v[74:75], v[72:73]
	v_mov_b32_e32 v73, v80
	v_mov_b32_e32 v80, v79
	s_waitcnt lgkmcnt(0)
	v_pk_mul_f32 v[68:69], v[80:81], v[68:69]
	v_mov_b32_e32 v72, v78
	v_cndmask_b32_e64 v69, v69, -v69, s[6:7]
	v_cndmask_b32_e64 v68, v68, -v68, s[6:7]
	v_pk_fma_f32 v[64:65], v[64:65], v[72:73], v[68:69]
; __device__ __forceinline__ unsigned cvt_pk_bf16(float lo, float hi) { unsigned r; asm volatile("v_cvt_pk_bf16_f32 %0, %1, %2" : "=v"(r) : "v"(lo), "v"(hi)); return r; }
;     __device__ __forceinline__ void operator()(const f32x4 (&acc)[2][2][4][2], const Unit& u, int wr, int wc, int fr, int fq) const {
;     ...
;                 for (int m = 0; m < 4; ++m) { const int lrow = row0 + ai * HALF + m * 16; const int pos = lrow & 2047, bb = lrow >> 11;
;                     f32x4 y[2][2]; float ss = 0.f;
; #pragma unroll
;                     for (int bj = 0; bj < 2; ++bj)
; #pragma unroll
;                         for (int n = 0; n < 2; ++n) { y[bj][n] = acc[ai][bj][m][n]; ss += (y[bj][n][0] * y[bj][n][0] + y[bj][n][1] * y[bj][n][1]) + (y[bj][n][2] * y[bj][n][2] + y[bj][n][3] * y[bj][n][3]); }
;                     ss += __shfl_xor(ss, 16); ss += __shfl_xor(ss, 32);
;                     const float rs = __builtin_amdgcn_rsqf(ss * (1.0f / 64.0f) + 1e-6f);
; #pragma unroll
;                     for (int bj = 0; bj < 2; ++bj)
; #pragma unroll
;                         for (int n = 0; n < 2; ++n) y[bj][n] = y[bj][n] * gn[bj][n] * rs;
; #pragma unroll
;                     for (int n = 0; n < 2; ++n) { f32x4 pr;
; #pragma unroll
;                         for (int e = 0; e < 4; ++e) pr[e] = __shfl_xor(y[0][n][e], 16);
;                         if (fq < 2) { const f32x4 t0 = *(const f32x4*)(RT + (size_t)pos * 16 + 8 * n), t1 = *(const f32x4*)(RT + (size_t)pos * 16 + 8 * n + 4);
;                             const float co[4] = {t0[0], t0[2], t1[0], t1[2]}, si[4] = {t0[1], t0[3], t1[1], t1[3]};
; #pragma unroll
;                             for (int e = 0; e < 4; ++e) y[0][n][e] = (fq == 0) ? (y[0][n][e] * co[e] - pr[e] * si[e]) : (y[0][n][e] * co[e] + pr[e] * si[e]); } }
;                     bf16_t* rowp = OB + ((size_t)(bb * 24 + gh) * 2048 + permpos(pos, grp)) * 64 + 8 * fq;
; #pragma unroll
;                     for (int bj = 0; bj < 2; ++bj) { const f32x4 v0 = y[bj][0] * sc, v1 = y[bj][1] * sc;
;                         u32x4 w; w.x = cvt_pk_bf16(v0[0], v0[1]); w.y = cvt_pk_bf16(v0[2], v0[3]); w.z = cvt_pk_bf16(v1[0], v1[1]); w.w = cvt_pk_bf16(v1[2], v1[3]);
;                         *(u32x4*)(rowp + 32 * bj) = w; }
;                     asm volatile("" ::: "memory"); }
.LBB0_360:
	s_or_b64 exec, exec, s[10:11]
	v_mov_b32_e32 v67, v66
	v_pk_mul_f32 v[60:61], v[60:61], v[144:145]
	v_pk_mul_f32 v[58:59], v[58:59], v[142:143]
	s_waitcnt lgkmcnt(3)
	v_mov_b32_e32 v72, v66
	s_waitcnt lgkmcnt(2)
	v_mov_b32_e32 v73, v66
	s_waitcnt lgkmcnt(0)
	v_pk_mul_f32 v[68:69], v[60:61], v[72:73]
	v_pk_mul_f32 v[60:61], v[58:59], v[66:67]
	ds_bpermute_b32 v74, v167, v60
	ds_bpermute_b32 v75, v167, v61
	ds_bpermute_b32 v58, v167, v68
	ds_bpermute_b32 v59, v167, v69
	s_and_saveexec_b64 s[10:11], s[4:5]
	s_cbranch_execz .LBB0_362
	v_mov_b32_e32 v78, v216
	v_mov_b32_e32 v79, v217
	v_mov_b32_e32 v80, v218
	v_mov_b32_e32 v81, v219
	v_mov_b32_e32 v86, v212
	v_mov_b32_e32 v87, v213
	v_mov_b32_e32 v88, v214
	v_mov_b32_e32 v89, v215
	v_mov_b32_e32 v71, v88
	v_mov_b32_e32 v88, v87
	s_waitcnt lgkmcnt(2)
	v_pk_mul_f32 v[74:75], v[88:89], v[74:75]
	v_mov_b32_e32 v70, v86
	v_cndmask_b32_e64 v75, v75, -v75, s[6:7]
	v_cndmask_b32_e64 v74, v74, -v74, s[6:7]
	v_pk_fma_f32 v[60:61], v[60:61], v[70:71], v[74:75]
	v_mov_b32_e32 v71, v80
	v_mov_b32_e32 v80, v79
	s_waitcnt lgkmcnt(0)
	v_pk_mul_f32 v[58:59], v[80:81], v[58:59]
	v_mov_b32_e32 v70, v78
	v_cndmask_b32_e64 v59, v59, -v59, s[6:7]
	v_cndmask_b32_e64 v58, v58, -v58, s[6:7]
	v_pk_fma_f32 v[68:69], v[68:69], v[70:71], v[58:59]
.LBB0_362:
	s_or_b64 exec, exec, s[10:11]
	s_waitcnt lgkmcnt(1)
	v_ashrrev_i32_e32 v58, 11, v77
	v_mad_i32_i24 v58, v58, 24, s23
	v_pk_mul_f32 v[54:55], v[54:55], v[138:139]
	v_pk_mul_f32 v[50:51], v[50:51], v[134:135]
	s_waitcnt lgkmcnt(0)
	v_ashrrev_i32_e32 v59, 31, v58
	v_pk_mul_f32 v[54:55], v[54:55], v[66:67]
	v_pk_mul_f32 v[66:67], v[50:51], v[66:67]
	v_and_b32_e32 v50, s22, v76
	v_lshlrev_b64 v[58:59], 18, v[58:59]
	v_mul_u32_u24_e32 v50, s13, v50
	v_lshrrev_b32_e32 v51, s12, v76
	v_lshl_add_u64 v[58:59], v[128:129], 0, v[58:59]
	v_pk_mul_f32 v[56:57], v[56:57], v[140:141]
	v_pk_mul_f32 v[52:53], v[52:53], v[136:137]
	v_add_lshl_u32 v50, v50, v51, 7
	v_mov_b32_e32 v51, v0
	v_mov_b32_e32 v74, v126
	v_mov_b32_e32 v75, v126
	v_pk_mul_f32 v[56:57], v[56:57], v[72:73]
	v_pk_mul_f32 v[70:71], v[52:53], v[72:73]
	v_lshl_add_u64 v[72:73], v[58:59], 0, v[50:51]
	v_pk_mul_f32 v[52:53], v[74:75], v[64:65]
	v_pk_mul_f32 v[50:51], v[126:127], v[62:63]
	v_pk_mul_f32 v[62:63], v[74:75], v[68:69]
	v_pk_mul_f32 v[60:61], v[126:127], v[60:61]
	v_cvt_pk_bf16_f32 v50, v50, v51
	v_cvt_pk_bf16_f32 v51, v52, v53
	s_nop 0
	v_cvt_pk_bf16_f32 v52, v60, v61
	v_cvt_pk_bf16_f32 v53, v62, v63
	global_store_dwordx4 v[72:73], v[50:53], off
	s_nop 1
	v_pk_mul_f32 v[52:53], v[74:75], v[56:57]
	v_pk_mul_f32 v[50:51], v[48:49], v[48:49]
	v_pk_mul_f32 v[56:57], v[46:47], v[46:47]
	v_pk_mul_f32 v[48:49], v[48:49], v[148:149]
	v_pk_mov_b32 v[60:61], v[56:57], v[50:51] op_sel:[1,0]
	v_mov_b32_e32 v57, v51
	v_pk_add_f32 v[50:51], v[60:61], v[56:57]
	v_pk_mul_f32 v[56:57], v[44:45], v[44:45]
	v_pk_mul_f32 v[60:61], v[42:43], v[42:43]
	v_pk_add_f32 v[50:51], v[50:51], v[50:51] op_sel:[0,1] op_sel_hi:[1,0]
	v_pk_mov_b32 v[62:63], v[60:61], v[56:57] op_sel:[1,0]
	v_mov_b32_e32 v61, v57
	v_pk_add_f32 v[56:57], v[62:63], v[60:61]
	v_mul_f32_e32 v60, v34, v34
	v_mul_f32_e32 v61, v35, v35
	v_pk_add_f32 v[56:57], v[56:57], v[56:57] op_sel:[0,1] op_sel_hi:[1,0]
	v_mov_b32_e32 v51, v60
	v_mov_b32_e32 v57, v61
	v_pk_add_f32 v[50:51], v[50:51], v[56:57]
	v_mul_f32_e32 v56, v39, v39
	v_mul_f32_e32 v60, v41, v41
	v_mul_f32_e32 v62, v36, v36
	v_mul_f32_e32 v63, v37, v37
	v_pk_fma_f32 v[56:57], v[38:39], v[38:39], v[56:57] op_sel_hi:[1,1,0]
	v_pk_fma_f32 v[60:61], v[40:41], v[40:41], v[60:61] op_sel_hi:[1,1,0]
	v_mov_b32_e32 v57, v62
	v_mov_b32_e32 v61, v63
	v_pk_add_f32 v[56:57], v[56:57], v[60:61]
	v_pk_mul_f32 v[46:47], v[46:47], v[146:147]
	v_pk_add_f32 v[50:51], v[50:51], v[56:57]
	v_pk_mul_f32 v[56:57], v[126:127], v[66:67]
	v_add_f32_e32 v60, v50, v51
	ds_bpermute_b32 v61, v167, v60
	v_pk_mul_f32 v[50:51], v[126:127], v[54:55]
	v_pk_mul_f32 v[54:55], v[74:75], v[70:71]
	v_cvt_pk_bf16_f32 v50, v50, v51
	v_cvt_pk_bf16_f32 v51, v52, v53
	s_waitcnt lgkmcnt(0)
	v_add_f32_e32 v60, v60, v61
	ds_bpermute_b32 v61, v183, v60
	v_cvt_pk_bf16_f32 v52, v56, v57
	v_cvt_pk_bf16_f32 v53, v54, v55
	global_store_dwordx4 v[72:73], v[50:53], off offset:64
	v_or_b32_e32 v62, 16, v76
	s_waitcnt lgkmcnt(0)
	v_add_f32_e32 v50, v60, v61
	v_fmamk_f32 v50, v50, 0x3c800000, v188
	v_rsq_f32_e32 v50, v50
	v_lshlrev_b32_e32 v52, 6, v62
	v_mov_b32_e32 v53, v0
	v_lshl_add_u64 v[52:53], s[62:63], 0, v[52:53]
	v_pk_mul_f32 v[48:49], v[48:49], v[50:51] op_sel_hi:[1,0]
	v_pk_mul_f32 v[46:47], v[46:47], v[50:51] op_sel_hi:[1,0]
	ds_bpermute_b32 v56, v167, v46
	ds_bpermute_b32 v57, v167, v47
	ds_bpermute_b32 v54, v167, v48
	ds_bpermute_b32 v55, v167, v49
	s_and_saveexec_b64 s[10:11], s[4:5]
	s_cbranch_execz .LBB0_364
	global_load_dwordx4 v[204:207], v[250:251], off offset:2048
	global_load_dwordx4 v[208:211], v[250:251], off offset:2064
	global_load_dwordx4 v[212:215], v[250:251], off offset:2080
	global_load_dwordx4 v[216:219], v[250:251], off offset:2096
	s_waitcnt vmcnt(6)
	v_mov_b32_e32 v64, v224
	v_mov_b32_e32 v65, v225
	v_mov_b32_e32 v66, v226
	v_mov_b32_e32 v67, v227
	v_mov_b32_e32 v68, v220
	v_mov_b32_e32 v69, v221
	v_mov_b32_e32 v70, v222
	v_mov_b32_e32 v71, v223
	v_mov_b32_e32 v61, v70
	v_mov_b32_e32 v70, v69
	s_waitcnt lgkmcnt(2)
	v_pk_mul_f32 v[56:57], v[70:71], v[56:57]
	v_mov_b32_e32 v60, v68
	v_cndmask_b32_e64 v57, v57, -v57, s[6:7]
	v_cndmask_b32_e64 v56, v56, -v56, s[6:7]
	v_pk_fma_f32 v[46:47], v[46:47], v[60:61], v[56:57]
	v_mov_b32_e32 v57, v66
	v_mov_b32_e32 v66, v65
	s_waitcnt lgkmcnt(0)
	v_pk_mul_f32 v[54:55], v[66:67], v[54:55]
	v_mov_b32_e32 v56, v64
	v_cndmask_b32_e64 v55, v55, -v55, s[6:7]
	v_cndmask_b32_e64 v54, v54, -v54, s[6:7]
	v_pk_fma_f32 v[48:49], v[48:49], v[56:57], v[54:55]
; __device__ __forceinline__ unsigned cvt_pk_bf16(float lo, float hi) { unsigned r; asm volatile("v_cvt_pk_bf16_f32 %0, %1, %2" : "=v"(r) : "v"(lo), "v"(hi)); return r; }
;     __device__ __forceinline__ void operator()(const f32x4 (&acc)[2][2][4][2], const Unit& u, int wr, int wc, int fr, int fq) const {
;     ...
;                 for (int m = 0; m < 4; ++m) { const int lrow = row0 + ai * HALF + m * 16; const int pos = lrow & 2047, bb = lrow >> 11;
;                     f32x4 y[2][2]; float ss = 0.f;
; #pragma unroll
;                     for (int bj = 0; bj < 2; ++bj)
; #pragma unroll
;                         for (int n = 0; n < 2; ++n) { y[bj][n] = acc[ai][bj][m][n]; ss += (y[bj][n][0] * y[bj][n][0] + y[bj][n][1] * y[bj][n][1]) + (y[bj][n][2] * y[bj][n][2] + y[bj][n][3] * y[bj][n][3]); }
;                     ss += __shfl_xor(ss, 16); ss += __shfl_xor(ss, 32);
;                     const float rs = __builtin_amdgcn_rsqf(ss * (1.0f / 64.0f) + 1e-6f);
; #pragma unroll
;                     for (int bj = 0; bj < 2; ++bj)
; #pragma unroll
;                         for (int n = 0; n < 2; ++n) y[bj][n] = y[bj][n] * gn[bj][n] * rs;
; #pragma unroll
;                     for (int n = 0; n < 2; ++n) { f32x4 pr;
; #pragma unroll
;                         for (int e = 0; e < 4; ++e) pr[e] = __shfl_xor(y[0][n][e], 16);
;                         if (fq < 2) { const f32x4 t0 = *(const f32x4*)(RT + (size_t)pos * 16 + 8 * n), t1 = *(const f32x4*)(RT + (size_t)pos * 16 + 8 * n + 4);
;                             const float co[4] = {t0[0], t0[2], t1[0], t1[2]}, si[4] = {t0[1], t0[3], t1[1], t1[3]};
; #pragma unroll
;                             for (int e = 0; e < 4; ++e) y[0][n][e] = (fq == 0) ? (y[0][n][e] * co[e] - pr[e] * si[e]) : (y[0][n][e] * co[e] + pr[e] * si[e]); } }
;                     bf16_t* rowp = OB + ((size_t)(bb * 24 + gh) * 2048 + permpos(pos, grp)) * 64 + 8 * fq;
; #pragma unroll
;                     for (int bj = 0; bj < 2; ++bj) { const f32x4 v0 = y[bj][0] * sc, v1 = y[bj][1] * sc;
;                         u32x4 w; w.x = cvt_pk_bf16(v0[0], v0[1]); w.y = cvt_pk_bf16(v0[2], v0[3]); w.z = cvt_pk_bf16(v1[0], v1[1]); w.w = cvt_pk_bf16(v1[2], v1[3]);
;                         *(u32x4*)(rowp + 32 * bj) = w; }
;                     asm volatile("" ::: "memory"); }
.LBB0_364:
	s_or_b64 exec, exec, s[10:11]
	v_mov_b32_e32 v51, v50
	v_pk_mul_f32 v[44:45], v[44:45], v[144:145]
	v_pk_mul_f32 v[42:43], v[42:43], v[142:143]
	s_waitcnt lgkmcnt(1)
	v_mov_b32_e32 v54, v50
	s_waitcnt lgkmcnt(0)
	v_mov_b32_e32 v55, v50
	v_pk_mul_f32 v[44:45], v[44:45], v[54:55]
	v_pk_mul_f32 v[42:43], v[42:43], v[50:51]
	ds_bpermute_b32 v60, v167, v42
	ds_bpermute_b32 v61, v167, v43
	ds_bpermute_b32 v56, v167, v44
	ds_bpermute_b32 v57, v167, v45
	s_and_saveexec_b64 s[10:11], s[4:5]
	s_cbranch_execz .LBB0_366
	v_mov_b32_e32 v64, v232
	v_mov_b32_e32 v65, v233
	v_mov_b32_e32 v66, v234
	v_mov_b32_e32 v67, v235
	v_mov_b32_e32 v68, v228
	v_mov_b32_e32 v69, v229
	v_mov_b32_e32 v70, v230
	v_mov_b32_e32 v71, v231
	v_mov_b32_e32 v53, v70
	v_mov_b32_e32 v70, v69
	s_waitcnt lgkmcnt(2)
	v_pk_mul_f32 v[60:61], v[70:71], v[60:61]
	v_mov_b32_e32 v52, v68
	v_cndmask_b32_e64 v61, v61, -v61, s[6:7]
	v_cndmask_b32_e64 v60, v60, -v60, s[6:7]
	v_pk_fma_f32 v[42:43], v[42:43], v[52:53], v[60:61]
	v_mov_b32_e32 v53, v66
	v_mov_b32_e32 v66, v65
	s_waitcnt lgkmcnt(0)
	v_pk_mul_f32 v[56:57], v[66:67], v[56:57]
	v_mov_b32_e32 v52, v64
	v_cndmask_b32_e64 v57, v57, -v57, s[6:7]
	v_cndmask_b32_e64 v56, v56, -v56, s[6:7]
	v_pk_fma_f32 v[44:45], v[44:45], v[52:53], v[56:57]
.LBB0_366:
	s_or_b64 exec, exec, s[10:11]
	v_pk_mul_f32 v[38:39], v[38:39], v[138:139]
	v_pk_mul_f32 v[34:35], v[34:35], v[134:135]
	v_pk_mul_f32 v[38:39], v[38:39], v[50:51]
	v_pk_mul_f32 v[50:51], v[34:35], v[50:51]
	v_and_b32_e32 v34, s22, v62
	v_mul_u32_u24_e32 v34, s13, v34
	v_lshrrev_b32_e32 v35, s12, v62
	v_pk_mul_f32 v[40:41], v[40:41], v[140:141]
	v_pk_mul_f32 v[36:37], v[36:37], v[136:137]
	v_add_lshl_u32 v34, v34, v35, 7
	v_mov_b32_e32 v35, v0
	s_waitcnt lgkmcnt(1)
	v_mov_b32_e32 v56, v126
	s_waitcnt lgkmcnt(0)
	v_mov_b32_e32 v57, v126
	v_pk_mul_f32 v[40:41], v[40:41], v[54:55]
	v_pk_mul_f32 v[52:53], v[36:37], v[54:55]
	v_lshl_add_u64 v[54:55], v[58:59], 0, v[34:35]
	v_pk_mul_f32 v[36:37], v[56:57], v[48:49]
	v_pk_mul_f32 v[34:35], v[126:127], v[46:47]
	v_pk_mul_f32 v[44:45], v[56:57], v[44:45]
	v_pk_mul_f32 v[42:43], v[126:127], v[42:43]
	v_cvt_pk_bf16_f32 v34, v34, v35
	v_cvt_pk_bf16_f32 v35, v36, v37
	s_nop 0
	v_cvt_pk_bf16_f32 v36, v42, v43
	v_cvt_pk_bf16_f32 v37, v44, v45
	global_store_dwordx4 v[54:55], v[34:37], off
	s_nop 1
	v_pk_mul_f32 v[36:37], v[56:57], v[40:41]
	v_pk_mul_f32 v[34:35], v[32:33], v[32:33]
	v_pk_mul_f32 v[40:41], v[30:31], v[30:31]
	v_pk_mul_f32 v[32:33], v[32:33], v[148:149]
	v_pk_mov_b32 v[42:43], v[40:41], v[34:35] op_sel:[1,0]
	v_mov_b32_e32 v41, v35
	v_pk_add_f32 v[34:35], v[42:43], v[40:41]
	v_pk_mul_f32 v[40:41], v[28:29], v[28:29]
	v_pk_mul_f32 v[42:43], v[26:27], v[26:27]
	v_pk_add_f32 v[34:35], v[34:35], v[34:35] op_sel:[0,1] op_sel_hi:[1,0]
	v_pk_mov_b32 v[44:45], v[42:43], v[40:41] op_sel:[1,0]
	v_mov_b32_e32 v43, v41
	v_pk_add_f32 v[40:41], v[44:45], v[42:43]
	v_mul_f32_e32 v42, v18, v18
	v_mul_f32_e32 v43, v19, v19
	v_pk_add_f32 v[40:41], v[40:41], v[40:41] op_sel:[0,1] op_sel_hi:[1,0]
	v_mov_b32_e32 v35, v42
	v_mov_b32_e32 v41, v43
	v_pk_add_f32 v[34:35], v[34:35], v[40:41]
	v_mul_f32_e32 v40, v23, v23
	v_mul_f32_e32 v42, v25, v25
	v_mul_f32_e32 v44, v20, v20
	v_mul_f32_e32 v45, v21, v21
	v_pk_fma_f32 v[40:41], v[22:23], v[22:23], v[40:41] op_sel_hi:[1,1,0]
	v_pk_fma_f32 v[42:43], v[24:25], v[24:25], v[42:43] op_sel_hi:[1,1,0]
	v_mov_b32_e32 v41, v44
	v_mov_b32_e32 v43, v45
	v_pk_add_f32 v[40:41], v[40:41], v[42:43]
	v_pk_mul_f32 v[30:31], v[30:31], v[146:147]
	v_pk_add_f32 v[34:35], v[34:35], v[40:41]
	v_pk_mul_f32 v[40:41], v[126:127], v[50:51]
	v_add_f32_e32 v42, v34, v35
	ds_bpermute_b32 v43, v167, v42
	v_pk_mul_f32 v[34:35], v[126:127], v[38:39]
	v_pk_mul_f32 v[38:39], v[56:57], v[52:53]
	v_cvt_pk_bf16_f32 v34, v34, v35
	v_cvt_pk_bf16_f32 v35, v36, v37
	s_waitcnt lgkmcnt(0)
	v_add_f32_e32 v42, v42, v43
	ds_bpermute_b32 v43, v183, v42
	v_cvt_pk_bf16_f32 v36, v40, v41
	v_cvt_pk_bf16_f32 v37, v38, v39
	global_store_dwordx4 v[54:55], v[34:37], off offset:64
	v_or_b32_e32 v44, 32, v76
	s_waitcnt lgkmcnt(0)
	v_add_f32_e32 v34, v42, v43
	v_fmamk_f32 v34, v34, 0x3c800000, v188
	v_rsq_f32_e32 v34, v34
	v_lshlrev_b32_e32 v36, 6, v44
	v_mov_b32_e32 v37, v0
	v_lshl_add_u64 v[36:37], s[62:63], 0, v[36:37]
	v_pk_mul_f32 v[32:33], v[32:33], v[34:35] op_sel_hi:[1,0]
	v_pk_mul_f32 v[30:31], v[30:31], v[34:35] op_sel_hi:[1,0]
	ds_bpermute_b32 v40, v167, v30
	ds_bpermute_b32 v41, v167, v31
	ds_bpermute_b32 v38, v167, v32
	ds_bpermute_b32 v39, v167, v33
	s_and_saveexec_b64 s[10:11], s[4:5]
	s_cbranch_execz .LBB0_368
	global_load_dwordx4 v[220:223], v[250:251], off offset:3072
	global_load_dwordx4 v[224:227], v[250:251], off offset:3088
	global_load_dwordx4 v[228:231], v[250:251], off offset:3104
	global_load_dwordx4 v[232:235], v[250:251], off offset:3120
	s_waitcnt vmcnt(6)
	v_mov_b32_e32 v46, v208
	v_mov_b32_e32 v47, v209
	v_mov_b32_e32 v48, v210
	v_mov_b32_e32 v49, v211
	v_mov_b32_e32 v50, v204
	v_mov_b32_e32 v51, v205
	v_mov_b32_e32 v52, v206
	v_mov_b32_e32 v53, v207
	v_mov_b32_e32 v43, v52
	v_mov_b32_e32 v52, v51
	s_waitcnt lgkmcnt(2)
	v_pk_mul_f32 v[40:41], v[52:53], v[40:41]
	v_mov_b32_e32 v42, v50
	v_cndmask_b32_e64 v41, v41, -v41, s[6:7]
	v_cndmask_b32_e64 v40, v40, -v40, s[6:7]
	v_pk_fma_f32 v[30:31], v[30:31], v[42:43], v[40:41]
	v_mov_b32_e32 v41, v48
	v_mov_b32_e32 v48, v47
	s_waitcnt lgkmcnt(0)
	v_pk_mul_f32 v[38:39], v[48:49], v[38:39]
	v_mov_b32_e32 v40, v46
	v_cndmask_b32_e64 v39, v39, -v39, s[6:7]
	v_cndmask_b32_e64 v38, v38, -v38, s[6:7]
	v_pk_fma_f32 v[32:33], v[32:33], v[40:41], v[38:39]
; __device__ __forceinline__ unsigned cvt_pk_bf16(float lo, float hi) { unsigned r; asm volatile("v_cvt_pk_bf16_f32 %0, %1, %2" : "=v"(r) : "v"(lo), "v"(hi)); return r; }
;     __device__ __forceinline__ void operator()(const f32x4 (&acc)[2][2][4][2], const Unit& u, int wr, int wc, int fr, int fq) const {
;     ...
;                 for (int m = 0; m < 4; ++m) { const int lrow = row0 + ai * HALF + m * 16; const int pos = lrow & 2047, bb = lrow >> 11;
;                     f32x4 y[2][2]; float ss = 0.f;
; #pragma unroll
;                     for (int bj = 0; bj < 2; ++bj)
; #pragma unroll
;                         for (int n = 0; n < 2; ++n) { y[bj][n] = acc[ai][bj][m][n]; ss += (y[bj][n][0] * y[bj][n][0] + y[bj][n][1] * y[bj][n][1]) + (y[bj][n][2] * y[bj][n][2] + y[bj][n][3] * y[bj][n][3]); }
;                     ss += __shfl_xor(ss, 16); ss += __shfl_xor(ss, 32);
;                     const float rs = __builtin_amdgcn_rsqf(ss * (1.0f / 64.0f) + 1e-6f);
; #pragma unroll
;                     for (int bj = 0; bj < 2; ++bj)
; #pragma unroll
;                         for (int n = 0; n < 2; ++n) y[bj][n] = y[bj][n] * gn[bj][n] * rs;
; #pragma unroll
;                     for (int n = 0; n < 2; ++n) { f32x4 pr;
; #pragma unroll
;                         for (int e = 0; e < 4; ++e) pr[e] = __shfl_xor(y[0][n][e], 16);
;                         if (fq < 2) { const f32x4 t0 = *(const f32x4*)(RT + (size_t)pos * 16 + 8 * n), t1 = *(const f32x4*)(RT + (size_t)pos * 16 + 8 * n + 4);
;                             const float co[4] = {t0[0], t0[2], t1[0], t1[2]}, si[4] = {t0[1], t0[3], t1[1], t1[3]};
; #pragma unroll
;                             for (int e = 0; e < 4; ++e) y[0][n][e] = (fq == 0) ? (y[0][n][e] * co[e] - pr[e] * si[e]) : (y[0][n][e] * co[e] + pr[e] * si[e]); } }
;                     bf16_t* rowp = OB + ((size_t)(bb * 24 + gh) * 2048 + permpos(pos, grp)) * 64 + 8 * fq;
; #pragma unroll
;                     for (int bj = 0; bj < 2; ++bj) { const f32x4 v0 = y[bj][0] * sc, v1 = y[bj][1] * sc;
;                         u32x4 w; w.x = cvt_pk_bf16(v0[0], v0[1]); w.y = cvt_pk_bf16(v0[2], v0[3]); w.z = cvt_pk_bf16(v1[0], v1[1]); w.w = cvt_pk_bf16(v1[2], v1[3]);
;                         *(u32x4*)(rowp + 32 * bj) = w; }
;                     asm volatile("" ::: "memory"); }
.LBB0_368:
	s_or_b64 exec, exec, s[10:11]
	v_mov_b32_e32 v35, v34
	v_pk_mul_f32 v[28:29], v[28:29], v[144:145]
	v_pk_mul_f32 v[26:27], v[26:27], v[142:143]
	s_waitcnt lgkmcnt(1)
	v_mov_b32_e32 v38, v34
	s_waitcnt lgkmcnt(0)
	v_mov_b32_e32 v39, v34
	v_pk_mul_f32 v[28:29], v[28:29], v[38:39]
	v_pk_mul_f32 v[26:27], v[26:27], v[34:35]
	ds_bpermute_b32 v42, v167, v26
	ds_bpermute_b32 v43, v167, v27
	ds_bpermute_b32 v40, v167, v28
	ds_bpermute_b32 v41, v167, v29
	s_and_saveexec_b64 s[10:11], s[4:5]
	s_cbranch_execz .LBB0_370
	v_mov_b32_e32 v46, v216
	v_mov_b32_e32 v47, v217
	v_mov_b32_e32 v48, v218
	v_mov_b32_e32 v49, v219
	v_mov_b32_e32 v50, v212
	v_mov_b32_e32 v51, v213
	v_mov_b32_e32 v52, v214
	v_mov_b32_e32 v53, v215
	v_mov_b32_e32 v37, v52
	v_mov_b32_e32 v52, v51
	s_waitcnt lgkmcnt(2)
	v_pk_mul_f32 v[42:43], v[52:53], v[42:43]
	v_mov_b32_e32 v36, v50
	v_cndmask_b32_e64 v43, v43, -v43, s[6:7]
	v_cndmask_b32_e64 v42, v42, -v42, s[6:7]
	v_pk_fma_f32 v[26:27], v[26:27], v[36:37], v[42:43]
	v_mov_b32_e32 v37, v48
	v_mov_b32_e32 v48, v47
	s_waitcnt lgkmcnt(0)
	v_pk_mul_f32 v[40:41], v[48:49], v[40:41]
	v_mov_b32_e32 v36, v46
	v_cndmask_b32_e64 v41, v41, -v41, s[6:7]
	v_cndmask_b32_e64 v40, v40, -v40, s[6:7]
	v_pk_fma_f32 v[28:29], v[28:29], v[36:37], v[40:41]
.LBB0_370:
	s_or_b64 exec, exec, s[10:11]
	v_pk_mul_f32 v[22:23], v[22:23], v[138:139]
	v_pk_mul_f32 v[18:19], v[18:19], v[134:135]
	v_pk_mul_f32 v[22:23], v[22:23], v[34:35]
	v_pk_mul_f32 v[34:35], v[18:19], v[34:35]
	v_and_b32_e32 v18, s22, v44
	v_mul_u32_u24_e32 v18, s13, v18
	v_lshrrev_b32_e32 v19, s12, v44
	v_pk_mul_f32 v[24:25], v[24:25], v[140:141]
	v_pk_mul_f32 v[20:21], v[20:21], v[136:137]
	v_add_lshl_u32 v18, v18, v19, 7
	v_mov_b32_e32 v19, v0
	s_waitcnt lgkmcnt(1)
	v_mov_b32_e32 v40, v126
	s_waitcnt lgkmcnt(0)
	v_mov_b32_e32 v41, v126
	v_pk_mul_f32 v[24:25], v[24:25], v[38:39]
	v_pk_mul_f32 v[36:37], v[20:21], v[38:39]
	v_lshl_add_u64 v[38:39], v[58:59], 0, v[18:19]
	v_pk_mul_f32 v[20:21], v[40:41], v[32:33]
	v_pk_mul_f32 v[18:19], v[126:127], v[30:31]
	v_pk_mul_f32 v[28:29], v[40:41], v[28:29]
	v_pk_mul_f32 v[26:27], v[126:127], v[26:27]
	v_cvt_pk_bf16_f32 v18, v18, v19
	v_cvt_pk_bf16_f32 v19, v20, v21
	s_nop 0
	v_cvt_pk_bf16_f32 v20, v26, v27
	v_cvt_pk_bf16_f32 v21, v28, v29
	global_store_dwordx4 v[38:39], v[18:21], off
	s_nop 1
	v_pk_mul_f32 v[20:21], v[40:41], v[24:25]
	v_pk_mul_f32 v[18:19], v[16:17], v[16:17]
	v_pk_mul_f32 v[24:25], v[14:15], v[14:15]
	v_pk_mul_f32 v[16:17], v[16:17], v[148:149]
	v_pk_mov_b32 v[26:27], v[24:25], v[18:19] op_sel:[1,0]
	v_mov_b32_e32 v25, v19
	v_pk_add_f32 v[18:19], v[26:27], v[24:25]
	v_pk_mul_f32 v[24:25], v[12:13], v[12:13]
	v_pk_mul_f32 v[26:27], v[10:11], v[10:11]
	v_pk_add_f32 v[18:19], v[18:19], v[18:19] op_sel:[0,1] op_sel_hi:[1,0]
	v_pk_mov_b32 v[28:29], v[26:27], v[24:25] op_sel:[1,0]
	v_mov_b32_e32 v27, v25
	v_pk_add_f32 v[24:25], v[28:29], v[26:27]
	v_mul_f32_e32 v26, v2, v2
	v_mul_f32_e32 v27, v3, v3
	v_pk_add_f32 v[24:25], v[24:25], v[24:25] op_sel:[0,1] op_sel_hi:[1,0]
	v_mov_b32_e32 v19, v26
	v_mov_b32_e32 v25, v27
	v_pk_add_f32 v[18:19], v[18:19], v[24:25]
	v_mul_f32_e32 v24, v7, v7
	v_mul_f32_e32 v26, v9, v9
	v_mul_f32_e32 v28, v4, v4
	v_mul_f32_e32 v29, v5, v5
	v_pk_fma_f32 v[24:25], v[6:7], v[6:7], v[24:25] op_sel_hi:[1,1,0]
	v_pk_fma_f32 v[26:27], v[8:9], v[8:9], v[26:27] op_sel_hi:[1,1,0]
	v_mov_b32_e32 v25, v28
	v_mov_b32_e32 v27, v29
	v_pk_add_f32 v[24:25], v[24:25], v[26:27]
	v_pk_mul_f32 v[14:15], v[14:15], v[146:147]
	v_pk_add_f32 v[18:19], v[18:19], v[24:25]
	v_pk_mul_f32 v[24:25], v[126:127], v[34:35]
	v_add_f32_e32 v26, v18, v19
	ds_bpermute_b32 v27, v167, v26
	v_pk_mul_f32 v[18:19], v[126:127], v[22:23]
	v_pk_mul_f32 v[22:23], v[40:41], v[36:37]
	v_cvt_pk_bf16_f32 v18, v18, v19
	v_cvt_pk_bf16_f32 v19, v20, v21
	s_waitcnt lgkmcnt(0)
	v_add_f32_e32 v26, v26, v27
	ds_bpermute_b32 v27, v183, v26
	v_cvt_pk_bf16_f32 v20, v24, v25
	v_cvt_pk_bf16_f32 v21, v22, v23
	global_store_dwordx4 v[38:39], v[18:21], off offset:64
	v_or_b32_e32 v28, 48, v76
	s_waitcnt lgkmcnt(0)
	v_add_f32_e32 v18, v26, v27
	v_fmamk_f32 v18, v18, 0x3c800000, v188
	v_rsq_f32_e32 v18, v18
	v_lshlrev_b32_e32 v20, 6, v28
	v_mov_b32_e32 v21, v0
	v_lshl_add_u64 v[20:21], s[62:63], 0, v[20:21]
	v_pk_mul_f32 v[16:17], v[16:17], v[18:19] op_sel_hi:[1,0]
	v_pk_mul_f32 v[14:15], v[14:15], v[18:19] op_sel_hi:[1,0]
	ds_bpermute_b32 v24, v167, v14
	ds_bpermute_b32 v25, v167, v15
	ds_bpermute_b32 v22, v167, v16
	ds_bpermute_b32 v23, v167, v17
	s_and_saveexec_b64 s[10:11], s[4:5]
	s_cbranch_execz .LBB0_372
	s_waitcnt vmcnt(2)
	v_mov_b32_e32 v30, v224
	v_mov_b32_e32 v31, v225
	v_mov_b32_e32 v32, v226
	v_mov_b32_e32 v33, v227
	v_mov_b32_e32 v34, v220
	v_mov_b32_e32 v35, v221
	v_mov_b32_e32 v36, v222
	v_mov_b32_e32 v37, v223
	v_mov_b32_e32 v27, v36
	v_mov_b32_e32 v36, v35
	s_waitcnt lgkmcnt(2)
	v_pk_mul_f32 v[24:25], v[36:37], v[24:25]
	v_mov_b32_e32 v26, v34
	v_cndmask_b32_e64 v25, v25, -v25, s[6:7]
	v_cndmask_b32_e64 v24, v24, -v24, s[6:7]
	v_pk_fma_f32 v[14:15], v[14:15], v[26:27], v[24:25]
	v_mov_b32_e32 v25, v32
	v_mov_b32_e32 v32, v31
	s_waitcnt lgkmcnt(0)
	v_pk_mul_f32 v[22:23], v[32:33], v[22:23]
	v_mov_b32_e32 v24, v30
	v_cndmask_b32_e64 v23, v23, -v23, s[6:7]
	v_cndmask_b32_e64 v22, v22, -v22, s[6:7]
	v_pk_fma_f32 v[16:17], v[16:17], v[24:25], v[22:23]
.LBB0_372:
	s_or_b64 exec, exec, s[10:11]
	v_mov_b32_e32 v19, v18
	v_pk_mul_f32 v[12:13], v[12:13], v[144:145]
	v_pk_mul_f32 v[10:11], v[10:11], v[142:143]
	s_waitcnt lgkmcnt(1)
	v_mov_b32_e32 v22, v18
	s_waitcnt lgkmcnt(0)
	v_mov_b32_e32 v23, v18
	v_pk_mul_f32 v[12:13], v[12:13], v[22:23]
	v_pk_mul_f32 v[10:11], v[10:11], v[18:19]
	ds_bpermute_b32 v26, v167, v10
	ds_bpermute_b32 v27, v167, v11
	ds_bpermute_b32 v24, v167, v12
	ds_bpermute_b32 v25, v167, v13
	s_and_saveexec_b64 s[10:11], s[4:5]
	s_cbranch_execz .LBB0_374
	v_mov_b32_e32 v30, v232
	v_mov_b32_e32 v31, v233
	v_mov_b32_e32 v32, v234
	v_mov_b32_e32 v33, v235
	v_mov_b32_e32 v34, v228
	v_mov_b32_e32 v35, v229
	v_mov_b32_e32 v36, v230
	v_mov_b32_e32 v37, v231
	v_mov_b32_e32 v21, v36
	v_mov_b32_e32 v36, v35
	s_waitcnt lgkmcnt(2)
	v_pk_mul_f32 v[26:27], v[36:37], v[26:27]
	v_mov_b32_e32 v20, v34
	v_cndmask_b32_e64 v27, v27, -v27, s[6:7]
	v_cndmask_b32_e64 v26, v26, -v26, s[6:7]
	v_pk_fma_f32 v[10:11], v[10:11], v[20:21], v[26:27]
	v_mov_b32_e32 v21, v32
	v_mov_b32_e32 v32, v31
	s_waitcnt lgkmcnt(0)
	v_pk_mul_f32 v[24:25], v[32:33], v[24:25]
	v_mov_b32_e32 v20, v30
	v_cndmask_b32_e64 v25, v25, -v25, s[6:7]
	v_cndmask_b32_e64 v24, v24, -v24, s[6:7]
	v_pk_fma_f32 v[12:13], v[12:13], v[20:21], v[24:25]

; DI int launder_v(int v) { asm volatile("" : "+v"(v)); return v; }
; #define LBAR() do { asm volatile("s_waitcnt lgkmcnt(0)" ::: "memory"); __builtin_amdgcn_s_barrier(); asm volatile("" ::: "memory"); } while (0)
; DI void lru_item(KP A, const bf16* XL, const bf16* GL, bf16* HG, int b, int nb, LAS unsigned char* lds, int tid, int wave, int lane) {
;     ...
;         LBAR();
;         v4u gt[5], pt[5];
;         { const int dt = launder_v(dtid);
; #pragma unroll
;         for (int i = 0; i < 5; ++i) { const int idx = dt + 256 * i; const int srow = idx / 10, c8 = idx % 10; const int t = t0 + (dir ? 127 - srow : srow);
;             gt[i] = (v4u){0u, 0u, 0u, 0u}; pt[i] = (v4u){0u, 0u, 0u, 0u};
;             if (second) { gt[i] = *(const v4u*)(GL + ((size_t)(b * 16 + nb) * S_ + t) * 80 + 8 * c8); pt[i] = *(const v4u*)(HG + (rowbase + t) * 1280 + 80 * nb + 8 * c8); } } }
.LBB0_568:
	s_or_b64 exec, exec, s[20:21]
	s_cmp_gt_u32 s34, 7
	s_waitcnt lgkmcnt(0)
	s_barrier
	s_cselect_b64 s[86:87], -1, 0
	s_cmp_lt_u32 s34, 8
	s_cselect_b64 s[84:85], -1, 0
	s_lshl_b32 s22, s1, 7
	v_mov_b32_e32 v118, v159
	v_mov_b32_e32 v94, 0
	s_and_b64 vcc, exec, s[86:87]
	v_mov_b32_e32 v110, 0
	v_mov_b32_e32 v111, 0
	v_mov_b32_e32 v112, 0
	v_mov_b32_e32 v113, 0
	v_mov_b32_e32 v114, 0
	v_mov_b32_e32 v115, 0
	v_mov_b32_e32 v116, 0
	v_mov_b32_e32 v117, 0
	s_cbranch_vccz .LBB0_570
	v_mul_hi_i32 v74, v118, s51
	v_lshrrev_b32_e32 v75, 31, v74
	v_ashrrev_i32_e32 v74, 2, v74
	v_add_u32_e32 v75, v74, v75
	v_sub_u32_e32 v74, 0x7f, v75
	v_cndmask_b32_e64 v74, v74, v75, s[6:7]
	v_add_u32_e32 v74, s22, v74
	v_mul_lo_u32 v75, v75, 10
	v_sub_u32_e32 v80, v118, v75
	v_ashrrev_i32_e32 v75, 31, v74
	v_lshl_add_u64 v[76:77], s[78:79], 0, v[74:75]
	v_mov_b64_e32 v[78:79], s[64:65]
	v_mad_u64_u32 v[78:79], s[8:9], v76, s57, v[78:79]
	v_lshlrev_b32_e32 v76, 3, v80
	v_mad_i32_i24 v79, v77, s57, v79
	v_ashrrev_i32_e32 v77, 31, v76
	v_lshlrev_b64 v[76:77], 1, v[76:77]
	v_lshl_add_u64 v[78:79], v[78:79], 0, v[76:77]
	global_load_dwordx4 v[110:113], v[78:79], off
	v_lshl_add_u64 v[74:75], s[80:81], 0, v[74:75]
	v_mov_b64_e32 v[78:79], s[82:83]
	v_mad_u64_u32 v[78:79], s[8:9], v74, s96, v[78:79]
	v_mad_i32_i24 v79, v75, s96, v79
	v_lshl_add_u64 v[74:75], v[78:79], 0, v[76:77]
	global_load_dwordx4 v[114:117], v[74:75], off

; #define LAS __attribute__((address_space(3)))
; DI float bf1(unsigned short h) { return __uint_as_float(((unsigned)h) << 16); }
; DI float frcp(float x) { return __builtin_amdgcn_rcpf(x); }
; DI void lru_unit_run(LruUnit& U, const bf16x8 (&wr)[3], const bf16x8 (&wi)[3], LAS unsigned char* xcb, LAS unsigned char* hst, int cb, int lane) {
;     ...
;         for (int t = 0; t < 4; ++t) {
;             const int tb = 4 * half + t;
;             f32x4 ar = {0.f, 0.f, 0.f, 0.f}, ai = {0.f, 0.f, 0.f, 0.f};
; #pragma unroll
;             for (int ks = 0; ks < 3; ++ks) {
;                 const bf16x8 a = *(const LAS bf16x8*)(xcb + (16 * tb + c) * 192 + (32 * ks + 8 * q) * 2);
;                 ar = __builtin_amdgcn_mfma_f32_16x16x32_bf16(a, wr[ks], ar, 0, 0, 0);
;                 ai = __builtin_amdgcn_mfma_f32_16x16x32_bf16(a, wi[ks], ai, 0, 0, 0);
;             }
; #pragma unroll
;             for (int e = 0; e < 4; ++e) {
;                 const int s = 16 * tb + 4 * q + e;
;                 const float xc = bf1(*(const LAS unsigned short*)(xcb + s * 192 + (16 * cb + c) * 2));
;                 const float r = frcp(1.0f + __builtin_amdgcn_exp2f(-(ar[e] + U.ba))), ig = frcp(1.0f + __builtin_amdgcn_exp2f(-(ai[e] + U.bx)));
;                 const float a = __builtin_amdgcn_exp2f(U.kk * r);
;                 av[t][e] = a; bv[t][e] = __builtin_amdgcn_sqrtf(fmaxf(1.0f - a * a, 0.f)) * ig * xc;
;             }
;             Ac[t] = av[t][0] * av[t][1] * av[t][2] * av[t][3];
;             Bc[t] = ((bv[t][0] * av[t][1] + bv[t][1]) * av[t][2] + bv[t][2]) * av[t][3] + bv[t][3];
.LBB0_579:
	v_or_b32_e32 v118, s1, v200
	v_mad_u32_u24 v130, v118, s93, v203
	ds_read_b128 v[118:121], v130 offset:41984
	ds_read_b128 v[126:129], v130 offset:42048
	v_or_b32_e32 v226, s1, v204
	s_or_b32 s2, s1, 16
	s_and_b64 vcc, exec, s[20:21]
	s_mov_b64 s[20:21], 0
	s_waitcnt vmcnt(11) lgkmcnt(1)
	v_mfma_f32_16x16x32_bf16 v[122:125], v[118:121], v[2:5], 0
	s_waitcnt vmcnt(10)
	v_mfma_f32_16x16x32_bf16 v[118:121], v[118:121], v[6:9], 0
	s_waitcnt vmcnt(7) lgkmcnt(0)
	v_mfma_f32_16x16x32_bf16 v[122:125], v[126:129], v[18:21], v[122:125]
	s_waitcnt vmcnt(6)
	v_mfma_f32_16x16x32_bf16 v[118:121], v[126:129], v[22:25], v[118:121]
	ds_read_b128 v[126:129], v130 offset:42112
	s_waitcnt vmcnt(3) lgkmcnt(0)
	v_mfma_f32_16x16x32_bf16 v[122:125], v[126:129], v[34:37], v[122:125]
	s_waitcnt vmcnt(2)
	v_mfma_f32_16x16x32_bf16 v[128:131], v[126:129], v[38:41], v[118:121]
	s_nop 2
	v_mad_u32_u24 v119, v226, s93, v205
	ds_read_u16 v146, v119 offset:41984
	ds_read_u16 v147, v119 offset:42176
	ds_read_u16 v148, v119 offset:42368
	ds_read_u16 v149, v119 offset:42560
	v_add_f32_e32 v119, v186, v125
	v_exp_f32_e64 v119, -v119
	v_add_f32_e32 v121, v220, v129
	v_exp_f32_e64 v121, -v121
	v_add_f32_e32 v120, v220, v128
	v_add_f32_e32 v119, 1.0, v119
	v_rcp_f32_e32 v119, v119
	v_add_f32_e32 v121, 1.0, v121
	v_rcp_f32_e32 v128, v121
	v_add_f32_e32 v121, v186, v124
	v_mul_f32_e32 v119, v187, v119
	v_exp_f32_e32 v124, v119
	v_or_b32_e32 v119, s2, v200
	v_mad_u32_u24 v119, v119, s93, v203
	ds_read_b128 v[134:137], v119 offset:41984
	ds_read_b128 v[142:145], v119 offset:42048
	s_waitcnt lgkmcnt(1)
	v_mfma_f32_16x16x32_bf16 v[138:141], v[134:137], v[2:5], 0
	v_exp_f32_e64 v121, -v121
	v_add_f32_e32 v118, v186, v122
	v_add_f32_e32 v122, v220, v130
	v_mfma_f32_16x16x32_bf16 v[134:137], v[134:137], v[6:9], 0
	v_add_f32_e32 v121, 1.0, v121
	v_rcp_f32_e32 v121, v121
	v_exp_f32_e64 v122, -v122
	s_waitcnt lgkmcnt(0)
	v_mfma_f32_16x16x32_bf16 v[138:141], v[142:145], v[18:21], v[138:141]
	v_exp_f32_e64 v120, -v120
	v_mul_f32_e32 v121, v187, v121
	v_add_f32_e32 v122, 1.0, v122
	v_mfma_f32_16x16x32_bf16 v[134:137], v[142:145], v[22:25], v[134:137]
	ds_read_b128 v[142:145], v119 offset:42112
	v_rcp_f32_e32 v130, v122
	v_exp_f32_e32 v122, v121
	v_add_f32_e32 v121, v220, v131
	v_exp_f32_e64 v121, -v121
	s_waitcnt lgkmcnt(0)
	v_mfma_f32_16x16x32_bf16 v[138:141], v[142:145], v[34:37], v[138:141]
	v_exp_f32_e64 v118, -v118
	v_or_b32_e32 v119, s2, v204
	v_add_f32_e32 v121, 1.0, v121
	v_mfma_f32_16x16x32_bf16 v[134:137], v[142:145], v[38:41], v[134:137]
	v_mad_u32_u24 v125, v119, s93, v205
	s_nop 2
	v_add_f32_e32 v119, v186, v138
	v_rcp_f32_e32 v132, v121
	v_exp_f32_e64 v119, -v119
	v_add_f32_e32 v120, 1.0, v120
	v_add_f32_e32 v121, v220, v134
	v_exp_f32_e64 v121, -v121
	v_add_f32_e32 v118, 1.0, v118
	v_rcp_f32_e32 v126, v120
	v_add_f32_e32 v120, v186, v123
	v_add_f32_e32 v123, v220, v135
	v_rcp_f32_e32 v118, v118
	v_exp_f32_e64 v123, -v123
	v_add_f32_e32 v119, 1.0, v119
	v_rcp_f32_e32 v119, v119
	v_add_f32_e32 v121, 1.0, v121
	v_rcp_f32_e32 v127, v121
	v_add_f32_e32 v121, v186, v139
	v_mul_f32_e32 v118, v187, v118
	v_exp_f32_e64 v120, -v120
	ds_read_u16 v142, v125 offset:41984
	ds_read_u16 v134, v125 offset:42176
	ds_read_u16 v135, v125 offset:42368
	ds_read_u16 v143, v125 offset:42560
	v_exp_f32_e64 v121, -v121
	v_add_f32_e32 v123, 1.0, v123
	v_exp_f32_e32 v118, v118
	v_rcp_f32_e32 v129, v123
	v_add_f32_e32 v123, v186, v140
	v_mul_f32_e32 v119, v187, v119
	v_exp_f32_e64 v123, -v123
	v_exp_f32_e32 v119, v119
	v_add_f32_e32 v125, v186, v141
	v_add_f32_e32 v120, 1.0, v120
	v_add_f32_e32 v121, 1.0, v121
	v_exp_f32_e64 v125, -v125
	v_rcp_f32_e32 v120, v120
	v_rcp_f32_e32 v121, v121
	s_waitcnt lgkmcnt(2)
	v_lshlrev_b32_e32 v139, 16, v134
	v_fma_f32 v134, -v118, v118, 1.0
	v_add_f32_e32 v123, 1.0, v123
	v_max_f32_e32 v134, 0, v134
	v_rcp_f32_e32 v123, v123
	v_sqrt_f32_e32 v144, v134
	v_fma_f32 v134, -v119, v119, 1.0
	v_add_f32_e32 v125, 1.0, v125
	v_max_f32_e32 v134, 0, v134
	v_mul_f32_e32 v120, v187, v120
	v_mul_f32_e32 v121, v187, v121
	v_rcp_f32_e32 v125, v125
	v_sqrt_f32_e32 v145, v134
	v_exp_f32_e32 v120, v120
	v_exp_f32_e32 v121, v121
	v_mul_f32_e32 v123, v187, v123
	v_exp_f32_e32 v123, v123
	v_add_f32_e32 v131, v220, v136
	v_add_f32_e32 v133, v220, v137
	v_mul_f32_e32 v125, v187, v125
	v_lshlrev_b32_e32 v136, 16, v146
	v_lshlrev_b32_e32 v137, 16, v142
	v_pk_mul_f32 v[126:127], v[126:127], v[144:145]
	v_exp_f32_e32 v125, v125
	v_fma_f32 v134, -v120, v120, 1.0
	v_pk_mul_f32 v[126:127], v[126:127], v[136:137]
	v_fma_f32 v136, -v121, v121, 1.0
	v_exp_f32_e64 v131, -v131
	v_exp_f32_e64 v133, -v133
	v_max_f32_e32 v134, 0, v134
	v_max_f32_e32 v136, 0, v136
	v_lshlrev_b32_e32 v138, 16, v147
	v_sqrt_f32_e32 v146, v134
	v_fma_f32 v134, -v122, v122, 1.0
	v_sqrt_f32_e32 v147, v136
	v_fma_f32 v136, -v123, v123, 1.0
	v_max_f32_e32 v134, 0, v134
	v_max_f32_e32 v136, 0, v136
	v_lshlrev_b32_e32 v140, 16, v148
	v_lshlrev_b32_e32 v142, 16, v149
	v_sqrt_f32_e32 v148, v134
	v_fma_f32 v134, -v124, v124, 1.0
	v_sqrt_f32_e32 v149, v136
	v_fma_f32 v136, -v125, v125, 1.0
	v_add_f32_e32 v131, 1.0, v131
	v_add_f32_e32 v133, 1.0, v133
	v_max_f32_e32 v134, 0, v134
	v_max_f32_e32 v136, 0, v136
	v_rcp_f32_e32 v131, v131
	v_rcp_f32_e32 v133, v133
	v_sqrt_f32_e32 v182, v134
	v_sqrt_f32_e32 v183, v136
	v_pk_mul_f32 v[128:129], v[128:129], v[146:147]
	s_or_b32 s2, s1, 32
	v_pk_mul_f32 v[128:129], v[128:129], v[138:139]
	v_or_b32_e32 v138, s2, v200
	s_waitcnt lgkmcnt(1)
; #define LAS __attribute__((address_space(3)))
; DI float bf1(unsigned short h) { return __uint_as_float(((unsigned)h) << 16); }
; DI float frcp(float x) { return __builtin_amdgcn_rcpf(x); }
; DI void lru_unit_run(LruUnit& U, const bf16x8 (&wr)[3], const bf16x8 (&wi)[3], LAS unsigned char* xcb, LAS unsigned char* hst, int cb, int lane) {
;     ...
;         for (int t = 0; t < 4; ++t) {
;             const int tb = 4 * half + t;
;             f32x4 ar = {0.f, 0.f, 0.f, 0.f}, ai = {0.f, 0.f, 0.f, 0.f};
; #pragma unroll
;             for (int ks = 0; ks < 3; ++ks) {
;                 const bf16x8 a = *(const LAS bf16x8*)(xcb + (16 * tb + c) * 192 + (32 * ks + 8 * q) * 2);
;                 ar = __builtin_amdgcn_mfma_f32_16x16x32_bf16(a, wr[ks], ar, 0, 0, 0);
;                 ai = __builtin_amdgcn_mfma_f32_16x16x32_bf16(a, wi[ks], ai, 0, 0, 0);
;             }
; #pragma unroll
;             for (int e = 0; e < 4; ++e) {
;                 const int s = 16 * tb + 4 * q + e;
;                 const float xc = bf1(*(const LAS unsigned short*)(xcb + s * 192 + (16 * cb + c) * 2));
;                 const float r = frcp(1.0f + __builtin_amdgcn_exp2f(-(ar[e] + U.ba))), ig = frcp(1.0f + __builtin_amdgcn_exp2f(-(ai[e] + U.bx)));
;                 const float a = __builtin_amdgcn_exp2f(U.kk * r);
;                 av[t][e] = a; bv[t][e] = __builtin_amdgcn_sqrtf(fmaxf(1.0f - a * a, 0.f)) * ig * xc;
;             }
;             Ac[t] = av[t][0] * av[t][1] * av[t][2] * av[t][3];
;             Bc[t] = ((bv[t][0] * av[t][1] + bv[t][1]) * av[t][2] + bv[t][2]) * av[t][3] + bv[t][3];
	v_lshlrev_b32_e32 v141, 16, v135
	v_pk_mul_f32 v[130:131], v[130:131], v[148:149]
	v_pk_mul_f32 v[132:133], v[132:133], v[182:183]
	v_mad_u32_u24 v182, v138, s93, v203
	v_pk_mul_f32 v[130:131], v[130:131], v[140:141]
	ds_read_b128 v[138:141], v182 offset:41984
	ds_read_b128 v[146:149], v182 offset:42048
	s_waitcnt lgkmcnt(2)
	v_lshlrev_b32_e32 v143, 16, v143
	v_pk_mul_f32 v[132:133], v[132:133], v[142:143]
	s_waitcnt lgkmcnt(1)
	v_mfma_f32_16x16x32_bf16 v[142:145], v[138:141], v[2:5], 0
	s_or_b32 s1, s1, 48
	v_pk_mul_f32 v[134:135], v[118:119], v[120:121]
	v_pk_fma_f32 v[136:137], v[120:121], v[126:127], v[128:129]
	v_mfma_f32_16x16x32_bf16 v[138:141], v[138:141], v[6:9], 0
	v_mul_f32_e64 v134, v122, v134
	v_mul_f32_e64 v135, v123, v135
	v_pk_fma_f32 v[136:137], v[122:123], v[136:137], v[130:131]
	v_pk_mul_f32 v[134:135], v[124:125], v[134:135]
	s_waitcnt lgkmcnt(0)
	v_mfma_f32_16x16x32_bf16 v[142:145], v[146:149], v[18:21], v[142:145]
	v_fma_f32 v136, v124, v136, v132
	v_fma_f32 v137, v125, v137, v133
	v_mfma_f32_16x16x32_bf16 v[138:141], v[146:149], v[22:25], v[138:141]
	ds_read_b128 v[146:149], v182 offset:42112
	s_waitcnt lgkmcnt(0)
	v_mfma_f32_16x16x32_bf16 v[142:145], v[146:149], v[34:37], v[142:145]
	v_mfma_f32_16x16x32_bf16 v[182:185], v[146:149], v[38:41], v[138:141]
	s_nop 3
	v_or_b32_e32 v138, s2, v204
	v_mad_u32_u24 v139, v138, s93, v205
	ds_read_u16 v227, v139 offset:41984
	ds_read_u16 v240, v139 offset:42176
	ds_read_u16 v241, v139 offset:42368
	ds_read_u16 v242, v139 offset:42560
	v_add_f32_e32 v139, v186, v145
	v_exp_f32_e64 v139, -v139
	v_add_f32_e32 v141, v220, v183
	v_exp_f32_e64 v141, -v141
	v_add_f32_e32 v138, v186, v142
	v_add_f32_e32 v139, 1.0, v139
	v_rcp_f32_e32 v139, v139
	v_add_f32_e32 v141, 1.0, v141
	v_rcp_f32_e32 v148, v141
	v_add_f32_e32 v141, v186, v144
	v_mul_f32_e32 v139, v187, v139
	v_exp_f32_e32 v144, v139
	v_or_b32_e32 v139, s1, v200
	v_mad_u32_u24 v139, v139, s93, v203
	ds_read_b128 v[228:231], v139 offset:41984
	ds_read_b128 v[236:239], v139 offset:42048
	s_waitcnt lgkmcnt(1)
	v_mfma_f32_16x16x32_bf16 v[232:235], v[228:231], v[2:5], 0
	v_exp_f32_e64 v141, -v141
	v_add_f32_e32 v142, v220, v184
	v_exp_f32_e64 v142, -v142
	v_mfma_f32_16x16x32_bf16 v[228:231], v[228:231], v[6:9], 0
	v_add_f32_e32 v141, 1.0, v141
	v_rcp_f32_e32 v141, v141
	v_add_f32_e32 v142, 1.0, v142
	s_waitcnt lgkmcnt(0)
	v_mfma_f32_16x16x32_bf16 v[232:235], v[236:239], v[18:21], v[232:235]
	v_add_f32_e32 v140, v220, v182
	v_mul_f32_e32 v141, v187, v141
	v_rcp_f32_e32 v182, v142
	v_mfma_f32_16x16x32_bf16 v[228:231], v[236:239], v[22:25], v[228:231]
	ds_read_b128 v[236:239], v139 offset:42112
	v_exp_f32_e32 v142, v141
	v_add_f32_e32 v141, v220, v185
	s_waitcnt lgkmcnt(0)
	v_mfma_f32_16x16x32_bf16 v[232:235], v[236:239], v[34:37], v[232:235]
	v_exp_f32_e64 v140, -v140
	v_exp_f32_e64 v141, -v141
	v_exp_f32_e64 v138, -v138
	v_mfma_f32_16x16x32_bf16 v[228:231], v[236:239], v[38:41], v[228:231]
	v_or_b32_e32 v139, s1, v204
	v_mad_u32_u24 v145, v139, s93, v205
	s_nop 1
	v_add_f32_e32 v139, v186, v232
	v_add_f32_e32 v140, 1.0, v140
	v_add_f32_e32 v141, 1.0, v141
	v_exp_f32_e64 v139, -v139
	v_rcp_f32_e32 v146, v140
	v_add_f32_e32 v140, v186, v143
	v_rcp_f32_e32 v184, v141
	v_add_f32_e32 v141, v220, v228
	v_add_f32_e32 v138, 1.0, v138
	v_exp_f32_e64 v140, -v140
	v_exp_f32_e64 v141, -v141
	v_rcp_f32_e32 v138, v138
	v_add_f32_e32 v143, v220, v229
	v_add_f32_e32 v139, 1.0, v139
	v_exp_f32_e64 v143, -v143
	v_rcp_f32_e32 v139, v139
	v_add_f32_e32 v140, 1.0, v140
	v_add_f32_e32 v141, 1.0, v141
	v_mul_f32_e32 v138, v187, v138
	v_rcp_f32_e32 v140, v140
	v_rcp_f32_e32 v147, v141
	v_add_f32_e32 v141, v186, v233
	v_exp_f32_e32 v138, v138
	v_exp_f32_e64 v141, -v141
	v_add_f32_e32 v143, 1.0, v143
	ds_read_u16 v236, v145 offset:41984
	ds_read_u16 v232, v145 offset:42176
	ds_read_u16 v233, v145 offset:42368
	v_mul_f32_e32 v139, v187, v139
	v_rcp_f32_e32 v149, v143
	v_add_f32_e32 v143, v186, v234
	v_exp_f32_e32 v139, v139
	v_exp_f32_e64 v143, -v143
	v_mul_f32_e32 v140, v187, v140
	ds_read_u16 v234, v145 offset:42560
	v_add_f32_e32 v145, v186, v235
	v_exp_f32_e32 v140, v140
	v_add_f32_e32 v141, 1.0, v141
	v_exp_f32_e64 v145, -v145
	v_lshlrev_b32_e32 v228, 16, v227
	v_fma_f32 v227, -v138, v138, 1.0
	v_rcp_f32_e32 v141, v141
	v_max_f32_e32 v227, 0, v227
	v_add_f32_e32 v143, 1.0, v143
	s_waitcnt lgkmcnt(3)
	v_lshlrev_b32_e32 v229, 16, v236
	v_sqrt_f32_e32 v236, v227
	v_fma_f32 v227, -v139, v139, 1.0
	v_rcp_f32_e32 v143, v143
	v_max_f32_e32 v227, 0, v227
	v_add_f32_e32 v145, 1.0, v145
	v_sqrt_f32_e32 v237, v227
	v_fma_f32 v227, -v140, v140, 1.0
	v_mul_f32_e32 v141, v187, v141
	v_rcp_f32_e32 v145, v145
	v_max_f32_e32 v227, 0, v227
	v_exp_f32_e32 v141, v141
	v_sqrt_f32_e32 v238, v227
	v_fma_f32 v227, -v142, v142, 1.0
	v_mul_f32_e32 v143, v187, v143
	v_max_f32_e32 v227, 0, v227
	v_add_f32_e32 v183, v220, v230
	v_exp_f32_e32 v143, v143
	v_lshlrev_b32_e32 v230, 16, v240
	v_sqrt_f32_e32 v240, v227
	v_fma_f32 v227, -v144, v144, 1.0
	v_mul_f32_e32 v145, v187, v145
	v_max_f32_e32 v227, 0, v227
	v_exp_f32_e64 v183, -v183
	v_add_f32_e32 v185, v220, v231
	v_exp_f32_e32 v145, v145
	s_waitcnt lgkmcnt(0)
; #define LAS __attribute__((address_space(3)))
; DI unsigned pk2(float lo, float hi) { f32x2_t v = {lo, hi}; bf16x2_t b = __builtin_convertvector(v, bf16x2_t); return __builtin_bit_cast(unsigned, b); }
; DI void lru_unit_run(LruUnit& U, const bf16x8 (&wr)[3], const bf16x8 (&wi)[3], LAS unsigned char* xcb, LAS unsigned char* hst, int cb, int lane) {
;     ...
;             Ac[t] = av[t][0] * av[t][1] * av[t][2] * av[t][3];
;             Bc[t] = ((bv[t][0] * av[t][1] + bv[t][1]) * av[t][2] + bv[t][2]) * av[t][3] + bv[t][3];
;         }
; #pragma unroll
;         for (int t = 0; t < 4; ++t) { const float A1 = __shfl_up(Ac[t], 16), B1 = __shfl_up(Bc[t], 16); if (q >= 1) { Bc[t] = Ac[t] * B1 + Bc[t]; Ac[t] = A1 * Ac[t]; } }
; #pragma unroll
;         for (int t = 0; t < 4; ++t) { const float A2 = __shfl_up(Ac[t], 32), B2 = __shfl_up(Bc[t], 32); if (q >= 2) { Bc[t] = Ac[t] * B2 + Bc[t]; Ac[t] = A2 * Ac[t]; } }
;         float At[4], Bt[4], Ae[4], Be[4];
; #pragma unroll
;         for (int t = 0; t < 4; ++t) { At[t] = __shfl(Ac[t], 48 + c); Bt[t] = __shfl(Bc[t], 48 + c); Ae[t] = __shfl_up(Ac[t], 16); Be[t] = __shfl_up(Bc[t], 16); }
; #pragma unroll
;         for (int t = 0; t < 4; ++t) {
;             const int tb = 4 * half + t;
;             float h = (q == 0) ? hc : (Ae[t] * hc + Be[t]);
; #pragma unroll
;             for (int e = 0; e < 4; ++e) { h = av[t][e] * h + bv[t][e]; *(LAS unsigned short*)(hst + (16 * tb + 4 * q + e) * 160 + (16 * cb + c) * 2) = (unsigned short)pk2(h, 0.f); }
;             hc = At[t] * hc + Bt[t];
;         }
	v_lshlrev_b32_e32 v235, 16, v234
	v_lshlrev_b32_e32 v234, 16, v242
	v_sqrt_f32_e32 v242, v227
	v_fma_f32 v227, -v141, v141, 1.0
	v_exp_f32_e64 v185, -v185
	v_max_f32_e32 v227, 0, v227
	v_sqrt_f32_e32 v239, v227
	v_fma_f32 v227, -v143, v143, 1.0
	v_max_f32_e32 v227, 0, v227
	v_add_f32_e32 v183, 1.0, v183
	v_lshlrev_b32_e32 v231, 16, v232
	v_lshlrev_b32_e32 v232, 16, v241
	v_sqrt_f32_e32 v241, v227
	v_fma_f32 v227, -v145, v145, 1.0
	v_rcp_f32_e32 v183, v183
	v_add_f32_e32 v185, 1.0, v185
	v_max_f32_e32 v227, 0, v227
	v_rcp_f32_e32 v185, v185
	v_sqrt_f32_e32 v243, v227
	v_lshlrev_b32_e32 v233, 16, v233
	v_pk_mul_f32 v[148:149], v[148:149], v[238:239]
	v_pk_mul_f32 v[182:183], v[182:183], v[240:241]
	v_pk_mul_f32 v[148:149], v[148:149], v[230:231]
	v_pk_mul_f32 v[182:183], v[182:183], v[232:233]
	v_pk_mul_f32 v[184:185], v[184:185], v[242:243]
	v_cndmask_b32_e64 v231, v137, v137, s[16:17]
	v_cndmask_b32_e64 v232, v135, v135, s[16:17]
	v_pk_mul_f32 v[146:147], v[146:147], v[236:237]
	v_pk_mul_f32 v[184:185], v[184:185], v[234:235]
	ds_bpermute_b32 v233, v223, v232
	ds_bpermute_b32 v234, v223, v231
	v_pk_mul_f32 v[146:147], v[146:147], v[228:229]
	v_pk_mul_f32 v[244:245], v[138:139], v[140:141]
	v_pk_fma_f32 v[228:229], v[140:141], v[146:147], v[148:149]
	v_pk_mul_f32 v[244:245], v[142:143], v[244:245]
	v_pk_fma_f32 v[228:229], v[142:143], v[228:229], v[182:183]
	v_pk_mul_f32 v[244:245], v[144:145], v[244:245]
	v_pk_fma_f32 v[228:229], v[144:145], v[228:229], v[184:185]
	ds_bpermute_b32 v227, v223, v134
	ds_bpermute_b32 v230, v223, v136
	s_waitcnt lgkmcnt(2)
	v_fmac_f32_e32 v231, v232, v234
	v_mul_f32_e32 v232, v232, v233
	v_cndmask_b32_e64 v233, v228, v228, s[16:17]
	v_cndmask_b32_e64 v234, v244, v244, s[16:17]
	ds_bpermute_b32 v235, v223, v234
	ds_bpermute_b32 v236, v223, v233
	s_waitcnt lgkmcnt(2)
	v_fma_f32 v230, v134, v230, v136
	v_mul_f32_e32 v227, v134, v227
	v_cndmask_b32_e64 v136, v230, v136, s[16:17]
	v_cndmask_b32_e64 v134, v227, v134, s[16:17]
	s_waitcnt lgkmcnt(0)
	v_fmac_f32_e32 v233, v234, v236
	v_mul_f32_e32 v234, v234, v235
	v_cndmask_b32_e64 v235, v229, v229, s[16:17]
	v_cndmask_b32_e64 v236, v245, v245, s[16:17]
	v_cndmask_b32_e64 v137, v231, v137, s[16:17]
	v_cndmask_b32_e64 v135, v232, v135, s[16:17]
	ds_bpermute_b32 v227, v224, v134
	ds_bpermute_b32 v232, v224, v136
	ds_bpermute_b32 v237, v223, v236
	ds_bpermute_b32 v238, v223, v235
	v_cndmask_b32_e64 v228, v233, v228, s[16:17]
	v_cndmask_b32_e64 v231, v234, v244, s[16:17]
	ds_bpermute_b32 v233, v224, v135
	ds_bpermute_b32 v234, v224, v137
	s_waitcnt lgkmcnt(4)
	v_fma_f32 v232, v134, v232, v136
	v_mul_f32_e32 v227, v134, v227
	s_waitcnt lgkmcnt(2)
	v_fmac_f32_e32 v235, v236, v238
	v_mul_f32_e32 v236, v236, v237
	s_waitcnt lgkmcnt(0)
	v_fma_f32 v234, v135, v234, v137
	v_mul_f32_e32 v233, v135, v233
	v_cndmask_b32_e64 v136, v136, v232, s[18:19]
	v_cndmask_b32_e64 v134, v134, v227, s[18:19]
	v_cndmask_b32_e64 v229, v235, v229, s[16:17]
	v_cndmask_b32_e64 v230, v236, v245, s[16:17]
	ds_bpermute_b32 v235, v224, v231
	ds_bpermute_b32 v236, v224, v228
	v_cndmask_b32_e64 v137, v137, v234, s[18:19]
	v_cndmask_b32_e64 v135, v135, v233, s[18:19]
	ds_bpermute_b32 v227, v225, v134
	ds_bpermute_b32 v232, v225, v136
	ds_bpermute_b32 v134, v223, v134
	ds_bpermute_b32 v136, v223, v136
	ds_bpermute_b32 v233, v225, v135
	ds_bpermute_b32 v234, v225, v137
	ds_bpermute_b32 v135, v223, v135
	ds_bpermute_b32 v137, v223, v137
	s_waitcnt lgkmcnt(8)
	v_fma_f32 v236, v231, v236, v228
	v_mul_f32_e32 v235, v231, v235
	s_waitcnt lgkmcnt(6)
	v_fmac_f32_e32 v232, v1, v227
	ds_bpermute_b32 v237, v224, v230
	ds_bpermute_b32 v238, v224, v229
	v_cndmask_b32_e64 v228, v228, v236, s[18:19]
	v_cndmask_b32_e64 v231, v231, v235, s[18:19]
	s_waitcnt lgkmcnt(6)
	v_fmac_f32_e32 v136, v1, v134
	s_waitcnt lgkmcnt(2)
	v_fmac_f32_e32 v137, v232, v135
	ds_bpermute_b32 v235, v225, v231
	ds_bpermute_b32 v236, v225, v228
	ds_bpermute_b32 v231, v223, v231
	ds_bpermute_b32 v228, v223, v228
	v_cndmask_b32_e64 v134, v136, v1, s[16:17]
	v_cndmask_b32_e64 v1, v137, v232, s[16:17]
	v_fmac_f32_e32 v127, v119, v1
	v_fma_f32 v118, v118, v134, v126
	v_mad_u32_u24 v134, v226, s57, v206
	v_cvt_pk_bf16_f32 v1, v127, s0
	v_fmac_f32_e32 v129, v121, v127
	ds_write_b16 v134, v1 offset:2560
	v_cvt_pk_bf16_f32 v1, v129, s0
	v_fmac_f32_e32 v131, v123, v129
	s_waitcnt lgkmcnt(5)
	v_fma_f32 v238, v230, v238, v229
	v_mul_f32_e32 v237, v230, v237
	v_cvt_pk_bf16_f32 v126, v118, s0
	v_fma_f32 v118, v120, v118, v128
	ds_write_b16 v134, v1 offset:2720
	v_cvt_pk_bf16_f32 v1, v131, s0
	v_fmac_f32_e32 v133, v125, v131
	v_fmac_f32_e32 v234, v232, v233
	v_cndmask_b32_e64 v229, v229, v238, s[18:19]
	v_cndmask_b32_e64 v230, v230, v237, s[18:19]
	v_cvt_pk_bf16_f32 v120, v118, s0
	v_fma_f32 v118, v122, v118, v130
	ds_write_b16 v134, v1 offset:2880
	v_cvt_pk_bf16_f32 v1, v133, s0
	s_waitcnt lgkmcnt(3)
	v_fmac_f32_e32 v228, v234, v231
	ds_bpermute_b32 v237, v225, v230
	ds_bpermute_b32 v238, v225, v229
	ds_bpermute_b32 v230, v223, v230
	ds_bpermute_b32 v229, v223, v229
	ds_write_b16 v134, v120 offset:160
	v_cvt_pk_bf16_f32 v120, v118, s0
	v_fma_f32 v118, v124, v118, v132
	ds_write_b16 v134, v1 offset:3040
	v_cndmask_b32_e64 v1, v228, v234, s[16:17]
	v_cvt_pk_bf16_f32 v118, v118, s0
	v_fma_f32 v1, v138, v1, v146
	ds_write_b16 v134, v118 offset:480
	v_cvt_pk_bf16_f32 v118, v1, s0
	v_fma_f32 v1, v140, v1, v148
	ds_write_b16 v134, v118 offset:5120
	v_cvt_pk_bf16_f32 v118, v1, s0
	v_fma_f32 v1, v142, v1, v182
	ds_write_b16 v134, v118 offset:5280
	v_cvt_pk_bf16_f32 v118, v1, s0
	v_fma_f32 v1, v144, v1, v184
	v_fmac_f32_e32 v236, v234, v235
	v_cvt_pk_bf16_f32 v1, v1, s0
	s_waitcnt lgkmcnt(5)
	v_fmac_f32_e32 v229, v236, v230
	ds_write_b16 v134, v1 offset:5600
	v_cndmask_b32_e64 v1, v229, v236, s[16:17]
	v_fmac_f32_e32 v147, v139, v1
	v_cvt_pk_bf16_f32 v1, v147, s0
	v_fmac_f32_e32 v149, v141, v147
	ds_write_b16 v134, v1 offset:7680
	v_cvt_pk_bf16_f32 v1, v149, s0
	v_fmac_f32_e32 v183, v143, v149
	ds_write_b16 v134, v1 offset:7840
	v_cvt_pk_bf16_f32 v1, v183, s0
	v_fmac_f32_e32 v185, v145, v183
	ds_write_b16 v134, v1 offset:8000
	v_cvt_pk_bf16_f32 v1, v185, s0
	ds_write_b16 v134, v1 offset:8160
	v_mov_b32_e32 v1, v238
	v_fmac_f32_e32 v1, v236, v237
	s_mov_b32 s1, 64
	ds_write_b16 v134, v126
	ds_write_b16 v134, v120 offset:320
	ds_write_b16 v134, v118 offset:5440
	s_cbranch_vccnz .LBB0_579
	s_andn2_b64 vcc, exec, s[24:25]
	s_cbranch_vccnz .LBB0_583
	s_mov_b32 s1, 0
	s_mov_b64 s[20:21], -1
; #define LAS __attribute__((address_space(3)))
; DI float bf1(unsigned short h) { return __uint_as_float(((unsigned)h) << 16); }
; DI float frcp(float x) { return __builtin_amdgcn_rcpf(x); }
; DI void lru_unit_run(LruUnit& U, const bf16x8 (&wr)[3], const bf16x8 (&wi)[3], LAS unsigned char* xcb, LAS unsigned char* hst, int cb, int lane) {
;     ...
;         for (int t = 0; t < 4; ++t) {
;             const int tb = 4 * half + t;
;             f32x4 ar = {0.f, 0.f, 0.f, 0.f}, ai = {0.f, 0.f, 0.f, 0.f};
; #pragma unroll
;             for (int ks = 0; ks < 3; ++ks) {
;                 const bf16x8 a = *(const LAS bf16x8*)(xcb + (16 * tb + c) * 192 + (32 * ks + 8 * q) * 2);
;                 ar = __builtin_amdgcn_mfma_f32_16x16x32_bf16(a, wr[ks], ar, 0, 0, 0);
;                 ai = __builtin_amdgcn_mfma_f32_16x16x32_bf16(a, wi[ks], ai, 0, 0, 0);
;             }
; #pragma unroll
;             for (int e = 0; e < 4; ++e) {
;                 const int s = 16 * tb + 4 * q + e;
;                 const float xc = bf1(*(const LAS unsigned short*)(xcb + s * 192 + (16 * cb + c) * 2));
;                 const float r = frcp(1.0f + __builtin_amdgcn_exp2f(-(ar[e] + U.ba))), ig = frcp(1.0f + __builtin_amdgcn_exp2f(-(ai[e] + U.bx)));
;                 const float a = __builtin_amdgcn_exp2f(U.kk * r);
;                 av[t][e] = a; bv[t][e] = __builtin_amdgcn_sqrtf(fmaxf(1.0f - a * a, 0.f)) * ig * xc;
;             }
;             Ac[t] = av[t][0] * av[t][1] * av[t][2] * av[t][3];
;             Bc[t] = ((bv[t][0] * av[t][1] + bv[t][1]) * av[t][2] + bv[t][2]) * av[t][3] + bv[t][3];
; DI void lru_item(KP A, const bf16* XL, const bf16* GL, bf16* HG, int b, int nb, LAS unsigned char* lds, int tid, int wave, int lane) {
;     ...
;         if (two) lru_unit_run(U1, w1r, w1i, lds + LRU_XCB + (u1 / 5) * LRU_XCB_SZ, lds + LRU_HST + (u1 / 5) * LRU_HST_SZ, u1 % 5, lane);
.LBB0_582:
	v_or_b32_e32 v118, s1, v200
	v_mad_u32_u24 v130, v118, s93, v207
	ds_read_b128 v[118:121], v130 offset:41984
	ds_read_b128 v[126:129], v130 offset:42048
	v_or_b32_e32 v226, s1, v204
	s_or_b32 s2, s1, 16
	s_and_b64 vcc, exec, s[20:21]
	s_mov_b64 s[20:21], 0
	s_waitcnt lgkmcnt(1)
	v_mfma_f32_16x16x32_bf16 v[122:125], v[118:121], v[10:13], 0
	v_mfma_f32_16x16x32_bf16 v[118:121], v[118:121], v[14:17], 0
	s_waitcnt lgkmcnt(0)
	v_mfma_f32_16x16x32_bf16 v[122:125], v[126:129], v[26:29], v[122:125]
	v_mfma_f32_16x16x32_bf16 v[118:121], v[126:129], v[30:33], v[118:121]
	ds_read_b128 v[126:129], v130 offset:42112
	s_waitcnt vmcnt(1) lgkmcnt(0)
	v_mfma_f32_16x16x32_bf16 v[122:125], v[126:129], v[42:45], v[122:125]
	s_waitcnt vmcnt(0)
	v_mfma_f32_16x16x32_bf16 v[128:131], v[126:129], v[46:49], v[118:121]
	s_nop 2
	v_mad_u32_u24 v119, v226, s93, v208
	ds_read_u16 v146, v119 offset:41984
	ds_read_u16 v147, v119 offset:42176
	ds_read_u16 v148, v119 offset:42368
	ds_read_u16 v149, v119 offset:42560
	v_add_f32_e32 v119, v219, v125
	v_exp_f32_e64 v119, -v119
	v_add_f32_e32 v121, v218, v129
	v_exp_f32_e64 v121, -v121
	v_add_f32_e32 v120, v218, v128
	v_add_f32_e32 v119, 1.0, v119
	v_rcp_f32_e32 v119, v119
	v_add_f32_e32 v121, 1.0, v121
	v_rcp_f32_e32 v128, v121
	v_add_f32_e32 v121, v219, v124
	v_mul_f32_e32 v119, v221, v119
	v_exp_f32_e32 v124, v119
	v_or_b32_e32 v119, s2, v200
	v_mad_u32_u24 v119, v119, s93, v207
	ds_read_b128 v[134:137], v119 offset:41984
	ds_read_b128 v[142:145], v119 offset:42048
	s_waitcnt lgkmcnt(1)
	v_mfma_f32_16x16x32_bf16 v[138:141], v[134:137], v[10:13], 0
	v_exp_f32_e64 v121, -v121
	v_add_f32_e32 v118, v219, v122
	v_add_f32_e32 v122, v218, v130
	v_mfma_f32_16x16x32_bf16 v[134:137], v[134:137], v[14:17], 0
	v_add_f32_e32 v121, 1.0, v121
	v_rcp_f32_e32 v121, v121
	v_exp_f32_e64 v122, -v122
	s_waitcnt lgkmcnt(0)
	v_mfma_f32_16x16x32_bf16 v[138:141], v[142:145], v[26:29], v[138:141]
	v_exp_f32_e64 v120, -v120
	v_mul_f32_e32 v121, v221, v121
	v_add_f32_e32 v122, 1.0, v122
	v_mfma_f32_16x16x32_bf16 v[134:137], v[142:145], v[30:33], v[134:137]
	ds_read_b128 v[142:145], v119 offset:42112
	v_rcp_f32_e32 v130, v122
	v_exp_f32_e32 v122, v121
	v_add_f32_e32 v121, v218, v131
	v_exp_f32_e64 v121, -v121
	s_waitcnt lgkmcnt(0)
	v_mfma_f32_16x16x32_bf16 v[138:141], v[142:145], v[42:45], v[138:141]
	v_exp_f32_e64 v118, -v118
	v_or_b32_e32 v119, s2, v204
	v_add_f32_e32 v121, 1.0, v121
	v_mfma_f32_16x16x32_bf16 v[134:137], v[142:145], v[46:49], v[134:137]
	v_mad_u32_u24 v125, v119, s93, v208
	s_nop 2
	v_add_f32_e32 v119, v219, v138
	v_rcp_f32_e32 v132, v121
	v_exp_f32_e64 v119, -v119
	v_add_f32_e32 v120, 1.0, v120
	v_add_f32_e32 v121, v218, v134
	v_exp_f32_e64 v121, -v121
	v_add_f32_e32 v118, 1.0, v118
	v_rcp_f32_e32 v126, v120
	v_add_f32_e32 v120, v219, v123
	v_add_f32_e32 v123, v218, v135
	v_rcp_f32_e32 v118, v118
	v_exp_f32_e64 v123, -v123
	v_add_f32_e32 v119, 1.0, v119
	v_rcp_f32_e32 v119, v119
	v_add_f32_e32 v121, 1.0, v121
	v_rcp_f32_e32 v127, v121
	v_add_f32_e32 v121, v219, v139
	v_mul_f32_e32 v118, v221, v118
	v_exp_f32_e64 v120, -v120
	ds_read_u16 v142, v125 offset:41984
	ds_read_u16 v134, v125 offset:42176
	ds_read_u16 v135, v125 offset:42368
	ds_read_u16 v143, v125 offset:42560
	v_exp_f32_e64 v121, -v121
	v_add_f32_e32 v123, 1.0, v123
	v_exp_f32_e32 v118, v118
	v_rcp_f32_e32 v129, v123
	v_add_f32_e32 v123, v219, v140
	v_mul_f32_e32 v119, v221, v119
	v_exp_f32_e64 v123, -v123
	v_exp_f32_e32 v119, v119
	v_add_f32_e32 v125, v219, v141
	v_add_f32_e32 v120, 1.0, v120
	v_add_f32_e32 v121, 1.0, v121
	v_exp_f32_e64 v125, -v125
	v_rcp_f32_e32 v120, v120
	v_rcp_f32_e32 v121, v121
	s_waitcnt lgkmcnt(2)
	v_lshlrev_b32_e32 v139, 16, v134
	v_fma_f32 v134, -v118, v118, 1.0
	v_add_f32_e32 v123, 1.0, v123
	v_max_f32_e32 v134, 0, v134
	v_rcp_f32_e32 v123, v123
	v_sqrt_f32_e32 v144, v134
	v_fma_f32 v134, -v119, v119, 1.0
	v_add_f32_e32 v125, 1.0, v125
	v_max_f32_e32 v134, 0, v134
	v_mul_f32_e32 v120, v221, v120
	v_mul_f32_e32 v121, v221, v121
	v_rcp_f32_e32 v125, v125
	v_sqrt_f32_e32 v145, v134
	v_exp_f32_e32 v120, v120
	v_exp_f32_e32 v121, v121
	v_mul_f32_e32 v123, v221, v123
	v_exp_f32_e32 v123, v123
	v_add_f32_e32 v131, v218, v136
	v_add_f32_e32 v133, v218, v137
	v_mul_f32_e32 v125, v221, v125
	v_lshlrev_b32_e32 v136, 16, v146
	v_lshlrev_b32_e32 v137, 16, v142
	v_pk_mul_f32 v[126:127], v[126:127], v[144:145]
	v_exp_f32_e32 v125, v125
	v_fma_f32 v134, -v120, v120, 1.0
	v_pk_mul_f32 v[126:127], v[126:127], v[136:137]
	v_fma_f32 v136, -v121, v121, 1.0
	v_exp_f32_e64 v131, -v131
	v_exp_f32_e64 v133, -v133
	v_max_f32_e32 v134, 0, v134
	v_max_f32_e32 v136, 0, v136
	v_lshlrev_b32_e32 v138, 16, v147
	v_sqrt_f32_e32 v146, v134
	v_fma_f32 v134, -v122, v122, 1.0
	v_sqrt_f32_e32 v147, v136
	v_fma_f32 v136, -v123, v123, 1.0
	v_max_f32_e32 v134, 0, v134
	v_max_f32_e32 v136, 0, v136
	v_lshlrev_b32_e32 v140, 16, v148
	v_lshlrev_b32_e32 v142, 16, v149
	v_sqrt_f32_e32 v148, v134
	v_fma_f32 v134, -v124, v124, 1.0
	v_sqrt_f32_e32 v149, v136
	v_fma_f32 v136, -v125, v125, 1.0
	v_add_f32_e32 v131, 1.0, v131
	v_add_f32_e32 v133, 1.0, v133
	v_max_f32_e32 v134, 0, v134
	v_max_f32_e32 v136, 0, v136
	v_rcp_f32_e32 v131, v131
	v_rcp_f32_e32 v133, v133
	v_sqrt_f32_e32 v182, v134
	v_sqrt_f32_e32 v183, v136
	v_pk_mul_f32 v[128:129], v[128:129], v[146:147]
	s_or_b32 s2, s1, 32
	v_pk_mul_f32 v[128:129], v[128:129], v[138:139]
	v_or_b32_e32 v138, s2, v200
	s_waitcnt lgkmcnt(1)
	v_lshlrev_b32_e32 v141, 16, v135
	v_pk_mul_f32 v[130:131], v[130:131], v[148:149]
	v_pk_mul_f32 v[132:133], v[132:133], v[182:183]
	v_mad_u32_u24 v182, v138, s93, v207
	v_pk_mul_f32 v[130:131], v[130:131], v[140:141]
	ds_read_b128 v[138:141], v182 offset:41984
	ds_read_b128 v[146:149], v182 offset:42048
	s_waitcnt lgkmcnt(2)
; #define LAS __attribute__((address_space(3)))
; DI float bf1(unsigned short h) { return __uint_as_float(((unsigned)h) << 16); }
; DI float frcp(float x) { return __builtin_amdgcn_rcpf(x); }
; DI void lru_unit_run(LruUnit& U, const bf16x8 (&wr)[3], const bf16x8 (&wi)[3], LAS unsigned char* xcb, LAS unsigned char* hst, int cb, int lane) {
;     ...
;         for (int t = 0; t < 4; ++t) {
;             const int tb = 4 * half + t;
;             f32x4 ar = {0.f, 0.f, 0.f, 0.f}, ai = {0.f, 0.f, 0.f, 0.f};
; #pragma unroll
;             for (int ks = 0; ks < 3; ++ks) {
;                 const bf16x8 a = *(const LAS bf16x8*)(xcb + (16 * tb + c) * 192 + (32 * ks + 8 * q) * 2);
;                 ar = __builtin_amdgcn_mfma_f32_16x16x32_bf16(a, wr[ks], ar, 0, 0, 0);
;                 ai = __builtin_amdgcn_mfma_f32_16x16x32_bf16(a, wi[ks], ai, 0, 0, 0);
;             }
; #pragma unroll
;             for (int e = 0; e < 4; ++e) {
;                 const int s = 16 * tb + 4 * q + e;
;                 const float xc = bf1(*(const LAS unsigned short*)(xcb + s * 192 + (16 * cb + c) * 2));
;                 const float r = frcp(1.0f + __builtin_amdgcn_exp2f(-(ar[e] + U.ba))), ig = frcp(1.0f + __builtin_amdgcn_exp2f(-(ai[e] + U.bx)));
;                 const float a = __builtin_amdgcn_exp2f(U.kk * r);
;                 av[t][e] = a; bv[t][e] = __builtin_amdgcn_sqrtf(fmaxf(1.0f - a * a, 0.f)) * ig * xc;
;             }
;             Ac[t] = av[t][0] * av[t][1] * av[t][2] * av[t][3];
;             Bc[t] = ((bv[t][0] * av[t][1] + bv[t][1]) * av[t][2] + bv[t][2]) * av[t][3] + bv[t][3];
	v_lshlrev_b32_e32 v143, 16, v143
	v_pk_mul_f32 v[132:133], v[132:133], v[142:143]
	s_waitcnt lgkmcnt(1)
	v_mfma_f32_16x16x32_bf16 v[142:145], v[138:141], v[10:13], 0
	s_or_b32 s1, s1, 48
	v_pk_mul_f32 v[134:135], v[118:119], v[120:121]
	v_pk_fma_f32 v[136:137], v[120:121], v[126:127], v[128:129]
	v_mfma_f32_16x16x32_bf16 v[138:141], v[138:141], v[14:17], 0
	v_mul_f32_e64 v134, v122, v134
	v_mul_f32_e64 v135, v123, v135
	v_pk_fma_f32 v[136:137], v[122:123], v[136:137], v[130:131]
	v_pk_mul_f32 v[134:135], v[124:125], v[134:135]
	s_waitcnt lgkmcnt(0)
	v_mfma_f32_16x16x32_bf16 v[142:145], v[146:149], v[26:29], v[142:145]
	v_fma_f32 v136, v124, v136, v132
	v_fma_f32 v137, v125, v137, v133
	v_mfma_f32_16x16x32_bf16 v[138:141], v[146:149], v[30:33], v[138:141]
	ds_read_b128 v[146:149], v182 offset:42112
	s_waitcnt lgkmcnt(0)
	v_mfma_f32_16x16x32_bf16 v[142:145], v[146:149], v[42:45], v[142:145]
	v_mfma_f32_16x16x32_bf16 v[182:185], v[146:149], v[46:49], v[138:141]
	s_nop 3
	v_or_b32_e32 v138, s2, v204
	v_mad_u32_u24 v139, v138, s93, v208
	ds_read_u16 v227, v139 offset:41984
	ds_read_u16 v240, v139 offset:42176
	ds_read_u16 v241, v139 offset:42368
	ds_read_u16 v242, v139 offset:42560
	v_add_f32_e32 v139, v219, v145
	v_exp_f32_e64 v139, -v139
	v_add_f32_e32 v141, v218, v183
	v_exp_f32_e64 v141, -v141
	v_add_f32_e32 v138, v219, v142
	v_add_f32_e32 v139, 1.0, v139
	v_rcp_f32_e32 v139, v139
	v_add_f32_e32 v141, 1.0, v141
	v_rcp_f32_e32 v148, v141
	v_add_f32_e32 v141, v219, v144
	v_mul_f32_e32 v139, v221, v139
	v_exp_f32_e32 v144, v139
	v_or_b32_e32 v139, s1, v200
	v_mad_u32_u24 v139, v139, s93, v207
	ds_read_b128 v[228:231], v139 offset:41984
	ds_read_b128 v[236:239], v139 offset:42048
	s_waitcnt lgkmcnt(1)
	v_mfma_f32_16x16x32_bf16 v[232:235], v[228:231], v[10:13], 0
	v_exp_f32_e64 v141, -v141
	v_add_f32_e32 v142, v218, v184
	v_exp_f32_e64 v142, -v142
	v_mfma_f32_16x16x32_bf16 v[228:231], v[228:231], v[14:17], 0
	v_add_f32_e32 v141, 1.0, v141
	v_rcp_f32_e32 v141, v141
	v_add_f32_e32 v142, 1.0, v142
	s_waitcnt lgkmcnt(0)
	v_mfma_f32_16x16x32_bf16 v[232:235], v[236:239], v[26:29], v[232:235]
	v_add_f32_e32 v140, v218, v182
	v_mul_f32_e32 v141, v221, v141
	v_rcp_f32_e32 v182, v142
	v_mfma_f32_16x16x32_bf16 v[228:231], v[236:239], v[30:33], v[228:231]
	ds_read_b128 v[236:239], v139 offset:42112
	v_exp_f32_e32 v142, v141
	v_add_f32_e32 v141, v218, v185
	s_waitcnt lgkmcnt(0)
	v_mfma_f32_16x16x32_bf16 v[232:235], v[236:239], v[42:45], v[232:235]
	v_exp_f32_e64 v140, -v140
	v_exp_f32_e64 v141, -v141
	v_exp_f32_e64 v138, -v138
	v_mfma_f32_16x16x32_bf16 v[228:231], v[236:239], v[46:49], v[228:231]
	v_or_b32_e32 v139, s1, v204
	v_mad_u32_u24 v145, v139, s93, v208
	s_nop 1
	v_add_f32_e32 v139, v219, v232
	v_add_f32_e32 v140, 1.0, v140
	v_add_f32_e32 v141, 1.0, v141
	v_exp_f32_e64 v139, -v139
	v_rcp_f32_e32 v146, v140
	v_add_f32_e32 v140, v219, v143
	v_rcp_f32_e32 v184, v141
	v_add_f32_e32 v141, v218, v228
	v_add_f32_e32 v138, 1.0, v138
	v_exp_f32_e64 v140, -v140
	v_exp_f32_e64 v141, -v141
	v_rcp_f32_e32 v138, v138
	v_add_f32_e32 v143, v218, v229
	v_add_f32_e32 v139, 1.0, v139
	v_exp_f32_e64 v143, -v143
	v_rcp_f32_e32 v139, v139
	v_add_f32_e32 v140, 1.0, v140
	v_add_f32_e32 v141, 1.0, v141
	v_mul_f32_e32 v138, v221, v138
	v_rcp_f32_e32 v140, v140
	v_rcp_f32_e32 v147, v141
	v_add_f32_e32 v141, v219, v233
	v_exp_f32_e32 v138, v138
	v_exp_f32_e64 v141, -v141
	v_add_f32_e32 v143, 1.0, v143
	ds_read_u16 v236, v145 offset:41984
	ds_read_u16 v232, v145 offset:42176
	ds_read_u16 v233, v145 offset:42368
	v_mul_f32_e32 v139, v221, v139
	v_rcp_f32_e32 v149, v143
	v_add_f32_e32 v143, v219, v234
	v_exp_f32_e32 v139, v139
	v_exp_f32_e64 v143, -v143
	v_mul_f32_e32 v140, v221, v140
	ds_read_u16 v234, v145 offset:42560
	v_add_f32_e32 v145, v219, v235
	v_exp_f32_e32 v140, v140
	v_add_f32_e32 v141, 1.0, v141
	v_exp_f32_e64 v145, -v145
	v_lshlrev_b32_e32 v228, 16, v227
	v_fma_f32 v227, -v138, v138, 1.0
	v_rcp_f32_e32 v141, v141
	v_max_f32_e32 v227, 0, v227
	v_add_f32_e32 v143, 1.0, v143
	s_waitcnt lgkmcnt(3)
	v_lshlrev_b32_e32 v229, 16, v236
	v_sqrt_f32_e32 v236, v227
	v_fma_f32 v227, -v139, v139, 1.0
	v_rcp_f32_e32 v143, v143
	v_max_f32_e32 v227, 0, v227
	v_add_f32_e32 v145, 1.0, v145
	v_sqrt_f32_e32 v237, v227
	v_fma_f32 v227, -v140, v140, 1.0
	v_mul_f32_e32 v141, v221, v141
	v_rcp_f32_e32 v145, v145
	v_max_f32_e32 v227, 0, v227
	v_exp_f32_e32 v141, v141
	v_sqrt_f32_e32 v238, v227
	v_fma_f32 v227, -v142, v142, 1.0
	v_mul_f32_e32 v143, v221, v143
	v_max_f32_e32 v227, 0, v227
	v_add_f32_e32 v183, v218, v230
	v_exp_f32_e32 v143, v143
	v_lshlrev_b32_e32 v230, 16, v240
	v_sqrt_f32_e32 v240, v227
	v_fma_f32 v227, -v144, v144, 1.0
	v_mul_f32_e32 v145, v221, v145
	v_max_f32_e32 v227, 0, v227
	v_exp_f32_e64 v183, -v183
	v_add_f32_e32 v185, v218, v231
	v_exp_f32_e32 v145, v145
	s_waitcnt lgkmcnt(0)
	v_lshlrev_b32_e32 v235, 16, v234
	v_lshlrev_b32_e32 v234, 16, v242
	v_sqrt_f32_e32 v242, v227
	v_fma_f32 v227, -v141, v141, 1.0
	v_exp_f32_e64 v185, -v185
	v_max_f32_e32 v227, 0, v227
	v_sqrt_f32_e32 v239, v227
	v_fma_f32 v227, -v143, v143, 1.0
	v_max_f32_e32 v227, 0, v227
	v_add_f32_e32 v183, 1.0, v183
	v_lshlrev_b32_e32 v231, 16, v232
	v_lshlrev_b32_e32 v232, 16, v241
	v_sqrt_f32_e32 v241, v227
	v_fma_f32 v227, -v145, v145, 1.0
	v_rcp_f32_e32 v183, v183
	v_add_f32_e32 v185, 1.0, v185
	v_max_f32_e32 v227, 0, v227
	v_rcp_f32_e32 v185, v185
	v_sqrt_f32_e32 v243, v227
	v_lshlrev_b32_e32 v233, 16, v233
	v_pk_mul_f32 v[148:149], v[148:149], v[238:239]
	v_pk_mul_f32 v[182:183], v[182:183], v[240:241]
	v_pk_mul_f32 v[148:149], v[148:149], v[230:231]
	v_pk_mul_f32 v[182:183], v[182:183], v[232:233]
	v_pk_mul_f32 v[184:185], v[184:185], v[242:243]
	ds_bpermute_b32 v227, v223, v134
	ds_bpermute_b32 v230, v223, v136
	v_cndmask_b32_e64 v231, v137, v137, s[16:17]
	v_cndmask_b32_e64 v232, v135, v135, s[16:17]
	v_pk_mul_f32 v[146:147], v[146:147], v[236:237]
	v_pk_mul_f32 v[184:185], v[184:185], v[234:235]
	ds_bpermute_b32 v233, v223, v232
	ds_bpermute_b32 v234, v223, v231
	v_pk_mul_f32 v[146:147], v[146:147], v[228:229]
	v_pk_mul_f32 v[244:245], v[138:139], v[140:141]
	v_pk_fma_f32 v[228:229], v[140:141], v[146:147], v[148:149]
	v_pk_mul_f32 v[244:245], v[142:143], v[244:245]
	v_pk_fma_f32 v[228:229], v[142:143], v[228:229], v[182:183]
	v_pk_mul_f32 v[244:245], v[144:145], v[244:245]
	v_pk_fma_f32 v[228:229], v[144:145], v[228:229], v[184:185]
	s_waitcnt lgkmcnt(2)
; #define LAS __attribute__((address_space(3)))
; DI unsigned pk2(float lo, float hi) { f32x2_t v = {lo, hi}; bf16x2_t b = __builtin_convertvector(v, bf16x2_t); return __builtin_bit_cast(unsigned, b); }
; DI void lru_unit_run(LruUnit& U, const bf16x8 (&wr)[3], const bf16x8 (&wi)[3], LAS unsigned char* xcb, LAS unsigned char* hst, int cb, int lane) {
;     ...
; #pragma unroll
;         for (int t = 0; t < 4; ++t) { const float A1 = __shfl_up(Ac[t], 16), B1 = __shfl_up(Bc[t], 16); if (q >= 1) { Bc[t] = Ac[t] * B1 + Bc[t]; Ac[t] = A1 * Ac[t]; } }
; #pragma unroll
;         for (int t = 0; t < 4; ++t) { const float A2 = __shfl_up(Ac[t], 32), B2 = __shfl_up(Bc[t], 32); if (q >= 2) { Bc[t] = Ac[t] * B2 + Bc[t]; Ac[t] = A2 * Ac[t]; } }
;         float At[4], Bt[4], Ae[4], Be[4];
; #pragma unroll
;         for (int t = 0; t < 4; ++t) { At[t] = __shfl(Ac[t], 48 + c); Bt[t] = __shfl(Bc[t], 48 + c); Ae[t] = __shfl_up(Ac[t], 16); Be[t] = __shfl_up(Bc[t], 16); }
; #pragma unroll
;         for (int t = 0; t < 4; ++t) {
;             const int tb = 4 * half + t;
;             float h = (q == 0) ? hc : (Ae[t] * hc + Be[t]);
; #pragma unroll
;             for (int e = 0; e < 4; ++e) { h = av[t][e] * h + bv[t][e]; *(LAS unsigned short*)(hst + (16 * tb + 4 * q + e) * 160 + (16 * cb + c) * 2) = (unsigned short)pk2(h, 0.f); }
;             hc = At[t] * hc + Bt[t];
;         }
	v_fma_f32 v230, v134, v230, v136
	v_mul_f32_e32 v227, v134, v227
	s_waitcnt lgkmcnt(0)
	v_fmac_f32_e32 v231, v232, v234
	v_mul_f32_e32 v232, v232, v233
	v_cndmask_b32_e64 v233, v228, v228, s[16:17]
	v_cndmask_b32_e64 v234, v244, v244, s[16:17]
	v_cndmask_b32_e64 v136, v230, v136, s[16:17]
	v_cndmask_b32_e64 v134, v227, v134, s[16:17]
	ds_bpermute_b32 v235, v223, v234
	ds_bpermute_b32 v236, v223, v233
	v_cndmask_b32_e64 v135, v232, v135, s[16:17]
	ds_bpermute_b32 v227, v224, v134
	ds_bpermute_b32 v232, v224, v136
	v_cndmask_b32_e64 v137, v231, v137, s[16:17]
	s_waitcnt lgkmcnt(2)
	v_fmac_f32_e32 v233, v234, v236
	v_mul_f32_e32 v234, v234, v235
	v_cndmask_b32_e64 v235, v229, v229, s[16:17]
	v_cndmask_b32_e64 v236, v245, v245, s[16:17]
	s_waitcnt lgkmcnt(0)
	v_fma_f32 v232, v134, v232, v136
	v_mul_f32_e32 v227, v134, v227
	ds_bpermute_b32 v237, v223, v236
	ds_bpermute_b32 v238, v223, v235
	v_cndmask_b32_e64 v228, v233, v228, s[16:17]
	v_cndmask_b32_e64 v231, v234, v244, s[16:17]
	ds_bpermute_b32 v233, v224, v135
	ds_bpermute_b32 v234, v224, v137
	v_cndmask_b32_e64 v136, v136, v232, s[18:19]
	v_cndmask_b32_e64 v134, v134, v227, s[18:19]
	ds_bpermute_b32 v227, v225, v134
	ds_bpermute_b32 v232, v225, v136
	ds_bpermute_b32 v134, v223, v134
	ds_bpermute_b32 v136, v223, v136
	s_waitcnt lgkmcnt(6)
	v_fmac_f32_e32 v235, v236, v238
	v_mul_f32_e32 v236, v236, v237
	s_waitcnt lgkmcnt(4)
	v_fma_f32 v234, v135, v234, v137
	v_mul_f32_e32 v233, v135, v233
	v_cndmask_b32_e64 v229, v235, v229, s[16:17]
	v_cndmask_b32_e64 v230, v236, v245, s[16:17]
	ds_bpermute_b32 v235, v224, v231
	ds_bpermute_b32 v236, v224, v228
	v_cndmask_b32_e64 v137, v137, v234, s[18:19]
	v_cndmask_b32_e64 v135, v135, v233, s[18:19]
	s_waitcnt lgkmcnt(2)
	v_fmac_f32_e32 v136, v222, v134
	ds_bpermute_b32 v233, v225, v135
	ds_bpermute_b32 v234, v225, v137
	ds_bpermute_b32 v135, v223, v135
	ds_bpermute_b32 v137, v223, v137
	v_cndmask_b32_e64 v134, v136, v222, s[16:17]
	v_fma_f32 v118, v118, v134, v126
	v_cvt_pk_bf16_f32 v126, v118, s0
	v_fma_f32 v118, v120, v118, v128
	v_mad_u32_u24 v134, v226, s57, v209
	v_cvt_pk_bf16_f32 v120, v118, s0
	v_fma_f32 v118, v122, v118, v130
	s_waitcnt lgkmcnt(4)
	v_fma_f32 v236, v231, v236, v228
	v_mul_f32_e32 v235, v231, v235
	ds_write_b16 v134, v120 offset:160
	v_cvt_pk_bf16_f32 v120, v118, s0
	v_fma_f32 v118, v124, v118, v132
	v_fmac_f32_e32 v232, v222, v227
	ds_bpermute_b32 v237, v224, v230
	ds_bpermute_b32 v238, v224, v229
	v_cndmask_b32_e64 v228, v228, v236, s[18:19]
	v_cndmask_b32_e64 v231, v231, v235, s[18:19]
	v_cvt_pk_bf16_f32 v118, v118, s0
	s_waitcnt lgkmcnt(3)
	v_fmac_f32_e32 v137, v232, v135
	ds_bpermute_b32 v235, v225, v231
	ds_bpermute_b32 v236, v225, v228
	ds_bpermute_b32 v231, v223, v231
	ds_bpermute_b32 v228, v223, v228
	ds_write_b16 v134, v118 offset:480
	v_cndmask_b32_e64 v118, v137, v232, s[16:17]
	v_fmac_f32_e32 v127, v119, v118
	v_cvt_pk_bf16_f32 v118, v127, s0
	v_fmac_f32_e32 v129, v121, v127
	ds_write_b16 v134, v118 offset:2560
	v_cvt_pk_bf16_f32 v118, v129, s0
	v_fmac_f32_e32 v131, v123, v129
	s_waitcnt lgkmcnt(6)
	v_fma_f32 v238, v230, v238, v229
	v_mul_f32_e32 v237, v230, v237
	ds_write_b16 v134, v118 offset:2720
	v_cvt_pk_bf16_f32 v118, v131, s0
	v_fmac_f32_e32 v133, v125, v131
	v_fmac_f32_e32 v234, v232, v233
	v_cndmask_b32_e64 v229, v229, v238, s[18:19]
	v_cndmask_b32_e64 v230, v230, v237, s[18:19]
	ds_write_b16 v134, v118 offset:2880
	v_cvt_pk_bf16_f32 v118, v133, s0
	s_waitcnt lgkmcnt(4)
	v_fmac_f32_e32 v228, v234, v231
	ds_bpermute_b32 v237, v225, v230
	ds_bpermute_b32 v238, v225, v229
	ds_bpermute_b32 v230, v223, v230
	ds_bpermute_b32 v229, v223, v229
	ds_write_b16 v134, v118 offset:3040
	v_cndmask_b32_e64 v118, v228, v234, s[16:17]
	v_fma_f32 v118, v138, v118, v146
	v_cvt_pk_bf16_f32 v119, v118, s0
	v_fma_f32 v118, v140, v118, v148
	ds_write_b16 v134, v119 offset:5120
	v_cvt_pk_bf16_f32 v119, v118, s0
	v_fma_f32 v118, v142, v118, v182
	ds_write_b16 v134, v119 offset:5280
	v_cvt_pk_bf16_f32 v119, v118, s0
	v_fma_f32 v118, v144, v118, v184
	v_fmac_f32_e32 v236, v234, v235
	v_cvt_pk_bf16_f32 v118, v118, s0
	s_waitcnt lgkmcnt(3)
	v_fmac_f32_e32 v229, v236, v230
	ds_write_b16 v134, v118 offset:5600
	v_cndmask_b32_e64 v118, v229, v236, s[16:17]
	v_fmac_f32_e32 v147, v139, v118
	v_cvt_pk_bf16_f32 v118, v147, s0
	v_fmac_f32_e32 v149, v141, v147
	ds_write_b16 v134, v118 offset:7680
	v_cvt_pk_bf16_f32 v118, v149, s0
	v_fmac_f32_e32 v183, v143, v149
	ds_write_b16 v134, v118 offset:7840
	v_cvt_pk_bf16_f32 v118, v183, s0
	v_fmac_f32_e32 v185, v145, v183
	v_mov_b32_e32 v222, v238
	ds_write_b16 v134, v118 offset:8000
	v_cvt_pk_bf16_f32 v118, v185, s0
	v_fmac_f32_e32 v222, v236, v237
	s_mov_b32 s1, 64
	ds_write_b16 v134, v126
	ds_write_b16 v134, v120 offset:320
	ds_write_b16 v134, v119 offset:5440
	ds_write_b16 v134, v118 offset:8160
	s_cbranch_vccnz .LBB0_582

; __device__ __forceinline__ unsigned cvt_pk_bf16(float lo, float hi) { unsigned r; asm volatile("v_cvt_pk_bf16_f32 %0, %1, %2" : "=v"(r) : "v"(lo), "v"(hi)); return r; }
; __device__ __forceinline__ float bf_lo(unsigned w) { return __uint_as_float(w << 16); }
; __device__ __forceinline__ float bf_hi(unsigned w) { return __uint_as_float(w & 0xffff0000u); }
;     __device__ __forceinline__ void operator()(const f32x4 (&acc)[2][2][4][2], const Unit& u, int wr, int wc, int fr, int fq) const {
;         const int row0 = u.pm * BM + wr * 64 + fr, col0 = u.pn * BM + wc * 32 + 8 * fq;
; #pragma unroll
;         for (int ai = 0; ai < 2; ++ai)
; #pragma unroll
;             for (int m = 0; m < 4; ++m) { const size_t row = (size_t)(row0 + ai * HALF + m * 16);
; #pragma unroll
;                 for (int bj = 0; bj < 2; ++bj) { const f32x4 v0 = acc[ai][bj][m][0], v1 = acc[ai][bj][m][1];
;                     const u32x2 g = *(const u32x2*)(G + row * ldg + col0 + bj * HALF);
;                     float o[8]; const float k255 = 1.0f / 255.0f;
;                     o[0] = v0[0] * ((float)(g.x & 0xffu) * k255); o[1] = v0[1] * ((float)((g.x >> 8) & 0xffu) * k255); o[2] = v0[2] * ((float)((g.x >> 16) & 0xffu) * k255); o[3] = v0[3] * ((float)(g.x >> 24) * k255);
;                     o[4] = v1[0] * ((float)(g.y & 0xffu) * k255); o[5] = v1[1] * ((float)((g.y >> 8) & 0xffu) * k255); o[6] = v1[2] * ((float)((g.y >> 16) & 0xffu) * k255); o[7] = v1[3] * ((float)(g.y >> 24) * k255);
;                     bf16_t* dst = MG + row * 1024 + col0 + bj * HALF;
;                     if (SECOND) { const u32x4 p = *(const u32x4*)dst;
;                         o[0] += bf_lo(p.x); o[1] += bf_hi(p.x); o[2] += bf_lo(p.y); o[3] += bf_hi(p.y); o[4] += bf_lo(p.z); o[5] += bf_hi(p.z); o[6] += bf_lo(p.w); o[7] += bf_hi(p.w); }
;                     u32x4 w; w.x = cvt_pk_bf16(o[0], o[1]); w.y = cvt_pk_bf16(o[2], o[3]); w.z = cvt_pk_bf16(o[4], o[5]); w.w = cvt_pk_bf16(o[6], o[7]);
;                     *(u32x4*)dst = w; } }
.LBB0_687:
	v_lshl_add_u32 v150, s40, 8, v1
	v_ashrrev_i32_e32 v151, 31, v150
	v_lshl_or_b32 v146, s23, 8, v153
	v_lshlrev_b64 v[148:149], 11, v[150:151]
	v_ashrrev_i32_e32 v147, 31, v146
	v_lshl_add_u64 v[156:157], s[14:15], 0, v[148:149]
	v_lshl_add_u64 v[156:157], v[156:157], 0, v[146:147]
	s_mov_b32 s77, 0
	v_mov_b32_e32 v252, v156
	v_mov_b32_e32 v253, v157
	global_load_dwordx2 v[200:201], v[252:253], off
	global_load_dwordx2 v[202:203], v[252:253], off offset:128
	s_mov_b32 s76, 0x8000
	v_lshl_add_u64 v[250:251], v[252:253], 0, s[76:77]
	global_load_dwordx2 v[204:205], v[250:251], off
	global_load_dwordx2 v[206:207], v[250:251], off offset:128
	s_mov_b32 s76, 0x10000
	v_lshl_add_u64 v[250:251], v[252:253], 0, s[76:77]
	global_load_dwordx2 v[208:209], v[250:251], off
	global_load_dwordx2 v[210:211], v[250:251], off offset:128
	s_mov_b32 s76, 0x18000
	v_lshl_add_u64 v[250:251], v[252:253], 0, s[76:77]
	global_load_dwordx2 v[212:213], v[250:251], off
	global_load_dwordx2 v[214:215], v[250:251], off offset:128
	s_mov_b32 s76, 0x40000
	v_lshl_add_u64 v[250:251], v[252:253], 0, s[76:77]
	global_load_dwordx2 v[216:217], v[250:251], off
	global_load_dwordx2 v[218:219], v[250:251], off offset:128
	s_mov_b32 s76, 0x48000
	v_lshl_add_u64 v[250:251], v[252:253], 0, s[76:77]
	global_load_dwordx2 v[220:221], v[250:251], off
	global_load_dwordx2 v[222:223], v[250:251], off offset:128
	s_mov_b64 s[20:21], 0x48000
	s_and_b64 vcc, exec, s[4:5]
	s_waitcnt vmcnt(11)
	s_nop 1
	v_mov_b32_e32 v158, v200
	v_mov_b32_e32 v159, v201
	v_cvt_f32_ubyte0_e32 v151, v158
	v_mul_f32_e32 v151, 0x3b808081, v151
	v_mul_f32_e32 v130, v130, v151
	v_cvt_f32_ubyte1_e32 v151, v158
	v_mul_f32_e32 v151, 0x3b808081, v151
	v_mul_f32_e32 v131, v131, v151
	v_cvt_f32_ubyte2_e32 v151, v158
	v_mul_f32_e32 v151, 0x3b808081, v151
	v_mul_f32_e32 v151, v132, v151
	v_cvt_f32_ubyte3_e32 v132, v158
	v_mul_f32_e32 v132, 0x3b808081, v132
	v_mul_f32_e32 v155, v133, v132
	v_cvt_f32_ubyte0_e32 v132, v159
	v_mul_f32_e32 v132, 0x3b808081, v132
	v_mul_f32_e32 v158, v126, v132
	v_cvt_f32_ubyte1_e32 v126, v159
	v_mul_f32_e32 v126, 0x3b808081, v126
	v_mul_f32_e32 v160, v127, v126
	v_cvt_f32_ubyte2_e32 v126, v159
	v_mul_f32_e32 v126, 0x3b808081, v126
	v_mul_f32_e32 v161, v128, v126
	v_cvt_f32_ubyte3_e32 v126, v159
	v_mul_f32_e32 v126, 0x3b808081, v126
	v_mul_f32_e32 v159, v129, v126
	v_lshl_add_u64 v[128:129], s[12:13], 0, v[148:149]
	v_lshlrev_b64 v[126:127], 1, v[146:147]
	v_lshl_add_u64 v[132:133], v[128:129], 0, v[126:127]
	v_cvt_pk_bf16_f32 v128, v130, v131
	v_cvt_pk_bf16_f32 v129, v151, v155
	v_cvt_pk_bf16_f32 v130, v158, v160
	v_cvt_pk_bf16_f32 v131, v161, v159
	global_store_dwordx4 v[132:133], v[128:131], off
	s_waitcnt vmcnt(11)
	s_nop 1
	v_mov_b32_e32 v128, v202
	v_mov_b32_e32 v129, v203
	s_mov_b32 s76, 0x50000
	v_lshl_add_u64 v[250:251], v[252:253], 0, s[76:77]
	global_load_dwordx2 v[200:201], v[250:251], off
	global_load_dwordx2 v[202:203], v[250:251], off offset:128
	v_cvt_f32_ubyte0_e32 v130, v128
	v_mul_f32_e32 v130, 0x3b808081, v130
	v_mul_f32_e32 v122, v122, v130
	v_cvt_f32_ubyte1_e32 v130, v128
	v_mul_f32_e32 v130, 0x3b808081, v130
	v_mul_f32_e32 v123, v123, v130
	v_cvt_f32_ubyte2_e32 v130, v128
	v_cvt_f32_ubyte3_e32 v128, v128
	v_mul_f32_e32 v128, 0x3b808081, v128
	v_mul_f32_e32 v125, v125, v128
	v_cvt_f32_ubyte0_e32 v128, v129
	v_mul_f32_e32 v128, 0x3b808081, v128
	v_mul_f32_e32 v128, v118, v128
	v_cvt_f32_ubyte1_e32 v118, v129
	v_mul_f32_e32 v130, 0x3b808081, v130
	v_mul_f32_e32 v118, 0x3b808081, v118
	v_mul_f32_e32 v124, v124, v130
	v_mul_f32_e32 v130, v119, v118
	v_cvt_f32_ubyte2_e32 v118, v129
	v_mul_f32_e32 v118, 0x3b808081, v118
	v_mul_f32_e32 v131, v120, v118
	v_cvt_f32_ubyte3_e32 v118, v129
	v_mul_f32_e32 v118, 0x3b808081, v118
	v_mul_f32_e32 v121, v121, v118
	v_cvt_pk_bf16_f32 v118, v122, v123
	v_cvt_pk_bf16_f32 v119, v124, v125
	v_cvt_pk_bf16_f32 v120, v128, v130
	v_cvt_pk_bf16_f32 v121, v131, v121
	global_store_dwordx4 v[132:133], v[118:121], off offset:256
	s_nop 1
	v_or_b32_e32 v118, 16, v150
	v_ashrrev_i32_e32 v119, 31, v118
	v_lshlrev_b64 v[120:121], 11, v[118:119]
	v_lshl_add_u64 v[118:119], s[14:15], 0, v[120:121]
	v_lshl_add_u64 v[118:119], v[118:119], 0, v[146:147]
	s_waitcnt vmcnt(13)
	s_nop 1
	v_mov_b32_e32 v122, v204
	v_mov_b32_e32 v123, v205
	v_cvt_f32_ubyte0_e32 v124, v122
	v_mul_f32_e32 v124, 0x3b808081, v124
	v_mul_f32_e32 v124, v114, v124
	v_cvt_f32_ubyte1_e32 v114, v122
	v_mul_f32_e32 v114, 0x3b808081, v114
	v_mul_f32_e32 v125, v115, v114
	v_cvt_f32_ubyte2_e32 v114, v122
	v_mul_f32_e32 v114, 0x3b808081, v114
	v_mul_f32_e32 v116, v116, v114
	v_cvt_f32_ubyte3_e32 v114, v122
	v_mul_f32_e32 v114, 0x3b808081, v114
	v_mul_f32_e32 v117, v117, v114
	v_cvt_f32_ubyte0_e32 v114, v123
	v_mul_f32_e32 v114, 0x3b808081, v114
	v_mul_f32_e32 v122, v110, v114
	v_cvt_f32_ubyte1_e32 v110, v123
	v_mul_f32_e32 v110, 0x3b808081, v110
	v_mul_f32_e32 v128, v111, v110
	v_cvt_f32_ubyte2_e32 v110, v123
	v_mul_f32_e32 v110, 0x3b808081, v110
	v_mul_f32_e32 v129, v112, v110
	v_cvt_f32_ubyte3_e32 v110, v123
	v_mul_f32_e32 v110, 0x3b808081, v110
	v_mul_f32_e32 v113, v113, v110
	v_lshl_add_u64 v[110:111], s[12:13], 0, v[120:121]
	v_lshl_add_u64 v[114:115], v[110:111], 0, v[126:127]
	v_cvt_pk_bf16_f32 v110, v124, v125
	v_cvt_pk_bf16_f32 v111, v116, v117
	v_cvt_pk_bf16_f32 v112, v122, v128
	v_cvt_pk_bf16_f32 v113, v129, v113
	global_store_dwordx4 v[114:115], v[110:113], off
	s_waitcnt vmcnt(13)
; __device__ __forceinline__ unsigned cvt_pk_bf16(float lo, float hi) { unsigned r; asm volatile("v_cvt_pk_bf16_f32 %0, %1, %2" : "=v"(r) : "v"(lo), "v"(hi)); return r; }
; __device__ __forceinline__ float bf_lo(unsigned w) { return __uint_as_float(w << 16); }
; __device__ __forceinline__ float bf_hi(unsigned w) { return __uint_as_float(w & 0xffff0000u); }
;     __device__ __forceinline__ void operator()(const f32x4 (&acc)[2][2][4][2], const Unit& u, int wr, int wc, int fr, int fq) const {
;     ...
;             for (int m = 0; m < 4; ++m) { const size_t row = (size_t)(row0 + ai * HALF + m * 16);
; #pragma unroll
;                 for (int bj = 0; bj < 2; ++bj) { const f32x4 v0 = acc[ai][bj][m][0], v1 = acc[ai][bj][m][1];
;                     const u32x2 g = *(const u32x2*)(G + row * ldg + col0 + bj * HALF);
;                     float o[8]; const float k255 = 1.0f / 255.0f;
;                     o[0] = v0[0] * ((float)(g.x & 0xffu) * k255); o[1] = v0[1] * ((float)((g.x >> 8) & 0xffu) * k255); o[2] = v0[2] * ((float)((g.x >> 16) & 0xffu) * k255); o[3] = v0[3] * ((float)(g.x >> 24) * k255);
;                     o[4] = v1[0] * ((float)(g.y & 0xffu) * k255); o[5] = v1[1] * ((float)((g.y >> 8) & 0xffu) * k255); o[6] = v1[2] * ((float)((g.y >> 16) & 0xffu) * k255); o[7] = v1[3] * ((float)(g.y >> 24) * k255);
;                     bf16_t* dst = MG + row * 1024 + col0 + bj * HALF;
;                     if (SECOND) { const u32x4 p = *(const u32x4*)dst;
;                         o[0] += bf_lo(p.x); o[1] += bf_hi(p.x); o[2] += bf_lo(p.y); o[3] += bf_hi(p.y); o[4] += bf_lo(p.z); o[5] += bf_hi(p.z); o[6] += bf_lo(p.w); o[7] += bf_hi(p.w); }
;                     u32x4 w; w.x = cvt_pk_bf16(o[0], o[1]); w.y = cvt_pk_bf16(o[2], o[3]); w.z = cvt_pk_bf16(o[4], o[5]); w.w = cvt_pk_bf16(o[6], o[7]);
;                     *(u32x4*)dst = w; } }
	s_nop 1
	v_mov_b32_e32 v110, v206
	v_mov_b32_e32 v111, v207
	s_mov_b32 s76, 0x58000
	v_lshl_add_u64 v[250:251], v[252:253], 0, s[76:77]
	global_load_dwordx2 v[204:205], v[250:251], off
	global_load_dwordx2 v[206:207], v[250:251], off offset:128
	v_cvt_f32_ubyte0_e32 v112, v110
	v_mul_f32_e32 v112, 0x3b808081, v112
	v_mul_f32_e32 v106, v106, v112
	v_cvt_f32_ubyte1_e32 v112, v110
	v_mul_f32_e32 v112, 0x3b808081, v112
	v_mul_f32_e32 v107, v107, v112
	v_cvt_f32_ubyte2_e32 v112, v110
	v_cvt_f32_ubyte3_e32 v110, v110
	v_mul_f32_e32 v110, 0x3b808081, v110
	v_mul_f32_e32 v109, v109, v110
	v_cvt_f32_ubyte0_e32 v110, v111
	v_mul_f32_e32 v110, 0x3b808081, v110
	v_mul_f32_e32 v110, v102, v110
	v_cvt_f32_ubyte1_e32 v102, v111
	v_mul_f32_e32 v112, 0x3b808081, v112
	v_mul_f32_e32 v102, 0x3b808081, v102
	v_mul_f32_e32 v108, v108, v112
	v_mul_f32_e32 v112, v103, v102
	v_cvt_f32_ubyte2_e32 v102, v111
	v_mul_f32_e32 v102, 0x3b808081, v102
	v_mul_f32_e32 v113, v104, v102
	v_cvt_f32_ubyte3_e32 v102, v111
	v_mul_f32_e32 v102, 0x3b808081, v102
	v_mul_f32_e32 v105, v105, v102
	v_cvt_pk_bf16_f32 v102, v106, v107
	v_cvt_pk_bf16_f32 v103, v108, v109
	v_cvt_pk_bf16_f32 v104, v110, v112
	v_cvt_pk_bf16_f32 v105, v113, v105
	global_store_dwordx4 v[114:115], v[102:105], off offset:256
	s_nop 1
	v_or_b32_e32 v102, 32, v150
	v_ashrrev_i32_e32 v103, 31, v102
	v_lshlrev_b64 v[104:105], 11, v[102:103]
	v_lshl_add_u64 v[102:103], s[14:15], 0, v[104:105]
	v_lshl_add_u64 v[102:103], v[102:103], 0, v[146:147]
	s_waitcnt vmcnt(15)
	s_nop 1
	v_mov_b32_e32 v106, v208
	v_mov_b32_e32 v107, v209
	v_cvt_f32_ubyte0_e32 v108, v106
	v_mul_f32_e32 v108, 0x3b808081, v108
	v_mul_f32_e32 v108, v98, v108
	v_cvt_f32_ubyte1_e32 v98, v106
	v_mul_f32_e32 v98, 0x3b808081, v98
	v_mul_f32_e32 v109, v99, v98
	v_cvt_f32_ubyte2_e32 v98, v106
	v_mul_f32_e32 v98, 0x3b808081, v98
	v_mul_f32_e32 v100, v100, v98
	v_cvt_f32_ubyte3_e32 v98, v106
	v_mul_f32_e32 v98, 0x3b808081, v98
	v_mul_f32_e32 v101, v101, v98
	v_cvt_f32_ubyte0_e32 v98, v107
	v_mul_f32_e32 v98, 0x3b808081, v98
	v_mul_f32_e32 v106, v94, v98
	v_cvt_f32_ubyte1_e32 v94, v107
	v_mul_f32_e32 v94, 0x3b808081, v94
	v_mul_f32_e32 v110, v95, v94
	v_cvt_f32_ubyte2_e32 v94, v107
	v_mul_f32_e32 v94, 0x3b808081, v94
	v_mul_f32_e32 v111, v96, v94
	v_cvt_f32_ubyte3_e32 v94, v107
	v_mul_f32_e32 v94, 0x3b808081, v94
	v_mul_f32_e32 v97, v97, v94
	v_lshl_add_u64 v[94:95], s[12:13], 0, v[104:105]
	v_lshl_add_u64 v[98:99], v[94:95], 0, v[126:127]
	v_cvt_pk_bf16_f32 v94, v108, v109
	v_cvt_pk_bf16_f32 v95, v100, v101
	v_cvt_pk_bf16_f32 v96, v106, v110
	v_cvt_pk_bf16_f32 v97, v111, v97
	global_store_dwordx4 v[98:99], v[94:97], off
	s_waitcnt vmcnt(15)
	s_nop 1
	v_mov_b32_e32 v94, v210
	v_mov_b32_e32 v95, v211
	v_cvt_f32_ubyte0_e32 v96, v94
	v_mul_f32_e32 v96, 0x3b808081, v96
	v_mul_f32_e32 v90, v90, v96
	v_cvt_f32_ubyte1_e32 v96, v94
	v_mul_f32_e32 v96, 0x3b808081, v96
	v_mul_f32_e32 v91, v91, v96
	v_cvt_f32_ubyte2_e32 v96, v94
	v_cvt_f32_ubyte3_e32 v94, v94
	v_mul_f32_e32 v94, 0x3b808081, v94
	v_mul_f32_e32 v93, v93, v94
	v_cvt_f32_ubyte0_e32 v94, v95
	v_mul_f32_e32 v94, 0x3b808081, v94
	v_mul_f32_e32 v94, v86, v94
	v_cvt_f32_ubyte1_e32 v86, v95
	v_mul_f32_e32 v96, 0x3b808081, v96
	v_mul_f32_e32 v86, 0x3b808081, v86
	v_mul_f32_e32 v92, v92, v96
	v_mul_f32_e32 v96, v87, v86
	v_cvt_f32_ubyte2_e32 v86, v95
	v_mul_f32_e32 v86, 0x3b808081, v86
	v_mul_f32_e32 v97, v88, v86
	v_cvt_f32_ubyte3_e32 v86, v95
	v_mul_f32_e32 v86, 0x3b808081, v86
	v_mul_f32_e32 v89, v89, v86
	v_cvt_pk_bf16_f32 v86, v90, v91
	v_cvt_pk_bf16_f32 v87, v92, v93
	v_cvt_pk_bf16_f32 v88, v94, v96
	v_cvt_pk_bf16_f32 v89, v97, v89
	global_store_dwordx4 v[98:99], v[86:89], off offset:256
	s_nop 1
	v_or_b32_e32 v86, 48, v150
	v_ashrrev_i32_e32 v87, 31, v86
	v_lshlrev_b64 v[88:89], 11, v[86:87]
	v_lshl_add_u64 v[86:87], s[14:15], 0, v[88:89]
	v_lshl_add_u64 v[86:87], v[86:87], 0, v[146:147]
	s_waitcnt vmcnt(15)
	s_nop 1
	v_mov_b32_e32 v90, v212
	v_mov_b32_e32 v91, v213
	v_cvt_f32_ubyte0_e32 v92, v90
	v_mul_f32_e32 v92, 0x3b808081, v92
	v_mul_f32_e32 v92, v78, v92
	v_cvt_f32_ubyte1_e32 v78, v90
	v_mul_f32_e32 v78, 0x3b808081, v78
	v_mul_f32_e32 v93, v79, v78
	v_cvt_f32_ubyte2_e32 v78, v90
	v_mul_f32_e32 v78, 0x3b808081, v78
	v_mul_f32_e32 v80, v80, v78
	v_cvt_f32_ubyte3_e32 v78, v90
	v_mul_f32_e32 v78, 0x3b808081, v78
	v_mul_f32_e32 v81, v81, v78
	v_cvt_f32_ubyte0_e32 v78, v91
	v_mul_f32_e32 v78, 0x3b808081, v78
	v_mul_f32_e32 v90, v74, v78
	v_cvt_f32_ubyte1_e32 v74, v91
	v_mul_f32_e32 v74, 0x3b808081, v74
	v_mul_f32_e32 v94, v75, v74
	v_cvt_f32_ubyte2_e32 v74, v91
	v_mul_f32_e32 v74, 0x3b808081, v74
	v_mul_f32_e32 v95, v76, v74
	v_cvt_f32_ubyte3_e32 v74, v91
	v_mul_f32_e32 v74, 0x3b808081, v74
	v_mul_f32_e32 v77, v77, v74
	v_lshl_add_u64 v[74:75], s[12:13], 0, v[88:89]
	v_lshl_add_u64 v[78:79], v[74:75], 0, v[126:127]
	v_cvt_pk_bf16_f32 v74, v92, v93
	v_cvt_pk_bf16_f32 v75, v80, v81
	v_cvt_pk_bf16_f32 v76, v90, v94
	v_cvt_pk_bf16_f32 v77, v95, v77
	global_store_dwordx4 v[78:79], v[74:77], off
	s_waitcnt vmcnt(15)
	s_nop 1
	v_mov_b32_e32 v74, v214
	v_mov_b32_e32 v75, v215
	v_cvt_f32_ubyte0_e32 v76, v74
	v_mul_f32_e32 v76, 0x3b808081, v76
	v_mul_f32_e32 v70, v70, v76
	v_cvt_f32_ubyte1_e32 v76, v74
	v_mul_f32_e32 v76, 0x3b808081, v76
	v_mul_f32_e32 v71, v71, v76
	v_cvt_f32_ubyte2_e32 v76, v74
	v_cvt_f32_ubyte3_e32 v74, v74
	v_mul_f32_e32 v74, 0x3b808081, v74
	v_mul_f32_e32 v73, v73, v74
	v_cvt_f32_ubyte0_e32 v74, v75
	v_mul_f32_e32 v74, 0x3b808081, v74
	v_mul_f32_e32 v74, v66, v74
	v_cvt_f32_ubyte1_e32 v66, v75
	v_mul_f32_e32 v76, 0x3b808081, v76
	v_mul_f32_e32 v66, 0x3b808081, v66
	v_mul_f32_e32 v72, v72, v76
	v_mul_f32_e32 v76, v67, v66
	v_cvt_f32_ubyte2_e32 v66, v75
	v_mul_f32_e32 v66, 0x3b808081, v66
	v_mul_f32_e32 v77, v68, v66
	v_cvt_f32_ubyte3_e32 v66, v75
	v_mul_f32_e32 v66, 0x3b808081, v66
	v_mul_f32_e32 v69, v69, v66
	v_cvt_pk_bf16_f32 v66, v70, v71
	v_cvt_pk_bf16_f32 v67, v72, v73
	v_cvt_pk_bf16_f32 v68, v74, v76
	v_cvt_pk_bf16_f32 v69, v77, v69
	global_store_dwordx4 v[78:79], v[66:69], off offset:256
	s_nop 1
	v_lshl_add_u64 v[68:69], v[148:149], 0, s[68:69]
	v_lshl_add_u64 v[66:67], s[14:15], 0, v[68:69]
	v_lshl_add_u64 v[66:67], v[66:67], 0, v[146:147]
	s_waitcnt vmcnt(15)
; __device__ __forceinline__ unsigned cvt_pk_bf16(float lo, float hi) { unsigned r; asm volatile("v_cvt_pk_bf16_f32 %0, %1, %2" : "=v"(r) : "v"(lo), "v"(hi)); return r; }
; __device__ __forceinline__ float bf_lo(unsigned w) { return __uint_as_float(w << 16); }
; __device__ __forceinline__ float bf_hi(unsigned w) { return __uint_as_float(w & 0xffff0000u); }
;     __device__ __forceinline__ void operator()(const f32x4 (&acc)[2][2][4][2], const Unit& u, int wr, int wc, int fr, int fq) const {
;     ...
;             for (int m = 0; m < 4; ++m) { const size_t row = (size_t)(row0 + ai * HALF + m * 16);
; #pragma unroll
;                 for (int bj = 0; bj < 2; ++bj) { const f32x4 v0 = acc[ai][bj][m][0], v1 = acc[ai][bj][m][1];
;                     const u32x2 g = *(const u32x2*)(G + row * ldg + col0 + bj * HALF);
;                     float o[8]; const float k255 = 1.0f / 255.0f;
;                     o[0] = v0[0] * ((float)(g.x & 0xffu) * k255); o[1] = v0[1] * ((float)((g.x >> 8) & 0xffu) * k255); o[2] = v0[2] * ((float)((g.x >> 16) & 0xffu) * k255); o[3] = v0[3] * ((float)(g.x >> 24) * k255);
;                     o[4] = v1[0] * ((float)(g.y & 0xffu) * k255); o[5] = v1[1] * ((float)((g.y >> 8) & 0xffu) * k255); o[6] = v1[2] * ((float)((g.y >> 16) & 0xffu) * k255); o[7] = v1[3] * ((float)(g.y >> 24) * k255);
;                     bf16_t* dst = MG + row * 1024 + col0 + bj * HALF;
;                     if (SECOND) { const u32x4 p = *(const u32x4*)dst;
;                         o[0] += bf_lo(p.x); o[1] += bf_hi(p.x); o[2] += bf_lo(p.y); o[3] += bf_hi(p.y); o[4] += bf_lo(p.z); o[5] += bf_hi(p.z); o[6] += bf_lo(p.w); o[7] += bf_hi(p.w); }
;                     u32x4 w; w.x = cvt_pk_bf16(o[0], o[1]); w.y = cvt_pk_bf16(o[2], o[3]); w.z = cvt_pk_bf16(o[4], o[5]); w.w = cvt_pk_bf16(o[6], o[7]);
;                     *(u32x4*)dst = w; } }
	s_nop 1
	v_mov_b32_e32 v70, v216
	v_mov_b32_e32 v71, v217
	v_cvt_f32_ubyte0_e32 v72, v70
	v_mul_f32_e32 v72, 0x3b808081, v72
	v_mul_f32_e32 v72, v62, v72
	v_cvt_f32_ubyte1_e32 v62, v70
	v_mul_f32_e32 v62, 0x3b808081, v62
	v_mul_f32_e32 v73, v63, v62
	v_cvt_f32_ubyte2_e32 v62, v70
	v_mul_f32_e32 v62, 0x3b808081, v62
	v_mul_f32_e32 v64, v64, v62
	v_cvt_f32_ubyte3_e32 v62, v70
	v_mul_f32_e32 v62, 0x3b808081, v62
	v_mul_f32_e32 v65, v65, v62
	v_cvt_f32_ubyte0_e32 v62, v71
	v_mul_f32_e32 v62, 0x3b808081, v62
	v_mul_f32_e32 v70, v58, v62
	v_cvt_f32_ubyte1_e32 v58, v71
	v_mul_f32_e32 v58, 0x3b808081, v58
	v_mul_f32_e32 v74, v59, v58
	v_cvt_f32_ubyte2_e32 v58, v71
	v_mul_f32_e32 v58, 0x3b808081, v58
	v_mul_f32_e32 v75, v60, v58
	v_cvt_f32_ubyte3_e32 v58, v71
	v_mul_f32_e32 v58, 0x3b808081, v58
	v_mul_f32_e32 v61, v61, v58
	v_lshl_add_u64 v[58:59], s[12:13], 0, v[68:69]
	v_lshl_add_u64 v[62:63], v[58:59], 0, v[126:127]
	v_cvt_pk_bf16_f32 v58, v72, v73
	v_cvt_pk_bf16_f32 v59, v64, v65
	v_cvt_pk_bf16_f32 v60, v70, v74
	v_cvt_pk_bf16_f32 v61, v75, v61
	global_store_dwordx4 v[62:63], v[58:61], off
	s_waitcnt vmcnt(15)
	s_nop 1
	v_mov_b32_e32 v58, v218
	v_mov_b32_e32 v59, v219
	v_cvt_f32_ubyte0_e32 v60, v58
	v_mul_f32_e32 v60, 0x3b808081, v60
	v_mul_f32_e32 v54, v54, v60
	v_cvt_f32_ubyte1_e32 v60, v58
	v_mul_f32_e32 v60, 0x3b808081, v60
	v_mul_f32_e32 v55, v55, v60
	v_cvt_f32_ubyte2_e32 v60, v58
	v_cvt_f32_ubyte3_e32 v58, v58
	v_mul_f32_e32 v58, 0x3b808081, v58
	v_mul_f32_e32 v57, v57, v58
	v_cvt_f32_ubyte0_e32 v58, v59
	v_mul_f32_e32 v58, 0x3b808081, v58
	v_mul_f32_e32 v58, v50, v58
	v_cvt_f32_ubyte1_e32 v50, v59
	v_mul_f32_e32 v60, 0x3b808081, v60
	v_mul_f32_e32 v50, 0x3b808081, v50
	v_mul_f32_e32 v56, v56, v60
	v_mul_f32_e32 v60, v51, v50
	v_cvt_f32_ubyte2_e32 v50, v59
	v_mul_f32_e32 v50, 0x3b808081, v50
	v_mul_f32_e32 v61, v52, v50
	v_cvt_f32_ubyte3_e32 v50, v59
	v_mul_f32_e32 v50, 0x3b808081, v50
	v_mul_f32_e32 v53, v53, v50
	v_cvt_pk_bf16_f32 v50, v54, v55
	v_cvt_pk_bf16_f32 v51, v56, v57
	v_cvt_pk_bf16_f32 v52, v58, v60
	v_cvt_pk_bf16_f32 v53, v61, v53
	global_store_dwordx4 v[62:63], v[50:53], off offset:256
	s_nop 1
	v_lshl_add_u64 v[52:53], v[148:149], 0, s[20:21]
	v_lshl_add_u64 v[50:51], s[14:15], 0, v[52:53]
	v_lshl_add_u64 v[50:51], v[50:51], 0, v[146:147]
	s_mov_b64 s[20:21], 0x50000
	s_waitcnt vmcnt(15)
	s_nop 1
	v_mov_b32_e32 v54, v220
	v_mov_b32_e32 v55, v221
	v_cvt_f32_ubyte0_e32 v56, v54
	v_mul_f32_e32 v56, 0x3b808081, v56
	v_mul_f32_e32 v56, v46, v56
	v_cvt_f32_ubyte1_e32 v46, v54
	v_mul_f32_e32 v46, 0x3b808081, v46
	v_mul_f32_e32 v57, v47, v46
	v_cvt_f32_ubyte2_e32 v46, v54
	v_mul_f32_e32 v46, 0x3b808081, v46
	v_mul_f32_e32 v48, v48, v46
	v_cvt_f32_ubyte3_e32 v46, v54
	v_mul_f32_e32 v46, 0x3b808081, v46
	v_mul_f32_e32 v49, v49, v46
	v_cvt_f32_ubyte0_e32 v46, v55
	v_mul_f32_e32 v46, 0x3b808081, v46
	v_mul_f32_e32 v54, v42, v46
	v_cvt_f32_ubyte1_e32 v42, v55
	v_mul_f32_e32 v42, 0x3b808081, v42
	v_mul_f32_e32 v58, v43, v42
	v_cvt_f32_ubyte2_e32 v42, v55
	v_mul_f32_e32 v42, 0x3b808081, v42
	v_mul_f32_e32 v59, v44, v42
	v_cvt_f32_ubyte3_e32 v42, v55
	v_mul_f32_e32 v42, 0x3b808081, v42
	v_mul_f32_e32 v45, v45, v42
	v_lshl_add_u64 v[42:43], s[12:13], 0, v[52:53]
	v_lshl_add_u64 v[46:47], v[42:43], 0, v[126:127]
	v_cvt_pk_bf16_f32 v42, v56, v57
	v_cvt_pk_bf16_f32 v43, v48, v49
	v_cvt_pk_bf16_f32 v44, v54, v58
	v_cvt_pk_bf16_f32 v45, v59, v45
	global_store_dwordx4 v[46:47], v[42:45], off
	s_waitcnt vmcnt(15)
	s_nop 1
	v_mov_b32_e32 v42, v222
	v_mov_b32_e32 v43, v223
	v_cvt_f32_ubyte0_e32 v44, v42
	v_mul_f32_e32 v44, 0x3b808081, v44
	v_mul_f32_e32 v38, v38, v44
	v_cvt_f32_ubyte1_e32 v44, v42
	v_mul_f32_e32 v44, 0x3b808081, v44
	v_mul_f32_e32 v39, v39, v44
	v_cvt_f32_ubyte2_e32 v44, v42
	v_cvt_f32_ubyte3_e32 v42, v42
	v_mul_f32_e32 v42, 0x3b808081, v42
	v_mul_f32_e32 v41, v41, v42
	v_cvt_f32_ubyte0_e32 v42, v43
	v_mul_f32_e32 v42, 0x3b808081, v42
	v_mul_f32_e32 v42, v34, v42
	v_cvt_f32_ubyte1_e32 v34, v43
	v_mul_f32_e32 v44, 0x3b808081, v44
	v_mul_f32_e32 v34, 0x3b808081, v34
	v_mul_f32_e32 v40, v40, v44
	v_mul_f32_e32 v44, v35, v34
	v_cvt_f32_ubyte2_e32 v34, v43
	v_mul_f32_e32 v34, 0x3b808081, v34
	v_mul_f32_e32 v45, v36, v34
	v_cvt_f32_ubyte3_e32 v34, v43
	v_mul_f32_e32 v34, 0x3b808081, v34
	v_mul_f32_e32 v37, v37, v34
	v_cvt_pk_bf16_f32 v34, v38, v39
	v_cvt_pk_bf16_f32 v35, v40, v41
	v_cvt_pk_bf16_f32 v36, v42, v44
	v_cvt_pk_bf16_f32 v37, v45, v37
	global_store_dwordx4 v[46:47], v[34:37], off offset:256
	s_nop 1
	v_lshl_add_u64 v[36:37], v[148:149], 0, s[20:21]
	v_lshl_add_u64 v[34:35], s[14:15], 0, v[36:37]
	v_lshl_add_u64 v[34:35], v[34:35], 0, v[146:147]
	s_mov_b64 s[20:21], 0x58000
	s_waitcnt vmcnt(14)
; __device__ __forceinline__ unsigned cvt_pk_bf16(float lo, float hi) { unsigned r; asm volatile("v_cvt_pk_bf16_f32 %0, %1, %2" : "=v"(r) : "v"(lo), "v"(hi)); return r; }
; __device__ __forceinline__ float bf_lo(unsigned w) { return __uint_as_float(w << 16); }
; __device__ __forceinline__ float bf_hi(unsigned w) { return __uint_as_float(w & 0xffff0000u); }
;     __device__ __forceinline__ void operator()(const f32x4 (&acc)[2][2][4][2], const Unit& u, int wr, int wc, int fr, int fq) const {
;     ...
;             for (int m = 0; m < 4; ++m) { const size_t row = (size_t)(row0 + ai * HALF + m * 16);
; #pragma unroll
;                 for (int bj = 0; bj < 2; ++bj) { const f32x4 v0 = acc[ai][bj][m][0], v1 = acc[ai][bj][m][1];
;                     const u32x2 g = *(const u32x2*)(G + row * ldg + col0 + bj * HALF);
;                     float o[8]; const float k255 = 1.0f / 255.0f;
;                     o[0] = v0[0] * ((float)(g.x & 0xffu) * k255); o[1] = v0[1] * ((float)((g.x >> 8) & 0xffu) * k255); o[2] = v0[2] * ((float)((g.x >> 16) & 0xffu) * k255); o[3] = v0[3] * ((float)(g.x >> 24) * k255);
;                     o[4] = v1[0] * ((float)(g.y & 0xffu) * k255); o[5] = v1[1] * ((float)((g.y >> 8) & 0xffu) * k255); o[6] = v1[2] * ((float)((g.y >> 16) & 0xffu) * k255); o[7] = v1[3] * ((float)(g.y >> 24) * k255);
;                     bf16_t* dst = MG + row * 1024 + col0 + bj * HALF;
;                     if (SECOND) { const u32x4 p = *(const u32x4*)dst;
;                         o[0] += bf_lo(p.x); o[1] += bf_hi(p.x); o[2] += bf_lo(p.y); o[3] += bf_hi(p.y); o[4] += bf_lo(p.z); o[5] += bf_hi(p.z); o[6] += bf_lo(p.w); o[7] += bf_hi(p.w); }
;                     u32x4 w; w.x = cvt_pk_bf16(o[0], o[1]); w.y = cvt_pk_bf16(o[2], o[3]); w.z = cvt_pk_bf16(o[4], o[5]); w.w = cvt_pk_bf16(o[6], o[7]);
;                     *(u32x4*)dst = w; } }
	s_nop 1
	v_mov_b32_e32 v38, v200
	v_mov_b32_e32 v39, v201
	v_cvt_f32_ubyte0_e32 v40, v38
	v_mul_f32_e32 v40, 0x3b808081, v40
	v_mul_f32_e32 v40, v30, v40
	v_cvt_f32_ubyte1_e32 v30, v38
	v_mul_f32_e32 v30, 0x3b808081, v30
	v_mul_f32_e32 v41, v31, v30
	v_cvt_f32_ubyte2_e32 v30, v38
	v_mul_f32_e32 v30, 0x3b808081, v30
	v_mul_f32_e32 v32, v32, v30
	v_cvt_f32_ubyte3_e32 v30, v38
	v_mul_f32_e32 v30, 0x3b808081, v30
	v_mul_f32_e32 v33, v33, v30
	v_cvt_f32_ubyte0_e32 v30, v39
	v_mul_f32_e32 v30, 0x3b808081, v30
	v_mul_f32_e32 v38, v26, v30
	v_cvt_f32_ubyte1_e32 v26, v39
	v_mul_f32_e32 v26, 0x3b808081, v26
	v_mul_f32_e32 v42, v27, v26
	v_cvt_f32_ubyte2_e32 v26, v39
	v_mul_f32_e32 v26, 0x3b808081, v26
	v_mul_f32_e32 v43, v28, v26
	v_cvt_f32_ubyte3_e32 v26, v39
	v_mul_f32_e32 v26, 0x3b808081, v26
	v_mul_f32_e32 v29, v29, v26
	v_lshl_add_u64 v[26:27], s[12:13], 0, v[36:37]
	v_lshl_add_u64 v[30:31], v[26:27], 0, v[126:127]
	v_cvt_pk_bf16_f32 v26, v40, v41
	v_cvt_pk_bf16_f32 v27, v32, v33
	v_cvt_pk_bf16_f32 v28, v38, v42
	v_cvt_pk_bf16_f32 v29, v43, v29
	global_store_dwordx4 v[30:31], v[26:29], off
	s_waitcnt vmcnt(14)
	s_nop 1
	v_mov_b32_e32 v26, v202
	v_mov_b32_e32 v27, v203
	v_cvt_f32_ubyte0_e32 v28, v26
	v_mul_f32_e32 v28, 0x3b808081, v28
	v_mul_f32_e32 v22, v22, v28
	v_cvt_f32_ubyte1_e32 v28, v26
	v_mul_f32_e32 v28, 0x3b808081, v28
	v_mul_f32_e32 v23, v23, v28
	v_cvt_f32_ubyte2_e32 v28, v26
	v_cvt_f32_ubyte3_e32 v26, v26
	v_mul_f32_e32 v26, 0x3b808081, v26
	v_mul_f32_e32 v25, v25, v26
	v_cvt_f32_ubyte0_e32 v26, v27
	v_mul_f32_e32 v26, 0x3b808081, v26
	v_mul_f32_e32 v26, v18, v26
	v_cvt_f32_ubyte1_e32 v18, v27
	v_mul_f32_e32 v28, 0x3b808081, v28
	v_mul_f32_e32 v18, 0x3b808081, v18
	v_mul_f32_e32 v24, v24, v28
	v_mul_f32_e32 v28, v19, v18
	v_cvt_f32_ubyte2_e32 v18, v27
	v_mul_f32_e32 v18, 0x3b808081, v18
	v_mul_f32_e32 v29, v20, v18
	v_cvt_f32_ubyte3_e32 v18, v27
	v_mul_f32_e32 v18, 0x3b808081, v18
	v_mul_f32_e32 v21, v21, v18
	v_cvt_pk_bf16_f32 v18, v22, v23
	v_cvt_pk_bf16_f32 v19, v24, v25
	v_cvt_pk_bf16_f32 v20, v26, v28
	v_cvt_pk_bf16_f32 v21, v29, v21
	global_store_dwordx4 v[30:31], v[18:21], off offset:256
	s_nop 1
	v_lshl_add_u64 v[20:21], v[148:149], 0, s[20:21]
	v_lshl_add_u64 v[18:19], s[14:15], 0, v[20:21]
	v_lshl_add_u64 v[18:19], v[18:19], 0, v[146:147]
	s_mov_b64 s[20:21], -1
	s_waitcnt vmcnt(12)
	s_nop 1
	v_mov_b32_e32 v22, v204
	v_mov_b32_e32 v23, v205
	v_cvt_f32_ubyte0_e32 v24, v22
	v_mul_f32_e32 v24, 0x3b808081, v24
	v_mul_f32_e32 v24, v14, v24
	v_cvt_f32_ubyte1_e32 v14, v22
	v_mul_f32_e32 v14, 0x3b808081, v14
	v_mul_f32_e32 v25, v15, v14
	v_cvt_f32_ubyte2_e32 v14, v22
	v_mul_f32_e32 v14, 0x3b808081, v14
	v_mul_f32_e32 v16, v16, v14
	v_cvt_f32_ubyte3_e32 v14, v22
	v_mul_f32_e32 v14, 0x3b808081, v14
	v_mul_f32_e32 v17, v17, v14
	v_cvt_f32_ubyte0_e32 v14, v23
	v_mul_f32_e32 v14, 0x3b808081, v14
	v_mul_f32_e32 v22, v10, v14
	v_cvt_f32_ubyte1_e32 v10, v23
	v_mul_f32_e32 v10, 0x3b808081, v10
	v_mul_f32_e32 v26, v11, v10
	v_cvt_f32_ubyte2_e32 v10, v23
	v_mul_f32_e32 v10, 0x3b808081, v10
	v_mul_f32_e32 v27, v12, v10
	v_cvt_f32_ubyte3_e32 v10, v23
	v_mul_f32_e32 v10, 0x3b808081, v10
	v_mul_f32_e32 v13, v13, v10
	v_lshl_add_u64 v[10:11], s[12:13], 0, v[20:21]
	v_lshl_add_u64 v[14:15], v[10:11], 0, v[126:127]
	v_cvt_pk_bf16_f32 v10, v24, v25
	v_cvt_pk_bf16_f32 v11, v16, v17
	v_cvt_pk_bf16_f32 v12, v22, v26
	v_cvt_pk_bf16_f32 v13, v27, v13
	global_store_dwordx4 v[14:15], v[10:13], off
	s_waitcnt vmcnt(12)
	s_nop 1
	v_mov_b32_e32 v10, v206
	v_mov_b32_e32 v11, v207
	v_cvt_f32_ubyte0_e32 v12, v10
	v_mul_f32_e32 v12, 0x3b808081, v12
	v_mul_f32_e32 v6, v6, v12
	v_cvt_f32_ubyte1_e32 v12, v10
	v_mul_f32_e32 v12, 0x3b808081, v12
	v_mul_f32_e32 v7, v7, v12
	v_cvt_f32_ubyte2_e32 v12, v10
	v_cvt_f32_ubyte3_e32 v10, v10
	v_mul_f32_e32 v10, 0x3b808081, v10
	v_mul_f32_e32 v9, v9, v10
	v_cvt_f32_ubyte0_e32 v10, v11
	v_mul_f32_e32 v10, 0x3b808081, v10
	v_mul_f32_e32 v10, v2, v10
	v_cvt_f32_ubyte1_e32 v2, v11
	v_mul_f32_e32 v12, 0x3b808081, v12
	v_mul_f32_e32 v2, 0x3b808081, v2
	v_mul_f32_e32 v8, v8, v12
	v_mul_f32_e32 v12, v3, v2
	v_cvt_f32_ubyte2_e32 v2, v11
	v_mul_f32_e32 v2, 0x3b808081, v2
	v_mul_f32_e32 v13, v4, v2
	v_cvt_f32_ubyte3_e32 v2, v11
	v_mul_f32_e32 v2, 0x3b808081, v2
	v_mul_f32_e32 v5, v5, v2
	v_cvt_pk_bf16_f32 v2, v6, v7
	v_cvt_pk_bf16_f32 v3, v8, v9
	v_cvt_pk_bf16_f32 v4, v10, v12
	v_cvt_pk_bf16_f32 v5, v13, v5
	global_store_dwordx4 v[14:15], v[2:5], off offset:256
	s_cbranch_vccnz .LBB0_676
	s_andn2_b64 vcc, exec, s[10:11]
	s_cbranch_vccnz .LBB0_675
	s_barrier
	s_branch .LBB0_675

; __device__ __forceinline__ unsigned cvt_pk_bf16(float lo, float hi) { unsigned r; asm volatile("v_cvt_pk_bf16_f32 %0, %1, %2" : "=v"(r) : "v"(lo), "v"(hi)); return r; }
; __device__ __forceinline__ float bf_lo(unsigned w) { return __uint_as_float(w << 16); }
; __device__ __forceinline__ float bf_hi(unsigned w) { return __uint_as_float(w & 0xffff0000u); }
;     __device__ __forceinline__ void operator()(const f32x4 (&acc)[2][2][4][2], const Unit& u, int wr, int wc, int fr, int fq) const {
;     ...
;             for (int m = 0; m < 4; ++m) { const size_t row = (size_t)(row0 + ai * HALF + m * 16);
; #pragma unroll
;                 for (int bj = 0; bj < 2; ++bj) { const f32x4 v0 = acc[ai][bj][m][0], v1 = acc[ai][bj][m][1];
;                     const u32x2 g = *(const u32x2*)(G + row * ldg + col0 + bj * HALF);
;                     float o[8]; const float k255 = 1.0f / 255.0f;
;                     o[0] = v0[0] * ((float)(g.x & 0xffu) * k255); o[1] = v0[1] * ((float)((g.x >> 8) & 0xffu) * k255); o[2] = v0[2] * ((float)((g.x >> 16) & 0xffu) * k255); o[3] = v0[3] * ((float)(g.x >> 24) * k255);
;                     o[4] = v1[0] * ((float)(g.y & 0xffu) * k255); o[5] = v1[1] * ((float)((g.y >> 8) & 0xffu) * k255); o[6] = v1[2] * ((float)((g.y >> 16) & 0xffu) * k255); o[7] = v1[3] * ((float)(g.y >> 24) * k255);
;                     bf16_t* dst = MG + row * 1024 + col0 + bj * HALF;
;                     if (SECOND) { const u32x4 p = *(const u32x4*)dst;
;                         o[0] += bf_lo(p.x); o[1] += bf_hi(p.x); o[2] += bf_lo(p.y); o[3] += bf_hi(p.y); o[4] += bf_lo(p.z); o[5] += bf_hi(p.z); o[6] += bf_lo(p.w); o[7] += bf_hi(p.w); }
;                     u32x4 w; w.x = cvt_pk_bf16(o[0], o[1]); w.y = cvt_pk_bf16(o[2], o[3]); w.z = cvt_pk_bf16(o[4], o[5]); w.w = cvt_pk_bf16(o[6], o[7]);
;                     *(u32x4*)dst = w; } }
.LBB0_703:
	v_lshl_add_u32 v152, s58, 8, v1
	v_ashrrev_i32_e32 v153, 31, v152
	v_lshl_or_b32 v148, s26, 8, v157
	v_lshlrev_b64 v[150:151], 11, v[152:153]
	v_ashrrev_i32_e32 v149, 31, v148
	v_lshl_add_u64 v[146:147], s[12:13], 0, v[150:151]
	v_lshl_add_u64 v[164:165], v[146:147], 0, v[148:149]
	global_load_dwordx2 v[146:147], v[164:165], off offset:1024
	s_mov_b64 s[26:27], 0x48000
	s_andn2_b64 vcc, exec, s[4:5]
	s_waitcnt vmcnt(0)
	v_cvt_f32_ubyte1_e32 v154, v146
	v_cvt_f32_ubyte0_e32 v153, v146
	v_mul_f32_e32 v159, 0x3b808081, v154
	v_cvt_f32_ubyte2_e32 v154, v146
	v_cvt_f32_ubyte3_e32 v146, v146
	v_mul_f32_e32 v167, 0x3b808081, v146
	v_cvt_f32_ubyte0_e32 v146, v147
	v_mul_f32_e32 v168, 0x3b808081, v146
	v_cvt_f32_ubyte1_e32 v146, v147
	v_mul_f32_e32 v169, 0x3b808081, v146
	v_cvt_f32_ubyte2_e32 v146, v147
	v_mul_f32_e32 v170, 0x3b808081, v146
	v_cvt_f32_ubyte3_e32 v146, v147
	v_mul_f32_e32 v166, 0x3b808081, v154
	v_mul_f32_e32 v171, 0x3b808081, v146
	v_lshl_add_u64 v[154:155], s[6:7], 0, v[150:151]
	v_lshlrev_b64 v[146:147], 1, v[148:149]
	v_lshl_add_u64 v[154:155], v[154:155], 0, v[146:147]
	s_mov_b32 s77, 0
	v_mov_b32_e32 v252, v164
	v_mov_b32_e32 v253, v165
	v_mov_b32_e32 v248, v154
	v_mov_b32_e32 v249, v155
	global_load_dwordx2 v[206:207], v[252:253], off offset:1152
	global_load_dwordx4 v[202:205], v[248:249], off
	global_load_dwordx4 v[208:211], v[248:249], off offset:256
	s_mov_b32 s76, 0x8000
	v_lshl_add_u64 v[250:251], v[252:253], 0, s[76:77]
	global_load_dwordx2 v[212:213], v[250:251], off offset:1024
	global_load_dwordx2 v[218:219], v[250:251], off offset:1152
	s_mov_b32 s76, 0x8000
	v_lshl_add_u64 v[250:251], v[248:249], 0, s[76:77]
	global_load_dwordx4 v[214:217], v[250:251], off
	global_load_dwordx4 v[220:223], v[250:251], off offset:256
	s_mov_b32 s76, 0x10000
	v_lshl_add_u64 v[250:251], v[252:253], 0, s[76:77]
	global_load_dwordx2 v[224:225], v[250:251], off offset:1024
	global_load_dwordx2 v[230:231], v[250:251], off offset:1152
	s_mov_b32 s76, 0x10000
	v_lshl_add_u64 v[250:251], v[248:249], 0, s[76:77]
	global_load_dwordx4 v[226:229], v[250:251], off
	global_load_dwordx4 v[232:235], v[250:251], off offset:256
	s_mov_b32 s76, 0x18000
	v_lshl_add_u64 v[250:251], v[252:253], 0, s[76:77]
	global_load_dwordx2 v[236:237], v[250:251], off offset:1024
	global_load_dwordx2 v[242:243], v[250:251], off offset:1152
	s_mov_b32 s76, 0x18000
	v_lshl_add_u64 v[250:251], v[248:249], 0, s[76:77]
	global_load_dwordx4 v[238:241], v[250:251], off
	global_load_dwordx4 v[244:247], v[250:251], off offset:256
	v_mul_f32_e32 v153, 0x3b808081, v153
	s_waitcnt vmcnt(13)
	s_nop 1
	v_mov_b32_e32 v160, v202
	v_mov_b32_e32 v161, v203
	v_mov_b32_e32 v162, v204
	v_mov_b32_e32 v163, v205
	v_lshlrev_b32_e32 v172, 16, v160
	v_fmac_f32_e32 v172, v130, v153
	v_and_b32_e32 v130, 0xffff0000, v160
	v_fmac_f32_e32 v130, v131, v159
	v_lshlrev_b32_e32 v131, 16, v161
	v_fmac_f32_e32 v131, v132, v166
	v_and_b32_e32 v132, 0xffff0000, v161
	v_fmac_f32_e32 v132, v133, v167
	v_lshlrev_b32_e32 v133, 16, v162
	v_and_b32_e32 v153, 0xffff0000, v162
	v_lshlrev_b32_e32 v159, 16, v163
	v_and_b32_e32 v160, 0xffff0000, v163
	v_fmac_f32_e32 v133, v126, v168
	v_fmac_f32_e32 v153, v127, v169
	v_fmac_f32_e32 v159, v128, v170
	v_fmac_f32_e32 v160, v129, v171
	v_cvt_pk_bf16_f32 v126, v172, v130
	v_cvt_pk_bf16_f32 v127, v131, v132
	v_cvt_pk_bf16_f32 v128, v133, v153
	v_cvt_pk_bf16_f32 v129, v159, v160
	global_store_dwordx4 v[154:155], v[126:129], off
	s_waitcnt vmcnt(15)
	s_nop 1
	v_mov_b32_e32 v126, v206
	v_mov_b32_e32 v127, v207
	v_cvt_f32_ubyte0_e32 v128, v126
	v_mul_f32_e32 v130, 0x3b808081, v128
	v_cvt_f32_ubyte1_e32 v128, v126
	v_mul_f32_e32 v131, 0x3b808081, v128
	v_cvt_f32_ubyte2_e32 v128, v126
	v_cvt_f32_ubyte3_e32 v126, v126
	v_mul_f32_e32 v133, 0x3b808081, v126
	v_cvt_f32_ubyte0_e32 v126, v127
	v_mul_f32_e32 v153, 0x3b808081, v126
	v_cvt_f32_ubyte1_e32 v126, v127
	v_mul_f32_e32 v159, 0x3b808081, v126
	v_cvt_f32_ubyte2_e32 v126, v127
	v_mul_f32_e32 v160, 0x3b808081, v126
	v_cvt_f32_ubyte3_e32 v126, v127
	v_mul_f32_e32 v132, 0x3b808081, v128
	v_mul_f32_e32 v161, 0x3b808081, v126
	s_waitcnt vmcnt(13)
	s_nop 1
	v_mov_b32_e32 v126, v208
	v_mov_b32_e32 v127, v209
	v_mov_b32_e32 v128, v210
	v_mov_b32_e32 v129, v211
	s_mov_b32 s76, 0x40000
	v_lshl_add_u64 v[250:251], v[252:253], 0, s[76:77]
	global_load_dwordx2 v[200:201], v[250:251], off offset:1024
	global_load_dwordx2 v[206:207], v[250:251], off offset:1152
	s_mov_b32 s76, 0x40000
	v_lshl_add_u64 v[250:251], v[248:249], 0, s[76:77]
	global_load_dwordx4 v[202:205], v[250:251], off
	global_load_dwordx4 v[208:211], v[250:251], off offset:256
	v_lshlrev_b32_e32 v162, 16, v126
	v_fmac_f32_e32 v162, v122, v130
	v_and_b32_e32 v122, 0xffff0000, v126
	v_fmac_f32_e32 v122, v123, v131
	v_lshlrev_b32_e32 v123, 16, v127
	v_fmac_f32_e32 v123, v124, v132
	v_and_b32_e32 v124, 0xffff0000, v127
	v_fmac_f32_e32 v124, v125, v133
	v_lshlrev_b32_e32 v125, 16, v128
	v_fmac_f32_e32 v125, v118, v153
	v_and_b32_e32 v126, 0xffff0000, v128
	v_lshlrev_b32_e32 v127, 16, v129
	v_and_b32_e32 v128, 0xffff0000, v129
	v_cvt_pk_bf16_f32 v118, v162, v122
	v_fmac_f32_e32 v126, v119, v159
	v_fmac_f32_e32 v127, v120, v160
	v_fmac_f32_e32 v128, v121, v161
	v_cvt_pk_bf16_f32 v119, v123, v124
	v_cvt_pk_bf16_f32 v120, v125, v126
	v_cvt_pk_bf16_f32 v121, v127, v128
	global_store_dwordx4 v[154:155], v[118:121], off offset:256
	s_nop 1
	v_or_b32_e32 v118, 16, v152
	v_ashrrev_i32_e32 v119, 31, v118
	v_lshlrev_b64 v[120:121], 11, v[118:119]
	v_lshl_add_u64 v[118:119], s[12:13], 0, v[120:121]
	v_lshl_add_u64 v[118:119], v[118:119], 0, v[148:149]
	v_lshl_add_u64 v[120:121], s[6:7], 0, v[120:121]
	v_lshl_add_u64 v[120:121], v[120:121], 0, v[146:147]
	s_waitcnt vmcnt(17)
; __device__ __forceinline__ unsigned cvt_pk_bf16(float lo, float hi) { unsigned r; asm volatile("v_cvt_pk_bf16_f32 %0, %1, %2" : "=v"(r) : "v"(lo), "v"(hi)); return r; }
; __device__ __forceinline__ float bf_lo(unsigned w) { return __uint_as_float(w << 16); }
; __device__ __forceinline__ float bf_hi(unsigned w) { return __uint_as_float(w & 0xffff0000u); }
;     __device__ __forceinline__ void operator()(const f32x4 (&acc)[2][2][4][2], const Unit& u, int wr, int wc, int fr, int fq) const {
;     ...
;             for (int m = 0; m < 4; ++m) { const size_t row = (size_t)(row0 + ai * HALF + m * 16);
; #pragma unroll
;                 for (int bj = 0; bj < 2; ++bj) { const f32x4 v0 = acc[ai][bj][m][0], v1 = acc[ai][bj][m][1];
;                     const u32x2 g = *(const u32x2*)(G + row * ldg + col0 + bj * HALF);
;                     float o[8]; const float k255 = 1.0f / 255.0f;
;                     o[0] = v0[0] * ((float)(g.x & 0xffu) * k255); o[1] = v0[1] * ((float)((g.x >> 8) & 0xffu) * k255); o[2] = v0[2] * ((float)((g.x >> 16) & 0xffu) * k255); o[3] = v0[3] * ((float)(g.x >> 24) * k255);
;                     o[4] = v1[0] * ((float)(g.y & 0xffu) * k255); o[5] = v1[1] * ((float)((g.y >> 8) & 0xffu) * k255); o[6] = v1[2] * ((float)((g.y >> 16) & 0xffu) * k255); o[7] = v1[3] * ((float)(g.y >> 24) * k255);
;                     bf16_t* dst = MG + row * 1024 + col0 + bj * HALF;
;                     if (SECOND) { const u32x4 p = *(const u32x4*)dst;
;                         o[0] += bf_lo(p.x); o[1] += bf_hi(p.x); o[2] += bf_lo(p.y); o[3] += bf_hi(p.y); o[4] += bf_lo(p.z); o[5] += bf_hi(p.z); o[6] += bf_lo(p.w); o[7] += bf_hi(p.w); }
;                     u32x4 w; w.x = cvt_pk_bf16(o[0], o[1]); w.y = cvt_pk_bf16(o[2], o[3]); w.z = cvt_pk_bf16(o[4], o[5]); w.w = cvt_pk_bf16(o[6], o[7]);
;                     *(u32x4*)dst = w; } }
	s_nop 1
	v_mov_b32_e32 v122, v212
	v_mov_b32_e32 v123, v213
	v_cvt_f32_ubyte0_e32 v124, v122
	v_mul_f32_e32 v126, 0x3b808081, v124
	v_cvt_f32_ubyte1_e32 v124, v122
	v_mul_f32_e32 v127, 0x3b808081, v124
	v_cvt_f32_ubyte2_e32 v124, v122
	v_cvt_f32_ubyte3_e32 v122, v122
	v_mul_f32_e32 v129, 0x3b808081, v122
	v_cvt_f32_ubyte0_e32 v122, v123
	v_mul_f32_e32 v130, 0x3b808081, v122
	v_cvt_f32_ubyte1_e32 v122, v123
	v_mul_f32_e32 v131, 0x3b808081, v122
	v_cvt_f32_ubyte2_e32 v122, v123
	v_mul_f32_e32 v132, 0x3b808081, v122
	v_cvt_f32_ubyte3_e32 v122, v123
	v_mul_f32_e32 v128, 0x3b808081, v124
	v_mul_f32_e32 v133, 0x3b808081, v122
	s_waitcnt vmcnt(15)
	s_nop 1
	v_mov_b32_e32 v122, v214
	v_mov_b32_e32 v123, v215
	v_mov_b32_e32 v124, v216
	v_mov_b32_e32 v125, v217
	v_lshlrev_b32_e32 v153, 16, v122
	v_fmac_f32_e32 v153, v114, v126
	v_and_b32_e32 v114, 0xffff0000, v122
	v_fmac_f32_e32 v114, v115, v127
	v_lshlrev_b32_e32 v115, 16, v123
	v_fmac_f32_e32 v115, v116, v128
	v_and_b32_e32 v116, 0xffff0000, v123
	v_fmac_f32_e32 v116, v117, v129
	v_lshlrev_b32_e32 v117, 16, v124
	v_and_b32_e32 v122, 0xffff0000, v124
	v_lshlrev_b32_e32 v123, 16, v125
	v_and_b32_e32 v124, 0xffff0000, v125
	v_fmac_f32_e32 v117, v110, v130
	v_fmac_f32_e32 v122, v111, v131
	v_fmac_f32_e32 v123, v112, v132
	v_fmac_f32_e32 v124, v113, v133
	v_cvt_pk_bf16_f32 v110, v153, v114
	v_cvt_pk_bf16_f32 v111, v115, v116
	v_cvt_pk_bf16_f32 v112, v117, v122
	v_cvt_pk_bf16_f32 v113, v123, v124
	global_store_dwordx4 v[120:121], v[110:113], off
	s_waitcnt vmcnt(17)
	s_nop 1
	v_mov_b32_e32 v110, v218
	v_mov_b32_e32 v111, v219
	v_cvt_f32_ubyte0_e32 v112, v110
	v_mul_f32_e32 v114, 0x3b808081, v112
	v_cvt_f32_ubyte1_e32 v112, v110
	v_mul_f32_e32 v115, 0x3b808081, v112
	v_cvt_f32_ubyte2_e32 v112, v110
	v_cvt_f32_ubyte3_e32 v110, v110
	v_mul_f32_e32 v117, 0x3b808081, v110
	v_cvt_f32_ubyte0_e32 v110, v111
	v_mul_f32_e32 v118, 0x3b808081, v110
	v_cvt_f32_ubyte1_e32 v110, v111
	v_mul_f32_e32 v119, 0x3b808081, v110
	v_cvt_f32_ubyte2_e32 v110, v111
	v_mul_f32_e32 v122, 0x3b808081, v110
	v_cvt_f32_ubyte3_e32 v110, v111
	v_mul_f32_e32 v116, 0x3b808081, v112
	v_mul_f32_e32 v123, 0x3b808081, v110
	s_waitcnt vmcnt(15)
	s_nop 1
	v_mov_b32_e32 v110, v220
	v_mov_b32_e32 v111, v221
	v_mov_b32_e32 v112, v222
	v_mov_b32_e32 v113, v223
	s_mov_b32 s76, 0x48000
	v_lshl_add_u64 v[250:251], v[252:253], 0, s[76:77]
	global_load_dwordx2 v[212:213], v[250:251], off offset:1024
	global_load_dwordx2 v[218:219], v[250:251], off offset:1152
	s_mov_b32 s76, 0x48000
	v_lshl_add_u64 v[250:251], v[248:249], 0, s[76:77]
	global_load_dwordx4 v[214:217], v[250:251], off
	global_load_dwordx4 v[220:223], v[250:251], off offset:256
	v_lshlrev_b32_e32 v124, 16, v110
	v_fmac_f32_e32 v124, v106, v114
	v_and_b32_e32 v106, 0xffff0000, v110
	v_fmac_f32_e32 v106, v107, v115
	v_lshlrev_b32_e32 v107, 16, v111
	v_fmac_f32_e32 v107, v108, v116
	v_and_b32_e32 v108, 0xffff0000, v111
	v_fmac_f32_e32 v108, v109, v117
	v_lshlrev_b32_e32 v109, 16, v112
	v_fmac_f32_e32 v109, v102, v118
	v_and_b32_e32 v110, 0xffff0000, v112
	v_lshlrev_b32_e32 v111, 16, v113
	v_and_b32_e32 v112, 0xffff0000, v113
	v_cvt_pk_bf16_f32 v102, v124, v106
	v_fmac_f32_e32 v110, v103, v119
	v_fmac_f32_e32 v111, v104, v122
	v_fmac_f32_e32 v112, v105, v123
	v_cvt_pk_bf16_f32 v103, v107, v108
	v_cvt_pk_bf16_f32 v104, v109, v110
	v_cvt_pk_bf16_f32 v105, v111, v112
	global_store_dwordx4 v[120:121], v[102:105], off offset:256
	s_nop 1
	v_or_b32_e32 v102, 32, v152
	v_ashrrev_i32_e32 v103, 31, v102
	v_lshlrev_b64 v[104:105], 11, v[102:103]
	v_lshl_add_u64 v[102:103], s[12:13], 0, v[104:105]
	v_lshl_add_u64 v[102:103], v[102:103], 0, v[148:149]
	v_lshl_add_u64 v[104:105], s[6:7], 0, v[104:105]
	v_lshl_add_u64 v[104:105], v[104:105], 0, v[146:147]
	s_waitcnt vmcnt(19)
	s_nop 1
	v_mov_b32_e32 v106, v224
	v_mov_b32_e32 v107, v225
	v_cvt_f32_ubyte0_e32 v108, v106
	v_mul_f32_e32 v110, 0x3b808081, v108
	v_cvt_f32_ubyte1_e32 v108, v106
	v_mul_f32_e32 v111, 0x3b808081, v108
	v_cvt_f32_ubyte2_e32 v108, v106
	v_cvt_f32_ubyte3_e32 v106, v106
	v_mul_f32_e32 v113, 0x3b808081, v106
	v_cvt_f32_ubyte0_e32 v106, v107
	v_mul_f32_e32 v114, 0x3b808081, v106
	v_cvt_f32_ubyte1_e32 v106, v107
	v_mul_f32_e32 v115, 0x3b808081, v106
	v_cvt_f32_ubyte2_e32 v106, v107
	v_mul_f32_e32 v116, 0x3b808081, v106
	v_cvt_f32_ubyte3_e32 v106, v107
	v_mul_f32_e32 v112, 0x3b808081, v108
	v_mul_f32_e32 v117, 0x3b808081, v106
	s_waitcnt vmcnt(17)
	s_nop 1
	v_mov_b32_e32 v106, v226
	v_mov_b32_e32 v107, v227
	v_mov_b32_e32 v108, v228
	v_mov_b32_e32 v109, v229
	v_lshlrev_b32_e32 v118, 16, v106
	v_fmac_f32_e32 v118, v98, v110
	v_and_b32_e32 v98, 0xffff0000, v106
	v_fmac_f32_e32 v98, v99, v111
	v_lshlrev_b32_e32 v99, 16, v107
	v_fmac_f32_e32 v99, v100, v112
	v_and_b32_e32 v100, 0xffff0000, v107
	v_fmac_f32_e32 v100, v101, v113
	v_lshlrev_b32_e32 v101, 16, v108
	v_and_b32_e32 v106, 0xffff0000, v108
	v_lshlrev_b32_e32 v107, 16, v109
	v_and_b32_e32 v108, 0xffff0000, v109
	v_fmac_f32_e32 v101, v94, v114
	v_fmac_f32_e32 v106, v95, v115
	v_fmac_f32_e32 v107, v96, v116
	v_fmac_f32_e32 v108, v97, v117
	v_cvt_pk_bf16_f32 v94, v118, v98
	v_cvt_pk_bf16_f32 v95, v99, v100
	v_cvt_pk_bf16_f32 v96, v101, v106
	v_cvt_pk_bf16_f32 v97, v107, v108
	global_store_dwordx4 v[104:105], v[94:97], off
	s_waitcnt vmcnt(19)
	s_nop 1
	v_mov_b32_e32 v94, v230
	v_mov_b32_e32 v95, v231
	v_cvt_f32_ubyte0_e32 v96, v94
	v_mul_f32_e32 v98, 0x3b808081, v96
	v_cvt_f32_ubyte1_e32 v96, v94
	v_mul_f32_e32 v99, 0x3b808081, v96
	v_cvt_f32_ubyte2_e32 v96, v94
	v_cvt_f32_ubyte3_e32 v94, v94
	v_mul_f32_e32 v101, 0x3b808081, v94
	v_cvt_f32_ubyte0_e32 v94, v95
	v_mul_f32_e32 v102, 0x3b808081, v94
	v_cvt_f32_ubyte1_e32 v94, v95
	v_mul_f32_e32 v103, 0x3b808081, v94
	v_cvt_f32_ubyte2_e32 v94, v95
	v_mul_f32_e32 v106, 0x3b808081, v94
	v_cvt_f32_ubyte3_e32 v94, v95
	v_mul_f32_e32 v100, 0x3b808081, v96
	v_mul_f32_e32 v107, 0x3b808081, v94
	s_waitcnt vmcnt(17)
; __device__ __forceinline__ unsigned cvt_pk_bf16(float lo, float hi) { unsigned r; asm volatile("v_cvt_pk_bf16_f32 %0, %1, %2" : "=v"(r) : "v"(lo), "v"(hi)); return r; }
; __device__ __forceinline__ float bf_lo(unsigned w) { return __uint_as_float(w << 16); }
; __device__ __forceinline__ float bf_hi(unsigned w) { return __uint_as_float(w & 0xffff0000u); }
;     __device__ __forceinline__ void operator()(const f32x4 (&acc)[2][2][4][2], const Unit& u, int wr, int wc, int fr, int fq) const {
;     ...
;             for (int m = 0; m < 4; ++m) { const size_t row = (size_t)(row0 + ai * HALF + m * 16);
; #pragma unroll
;                 for (int bj = 0; bj < 2; ++bj) { const f32x4 v0 = acc[ai][bj][m][0], v1 = acc[ai][bj][m][1];
;                     const u32x2 g = *(const u32x2*)(G + row * ldg + col0 + bj * HALF);
;                     float o[8]; const float k255 = 1.0f / 255.0f;
;                     o[0] = v0[0] * ((float)(g.x & 0xffu) * k255); o[1] = v0[1] * ((float)((g.x >> 8) & 0xffu) * k255); o[2] = v0[2] * ((float)((g.x >> 16) & 0xffu) * k255); o[3] = v0[3] * ((float)(g.x >> 24) * k255);
;                     o[4] = v1[0] * ((float)(g.y & 0xffu) * k255); o[5] = v1[1] * ((float)((g.y >> 8) & 0xffu) * k255); o[6] = v1[2] * ((float)((g.y >> 16) & 0xffu) * k255); o[7] = v1[3] * ((float)(g.y >> 24) * k255);
;                     bf16_t* dst = MG + row * 1024 + col0 + bj * HALF;
;                     if (SECOND) { const u32x4 p = *(const u32x4*)dst;
;                         o[0] += bf_lo(p.x); o[1] += bf_hi(p.x); o[2] += bf_lo(p.y); o[3] += bf_hi(p.y); o[4] += bf_lo(p.z); o[5] += bf_hi(p.z); o[6] += bf_lo(p.w); o[7] += bf_hi(p.w); }
;                     u32x4 w; w.x = cvt_pk_bf16(o[0], o[1]); w.y = cvt_pk_bf16(o[2], o[3]); w.z = cvt_pk_bf16(o[4], o[5]); w.w = cvt_pk_bf16(o[6], o[7]);
;                     *(u32x4*)dst = w; } }
	s_nop 1
	v_mov_b32_e32 v94, v232
	v_mov_b32_e32 v95, v233
	v_mov_b32_e32 v96, v234
	v_mov_b32_e32 v97, v235
	s_mov_b32 s76, 0x50000
	v_lshl_add_u64 v[250:251], v[252:253], 0, s[76:77]
	global_load_dwordx2 v[224:225], v[250:251], off offset:1024
	global_load_dwordx2 v[230:231], v[250:251], off offset:1152
	s_mov_b32 s76, 0x50000
	v_lshl_add_u64 v[250:251], v[248:249], 0, s[76:77]
	global_load_dwordx4 v[226:229], v[250:251], off
	global_load_dwordx4 v[232:235], v[250:251], off offset:256
	v_lshlrev_b32_e32 v108, 16, v94
	v_fmac_f32_e32 v108, v90, v98
	v_and_b32_e32 v90, 0xffff0000, v94
	v_fmac_f32_e32 v90, v91, v99
	v_lshlrev_b32_e32 v91, 16, v95
	v_fmac_f32_e32 v91, v92, v100
	v_and_b32_e32 v92, 0xffff0000, v95
	v_fmac_f32_e32 v92, v93, v101
	v_lshlrev_b32_e32 v93, 16, v96
	v_fmac_f32_e32 v93, v86, v102
	v_and_b32_e32 v94, 0xffff0000, v96
	v_lshlrev_b32_e32 v95, 16, v97
	v_and_b32_e32 v96, 0xffff0000, v97
	v_cvt_pk_bf16_f32 v86, v108, v90
	v_fmac_f32_e32 v94, v87, v103
	v_fmac_f32_e32 v95, v88, v106
	v_fmac_f32_e32 v96, v89, v107
	v_cvt_pk_bf16_f32 v87, v91, v92
	v_cvt_pk_bf16_f32 v88, v93, v94
	v_cvt_pk_bf16_f32 v89, v95, v96
	global_store_dwordx4 v[104:105], v[86:89], off offset:256
	s_nop 1
	v_or_b32_e32 v86, 48, v152
	v_ashrrev_i32_e32 v87, 31, v86
	v_lshlrev_b64 v[88:89], 11, v[86:87]
	v_lshl_add_u64 v[86:87], s[12:13], 0, v[88:89]
	v_lshl_add_u64 v[86:87], v[86:87], 0, v[148:149]
	v_lshl_add_u64 v[88:89], s[6:7], 0, v[88:89]
	v_lshl_add_u64 v[88:89], v[88:89], 0, v[146:147]
	s_waitcnt vmcnt(21)
	s_nop 1
	v_mov_b32_e32 v90, v236
	v_mov_b32_e32 v91, v237
	v_cvt_f32_ubyte0_e32 v92, v90
	v_mul_f32_e32 v94, 0x3b808081, v92
	v_cvt_f32_ubyte1_e32 v92, v90
	v_mul_f32_e32 v95, 0x3b808081, v92
	v_cvt_f32_ubyte2_e32 v92, v90
	v_cvt_f32_ubyte3_e32 v90, v90
	v_mul_f32_e32 v97, 0x3b808081, v90
	v_cvt_f32_ubyte0_e32 v90, v91
	v_mul_f32_e32 v98, 0x3b808081, v90
	v_cvt_f32_ubyte1_e32 v90, v91
	v_mul_f32_e32 v99, 0x3b808081, v90
	v_cvt_f32_ubyte2_e32 v90, v91
	v_mul_f32_e32 v100, 0x3b808081, v90
	v_cvt_f32_ubyte3_e32 v90, v91
	v_mul_f32_e32 v96, 0x3b808081, v92
	v_mul_f32_e32 v101, 0x3b808081, v90
	s_waitcnt vmcnt(19)
	s_nop 1
	v_mov_b32_e32 v90, v238
	v_mov_b32_e32 v91, v239
	v_mov_b32_e32 v92, v240
	v_mov_b32_e32 v93, v241
	v_lshlrev_b32_e32 v102, 16, v90
	v_fmac_f32_e32 v102, v78, v94
	v_and_b32_e32 v78, 0xffff0000, v90
	v_fmac_f32_e32 v78, v79, v95
	v_lshlrev_b32_e32 v79, 16, v91
	v_fmac_f32_e32 v79, v80, v96
	v_and_b32_e32 v80, 0xffff0000, v91
	v_fmac_f32_e32 v80, v81, v97
	v_lshlrev_b32_e32 v81, 16, v92
	v_and_b32_e32 v90, 0xffff0000, v92
	v_lshlrev_b32_e32 v91, 16, v93
	v_and_b32_e32 v92, 0xffff0000, v93
	v_fmac_f32_e32 v81, v74, v98
	v_fmac_f32_e32 v90, v75, v99
	v_fmac_f32_e32 v91, v76, v100
	v_fmac_f32_e32 v92, v77, v101
	v_cvt_pk_bf16_f32 v74, v102, v78
	v_cvt_pk_bf16_f32 v75, v79, v80
	v_cvt_pk_bf16_f32 v76, v81, v90
	v_cvt_pk_bf16_f32 v77, v91, v92
	global_store_dwordx4 v[88:89], v[74:77], off
	s_waitcnt vmcnt(21)
	s_nop 1
	v_mov_b32_e32 v74, v242
	v_mov_b32_e32 v75, v243
	v_cvt_f32_ubyte0_e32 v76, v74
	v_mul_f32_e32 v78, 0x3b808081, v76
	v_cvt_f32_ubyte1_e32 v76, v74
	v_mul_f32_e32 v79, 0x3b808081, v76
	v_cvt_f32_ubyte2_e32 v76, v74
	v_cvt_f32_ubyte3_e32 v74, v74
	v_mul_f32_e32 v81, 0x3b808081, v74
	v_cvt_f32_ubyte0_e32 v74, v75
	v_mul_f32_e32 v86, 0x3b808081, v74
	v_cvt_f32_ubyte1_e32 v74, v75
	v_mul_f32_e32 v87, 0x3b808081, v74
	v_cvt_f32_ubyte2_e32 v74, v75
	v_mul_f32_e32 v90, 0x3b808081, v74
	v_cvt_f32_ubyte3_e32 v74, v75
	v_mul_f32_e32 v80, 0x3b808081, v76
	v_mul_f32_e32 v91, 0x3b808081, v74
	s_waitcnt vmcnt(19)
	s_nop 1
	v_mov_b32_e32 v74, v244
	v_mov_b32_e32 v75, v245
	v_mov_b32_e32 v76, v246
	v_mov_b32_e32 v77, v247
	s_mov_b32 s76, 0x58000
	v_lshl_add_u64 v[250:251], v[252:253], 0, s[76:77]
	global_load_dwordx2 v[236:237], v[250:251], off offset:1024
	global_load_dwordx2 v[242:243], v[250:251], off offset:1152
	s_mov_b32 s76, 0x58000
	v_lshl_add_u64 v[250:251], v[248:249], 0, s[76:77]
	global_load_dwordx4 v[238:241], v[250:251], off
	global_load_dwordx4 v[244:247], v[250:251], off offset:256
	v_lshlrev_b32_e32 v92, 16, v74
	v_fmac_f32_e32 v92, v70, v78
	v_and_b32_e32 v70, 0xffff0000, v74
	v_fmac_f32_e32 v70, v71, v79
	v_lshlrev_b32_e32 v71, 16, v75
	v_fmac_f32_e32 v71, v72, v80
	v_and_b32_e32 v72, 0xffff0000, v75
	v_fmac_f32_e32 v72, v73, v81
	v_lshlrev_b32_e32 v73, 16, v76
	v_and_b32_e32 v74, 0xffff0000, v76
	v_lshlrev_b32_e32 v75, 16, v77
	v_and_b32_e32 v76, 0xffff0000, v77
	v_fmac_f32_e32 v73, v66, v86
	v_fmac_f32_e32 v74, v67, v87
	v_fmac_f32_e32 v75, v68, v90
	v_fmac_f32_e32 v76, v69, v91
	v_cvt_pk_bf16_f32 v66, v92, v70
	v_cvt_pk_bf16_f32 v67, v71, v72
	v_cvt_pk_bf16_f32 v68, v73, v74
	v_cvt_pk_bf16_f32 v69, v75, v76
	global_store_dwordx4 v[88:89], v[66:69], off offset:256
	s_nop 1
	v_lshl_add_u64 v[68:69], v[150:151], 0, s[68:69]
	v_lshl_add_u64 v[66:67], s[12:13], 0, v[68:69]
	v_lshl_add_u64 v[66:67], v[66:67], 0, v[148:149]
	v_lshl_add_u64 v[68:69], s[6:7], 0, v[68:69]
	v_lshl_add_u64 v[68:69], v[68:69], 0, v[146:147]
	s_waitcnt vmcnt(22)
	s_nop 1
	v_mov_b32_e32 v70, v200
	v_mov_b32_e32 v71, v201
	v_cvt_f32_ubyte0_e32 v72, v70
	v_mul_f32_e32 v74, 0x3b808081, v72
	v_cvt_f32_ubyte1_e32 v72, v70
	v_mul_f32_e32 v75, 0x3b808081, v72
	v_cvt_f32_ubyte2_e32 v72, v70
	v_cvt_f32_ubyte3_e32 v70, v70
	v_mul_f32_e32 v77, 0x3b808081, v70
	v_cvt_f32_ubyte0_e32 v70, v71
	v_mul_f32_e32 v78, 0x3b808081, v70
	v_cvt_f32_ubyte1_e32 v70, v71
	v_mul_f32_e32 v79, 0x3b808081, v70
	v_cvt_f32_ubyte2_e32 v70, v71
	v_mul_f32_e32 v80, 0x3b808081, v70
	v_cvt_f32_ubyte3_e32 v70, v71
	v_mul_f32_e32 v76, 0x3b808081, v72
	v_mul_f32_e32 v81, 0x3b808081, v70
	s_waitcnt vmcnt(20)
; __device__ __forceinline__ unsigned cvt_pk_bf16(float lo, float hi) { unsigned r; asm volatile("v_cvt_pk_bf16_f32 %0, %1, %2" : "=v"(r) : "v"(lo), "v"(hi)); return r; }
; __device__ __forceinline__ float bf_lo(unsigned w) { return __uint_as_float(w << 16); }
; __device__ __forceinline__ float bf_hi(unsigned w) { return __uint_as_float(w & 0xffff0000u); }
;     __device__ __forceinline__ void operator()(const f32x4 (&acc)[2][2][4][2], const Unit& u, int wr, int wc, int fr, int fq) const {
;     ...
;             for (int m = 0; m < 4; ++m) { const size_t row = (size_t)(row0 + ai * HALF + m * 16);
; #pragma unroll
;                 for (int bj = 0; bj < 2; ++bj) { const f32x4 v0 = acc[ai][bj][m][0], v1 = acc[ai][bj][m][1];
;                     const u32x2 g = *(const u32x2*)(G + row * ldg + col0 + bj * HALF);
;                     float o[8]; const float k255 = 1.0f / 255.0f;
;                     o[0] = v0[0] * ((float)(g.x & 0xffu) * k255); o[1] = v0[1] * ((float)((g.x >> 8) & 0xffu) * k255); o[2] = v0[2] * ((float)((g.x >> 16) & 0xffu) * k255); o[3] = v0[3] * ((float)(g.x >> 24) * k255);
;                     o[4] = v1[0] * ((float)(g.y & 0xffu) * k255); o[5] = v1[1] * ((float)((g.y >> 8) & 0xffu) * k255); o[6] = v1[2] * ((float)((g.y >> 16) & 0xffu) * k255); o[7] = v1[3] * ((float)(g.y >> 24) * k255);
;                     bf16_t* dst = MG + row * 1024 + col0 + bj * HALF;
;                     if (SECOND) { const u32x4 p = *(const u32x4*)dst;
;                         o[0] += bf_lo(p.x); o[1] += bf_hi(p.x); o[2] += bf_lo(p.y); o[3] += bf_hi(p.y); o[4] += bf_lo(p.z); o[5] += bf_hi(p.z); o[6] += bf_lo(p.w); o[7] += bf_hi(p.w); }
;                     u32x4 w; w.x = cvt_pk_bf16(o[0], o[1]); w.y = cvt_pk_bf16(o[2], o[3]); w.z = cvt_pk_bf16(o[4], o[5]); w.w = cvt_pk_bf16(o[6], o[7]);
;                     *(u32x4*)dst = w; } }
	s_nop 1
	v_mov_b32_e32 v70, v202
	v_mov_b32_e32 v71, v203
	v_mov_b32_e32 v72, v204
	v_mov_b32_e32 v73, v205
	v_lshlrev_b32_e32 v86, 16, v70
	v_fmac_f32_e32 v86, v62, v74
	v_and_b32_e32 v62, 0xffff0000, v70
	v_fmac_f32_e32 v62, v63, v75
	v_lshlrev_b32_e32 v63, 16, v71
	v_fmac_f32_e32 v63, v64, v76
	v_and_b32_e32 v64, 0xffff0000, v71
	v_fmac_f32_e32 v64, v65, v77
	v_lshlrev_b32_e32 v65, 16, v72
	v_and_b32_e32 v70, 0xffff0000, v72
	v_lshlrev_b32_e32 v71, 16, v73
	v_and_b32_e32 v72, 0xffff0000, v73
	v_fmac_f32_e32 v65, v58, v78
	v_fmac_f32_e32 v70, v59, v79
	v_fmac_f32_e32 v71, v60, v80
	v_fmac_f32_e32 v72, v61, v81
	v_cvt_pk_bf16_f32 v58, v86, v62
	v_cvt_pk_bf16_f32 v59, v63, v64
	v_cvt_pk_bf16_f32 v60, v65, v70
	v_cvt_pk_bf16_f32 v61, v71, v72
	global_store_dwordx4 v[68:69], v[58:61], off
	s_waitcnt vmcnt(22)
	s_nop 1
	v_mov_b32_e32 v58, v206
	v_mov_b32_e32 v59, v207
	v_cvt_f32_ubyte0_e32 v60, v58
	v_mul_f32_e32 v62, 0x3b808081, v60
	v_cvt_f32_ubyte1_e32 v60, v58
	v_mul_f32_e32 v63, 0x3b808081, v60
	v_cvt_f32_ubyte2_e32 v60, v58
	v_cvt_f32_ubyte3_e32 v58, v58
	v_mul_f32_e32 v65, 0x3b808081, v58
	v_cvt_f32_ubyte0_e32 v58, v59
	v_mul_f32_e32 v66, 0x3b808081, v58
	v_cvt_f32_ubyte1_e32 v58, v59
	v_mul_f32_e32 v67, 0x3b808081, v58
	v_cvt_f32_ubyte2_e32 v58, v59
	v_mul_f32_e32 v70, 0x3b808081, v58
	v_cvt_f32_ubyte3_e32 v58, v59
	v_mul_f32_e32 v64, 0x3b808081, v60
	v_mul_f32_e32 v71, 0x3b808081, v58
	s_waitcnt vmcnt(20)
	s_nop 1
	v_mov_b32_e32 v58, v208
	v_mov_b32_e32 v59, v209
	v_mov_b32_e32 v60, v210
	v_mov_b32_e32 v61, v211
	v_lshlrev_b32_e32 v72, 16, v58
	v_fmac_f32_e32 v72, v54, v62
	v_and_b32_e32 v54, 0xffff0000, v58
	v_fmac_f32_e32 v54, v55, v63
	v_lshlrev_b32_e32 v55, 16, v59
	v_fmac_f32_e32 v55, v56, v64
	v_and_b32_e32 v56, 0xffff0000, v59
	v_fmac_f32_e32 v56, v57, v65
	v_lshlrev_b32_e32 v57, 16, v60
	v_and_b32_e32 v58, 0xffff0000, v60
	v_lshlrev_b32_e32 v59, 16, v61
	v_and_b32_e32 v60, 0xffff0000, v61
	v_fmac_f32_e32 v57, v50, v66
	v_fmac_f32_e32 v58, v51, v67
	v_fmac_f32_e32 v59, v52, v70
	v_fmac_f32_e32 v60, v53, v71
	v_cvt_pk_bf16_f32 v50, v72, v54
	v_cvt_pk_bf16_f32 v51, v55, v56
	v_cvt_pk_bf16_f32 v52, v57, v58
	v_cvt_pk_bf16_f32 v53, v59, v60
	global_store_dwordx4 v[68:69], v[50:53], off offset:256
	s_nop 1
	v_lshl_add_u64 v[52:53], v[150:151], 0, s[26:27]
	v_lshl_add_u64 v[50:51], s[12:13], 0, v[52:53]
	v_lshl_add_u64 v[50:51], v[50:51], 0, v[148:149]
	v_lshl_add_u64 v[52:53], s[6:7], 0, v[52:53]
	v_lshl_add_u64 v[52:53], v[52:53], 0, v[146:147]
	s_mov_b64 s[26:27], 0x50000
	s_waitcnt vmcnt(18)
	s_nop 1
	v_mov_b32_e32 v54, v212
	v_mov_b32_e32 v55, v213
	v_cvt_f32_ubyte0_e32 v56, v54
	v_mul_f32_e32 v58, 0x3b808081, v56
	v_cvt_f32_ubyte1_e32 v56, v54
	v_mul_f32_e32 v59, 0x3b808081, v56
	v_cvt_f32_ubyte2_e32 v56, v54
	v_cvt_f32_ubyte3_e32 v54, v54
	v_mul_f32_e32 v61, 0x3b808081, v54
	v_cvt_f32_ubyte0_e32 v54, v55
	v_mul_f32_e32 v62, 0x3b808081, v54
	v_cvt_f32_ubyte1_e32 v54, v55
	v_mul_f32_e32 v63, 0x3b808081, v54
	v_cvt_f32_ubyte2_e32 v54, v55
	v_mul_f32_e32 v64, 0x3b808081, v54
	v_cvt_f32_ubyte3_e32 v54, v55
	v_mul_f32_e32 v60, 0x3b808081, v56
	v_mul_f32_e32 v65, 0x3b808081, v54
	s_waitcnt vmcnt(16)
	s_nop 1
	v_mov_b32_e32 v54, v214
	v_mov_b32_e32 v55, v215
	v_mov_b32_e32 v56, v216
	v_mov_b32_e32 v57, v217
	v_lshlrev_b32_e32 v66, 16, v54
	v_fmac_f32_e32 v66, v46, v58
	v_and_b32_e32 v46, 0xffff0000, v54
	v_fmac_f32_e32 v46, v47, v59
	v_lshlrev_b32_e32 v47, 16, v55
	v_fmac_f32_e32 v47, v48, v60
	v_and_b32_e32 v48, 0xffff0000, v55
	v_fmac_f32_e32 v48, v49, v61
	v_lshlrev_b32_e32 v49, 16, v56
	v_and_b32_e32 v54, 0xffff0000, v56
	v_lshlrev_b32_e32 v55, 16, v57
	v_and_b32_e32 v56, 0xffff0000, v57
	v_fmac_f32_e32 v49, v42, v62
	v_fmac_f32_e32 v54, v43, v63
	v_fmac_f32_e32 v55, v44, v64
	v_fmac_f32_e32 v56, v45, v65
	v_cvt_pk_bf16_f32 v42, v66, v46
	v_cvt_pk_bf16_f32 v43, v47, v48
	v_cvt_pk_bf16_f32 v44, v49, v54
	v_cvt_pk_bf16_f32 v45, v55, v56
	global_store_dwordx4 v[52:53], v[42:45], off
	s_waitcnt vmcnt(18)
	s_nop 1
	v_mov_b32_e32 v42, v218
	v_mov_b32_e32 v43, v219
	v_cvt_f32_ubyte0_e32 v44, v42
	v_mul_f32_e32 v46, 0x3b808081, v44
	v_cvt_f32_ubyte1_e32 v44, v42
	v_mul_f32_e32 v47, 0x3b808081, v44
	v_cvt_f32_ubyte2_e32 v44, v42
	v_cvt_f32_ubyte3_e32 v42, v42
	v_mul_f32_e32 v49, 0x3b808081, v42
	v_cvt_f32_ubyte0_e32 v42, v43
	v_mul_f32_e32 v50, 0x3b808081, v42
	v_cvt_f32_ubyte1_e32 v42, v43
	v_mul_f32_e32 v51, 0x3b808081, v42
	v_cvt_f32_ubyte2_e32 v42, v43
	v_mul_f32_e32 v54, 0x3b808081, v42
	v_cvt_f32_ubyte3_e32 v42, v43
	v_mul_f32_e32 v48, 0x3b808081, v44
	v_mul_f32_e32 v55, 0x3b808081, v42
	s_waitcnt vmcnt(16)
	s_nop 1
	v_mov_b32_e32 v42, v220
	v_mov_b32_e32 v43, v221
	v_mov_b32_e32 v44, v222
	v_mov_b32_e32 v45, v223
	v_lshlrev_b32_e32 v56, 16, v42
	v_fmac_f32_e32 v56, v38, v46
	v_and_b32_e32 v38, 0xffff0000, v42
	v_fmac_f32_e32 v38, v39, v47
	v_lshlrev_b32_e32 v39, 16, v43
	v_fmac_f32_e32 v39, v40, v48
	v_and_b32_e32 v40, 0xffff0000, v43
	v_fmac_f32_e32 v40, v41, v49
	v_lshlrev_b32_e32 v41, 16, v44
	v_and_b32_e32 v42, 0xffff0000, v44
	v_lshlrev_b32_e32 v43, 16, v45
	v_and_b32_e32 v44, 0xffff0000, v45
	v_fmac_f32_e32 v41, v34, v50
	v_fmac_f32_e32 v42, v35, v51
	v_fmac_f32_e32 v43, v36, v54
	v_fmac_f32_e32 v44, v37, v55
	v_cvt_pk_bf16_f32 v34, v56, v38
	v_cvt_pk_bf16_f32 v35, v39, v40
	v_cvt_pk_bf16_f32 v36, v41, v42
	v_cvt_pk_bf16_f32 v37, v43, v44
	global_store_dwordx4 v[52:53], v[34:37], off offset:256
	s_nop 1
	v_lshl_add_u64 v[36:37], v[150:151], 0, s[26:27]
	v_lshl_add_u64 v[34:35], s[12:13], 0, v[36:37]
	v_lshl_add_u64 v[34:35], v[34:35], 0, v[148:149]
	v_lshl_add_u64 v[36:37], s[6:7], 0, v[36:37]
	v_lshl_add_u64 v[36:37], v[36:37], 0, v[146:147]
	s_mov_b64 s[26:27], 0x58000
	s_waitcnt vmcnt(14)
; __device__ __forceinline__ unsigned cvt_pk_bf16(float lo, float hi) { unsigned r; asm volatile("v_cvt_pk_bf16_f32 %0, %1, %2" : "=v"(r) : "v"(lo), "v"(hi)); return r; }
; __device__ __forceinline__ float bf_lo(unsigned w) { return __uint_as_float(w << 16); }
;     __device__ __forceinline__ void operator()(const f32x4 (&acc)[2][2][4][2], const Unit& u, int wr, int wc, int fr, int fq) const {
;     ...
;             for (int m = 0; m < 4; ++m) { const size_t row = (size_t)(row0 + ai * HALF + m * 16);
; #pragma unroll
;                 for (int bj = 0; bj < 2; ++bj) { const f32x4 v0 = acc[ai][bj][m][0], v1 = acc[ai][bj][m][1];
;                     const u32x2 g = *(const u32x2*)(G + row * ldg + col0 + bj * HALF);
;                     float o[8]; const float k255 = 1.0f / 255.0f;
;                     o[0] = v0[0] * ((float)(g.x & 0xffu) * k255); o[1] = v0[1] * ((float)((g.x >> 8) & 0xffu) * k255); o[2] = v0[2] * ((float)((g.x >> 16) & 0xffu) * k255); o[3] = v0[3] * ((float)(g.x >> 24) * k255);
;                     o[4] = v1[0] * ((float)(g.y & 0xffu) * k255); o[5] = v1[1] * ((float)((g.y >> 8) & 0xffu) * k255); o[6] = v1[2] * ((float)((g.y >> 16) & 0xffu) * k255); o[7] = v1[3] * ((float)(g.y >> 24) * k255);
;                     bf16_t* dst = MG + row * 1024 + col0 + bj * HALF;
;                     if (SECOND) { const u32x4 p = *(const u32x4*)dst;
;                         o[0] += bf_lo(p.x); o[1] += bf_hi(p.x); o[2] += bf_lo(p.y); o[3] += bf_hi(p.y); o[4] += bf_lo(p.z); o[5] += bf_hi(p.z); o[6] += bf_lo(p.w); o[7] += bf_hi(p.w); }
;                     u32x4 w; w.x = cvt_pk_bf16(o[0], o[1]); w.y = cvt_pk_bf16(o[2], o[3]); w.z = cvt_pk_bf16(o[4], o[5]); w.w = cvt_pk_bf16(o[6], o[7]);
;                     *(u32x4*)dst = w; } }
; template <class Epi, class Sched, bool ALIGN_EPI = false, bool SP2 = false>
; __device__ __forceinline__ void gemm_phase(PG8_LAS unsigned char* lds, const Gemm g, const Sched& S, const Epi& E) {
;     ...
;         if (!has_next) break;
; #pragma unroll
;         for (int a = 0; a < 2; ++a)
; #pragma unroll
;             for (int b = 0; b < 2; ++b)
; #pragma unroll
;                 for (int m = 0; m < 4; ++m)
; #pragma unroll
;                     for (int n = 0; n < 2; ++n) acc[a][b][m][n] = (f32x4){0.f, 0.f, 0.f, 0.f};
;         cur = nxt; cA = nA; cB = nB; ++ui;
;         if constexpr (ALIGN_EPI) { if (wr == 1) PG8_BAR; }
	s_nop 1
	v_mov_b32_e32 v38, v224
	v_mov_b32_e32 v39, v225
	v_cvt_f32_ubyte0_e32 v40, v38
	v_mul_f32_e32 v42, 0x3b808081, v40
	v_cvt_f32_ubyte1_e32 v40, v38
	v_mul_f32_e32 v43, 0x3b808081, v40
	v_cvt_f32_ubyte2_e32 v40, v38
	v_cvt_f32_ubyte3_e32 v38, v38
	v_mul_f32_e32 v45, 0x3b808081, v38
	v_cvt_f32_ubyte0_e32 v38, v39
	v_mul_f32_e32 v46, 0x3b808081, v38
	v_cvt_f32_ubyte1_e32 v38, v39
	v_mul_f32_e32 v47, 0x3b808081, v38
	v_cvt_f32_ubyte2_e32 v38, v39
	v_mul_f32_e32 v48, 0x3b808081, v38
	v_cvt_f32_ubyte3_e32 v38, v39
	v_mul_f32_e32 v44, 0x3b808081, v40
	v_mul_f32_e32 v49, 0x3b808081, v38
	s_waitcnt vmcnt(12)
	s_nop 1
	v_mov_b32_e32 v38, v226
	v_mov_b32_e32 v39, v227
	v_mov_b32_e32 v40, v228
	v_mov_b32_e32 v41, v229
	v_lshlrev_b32_e32 v50, 16, v38
	v_fmac_f32_e32 v50, v30, v42
	v_and_b32_e32 v30, 0xffff0000, v38
	v_fmac_f32_e32 v30, v31, v43
	v_lshlrev_b32_e32 v31, 16, v39
	v_fmac_f32_e32 v31, v32, v44
	v_and_b32_e32 v32, 0xffff0000, v39
	v_fmac_f32_e32 v32, v33, v45
	v_lshlrev_b32_e32 v33, 16, v40
	v_and_b32_e32 v38, 0xffff0000, v40
	v_lshlrev_b32_e32 v39, 16, v41
	v_and_b32_e32 v40, 0xffff0000, v41
	v_fmac_f32_e32 v33, v26, v46
	v_fmac_f32_e32 v38, v27, v47
	v_fmac_f32_e32 v39, v28, v48
	v_fmac_f32_e32 v40, v29, v49
	v_cvt_pk_bf16_f32 v26, v50, v30
	v_cvt_pk_bf16_f32 v27, v31, v32
	v_cvt_pk_bf16_f32 v28, v33, v38
	v_cvt_pk_bf16_f32 v29, v39, v40
	global_store_dwordx4 v[36:37], v[26:29], off
	s_waitcnt vmcnt(14)
	s_nop 1
	v_mov_b32_e32 v26, v230
	v_mov_b32_e32 v27, v231
	v_cvt_f32_ubyte0_e32 v28, v26
	v_mul_f32_e32 v30, 0x3b808081, v28
	v_cvt_f32_ubyte1_e32 v28, v26
	v_mul_f32_e32 v31, 0x3b808081, v28
	v_cvt_f32_ubyte2_e32 v28, v26
	v_cvt_f32_ubyte3_e32 v26, v26
	v_mul_f32_e32 v33, 0x3b808081, v26
	v_cvt_f32_ubyte0_e32 v26, v27
	v_mul_f32_e32 v34, 0x3b808081, v26
	v_cvt_f32_ubyte1_e32 v26, v27
	v_mul_f32_e32 v35, 0x3b808081, v26
	v_cvt_f32_ubyte2_e32 v26, v27
	v_mul_f32_e32 v38, 0x3b808081, v26
	v_cvt_f32_ubyte3_e32 v26, v27
	v_mul_f32_e32 v32, 0x3b808081, v28
	v_mul_f32_e32 v39, 0x3b808081, v26
	s_waitcnt vmcnt(12)
	s_nop 1
	v_mov_b32_e32 v26, v232
	v_mov_b32_e32 v27, v233
	v_mov_b32_e32 v28, v234
	v_mov_b32_e32 v29, v235
	v_lshlrev_b32_e32 v40, 16, v26
	v_fmac_f32_e32 v40, v22, v30
	v_and_b32_e32 v22, 0xffff0000, v26
	v_fmac_f32_e32 v22, v23, v31
	v_lshlrev_b32_e32 v23, 16, v27
	v_fmac_f32_e32 v23, v24, v32
	v_and_b32_e32 v24, 0xffff0000, v27
	v_fmac_f32_e32 v24, v25, v33
	v_lshlrev_b32_e32 v25, 16, v28
	v_and_b32_e32 v26, 0xffff0000, v28
	v_lshlrev_b32_e32 v27, 16, v29
	v_and_b32_e32 v28, 0xffff0000, v29
	v_fmac_f32_e32 v25, v18, v34
	v_fmac_f32_e32 v26, v19, v35
	v_fmac_f32_e32 v27, v20, v38
	v_fmac_f32_e32 v28, v21, v39
	v_cvt_pk_bf16_f32 v18, v40, v22
	v_cvt_pk_bf16_f32 v19, v23, v24
	v_cvt_pk_bf16_f32 v20, v25, v26
	v_cvt_pk_bf16_f32 v21, v27, v28
	global_store_dwordx4 v[36:37], v[18:21], off offset:256
	s_nop 1
	v_lshl_add_u64 v[20:21], v[150:151], 0, s[26:27]
	v_lshl_add_u64 v[18:19], s[12:13], 0, v[20:21]
	v_lshl_add_u64 v[18:19], v[18:19], 0, v[148:149]
	v_lshl_add_u64 v[20:21], s[6:7], 0, v[20:21]
	v_lshl_add_u64 v[20:21], v[20:21], 0, v[146:147]
	s_mov_b64 s[26:27], -1
	s_waitcnt vmcnt(10)
	s_nop 1
	v_mov_b32_e32 v22, v236
	v_mov_b32_e32 v23, v237
	v_cvt_f32_ubyte0_e32 v24, v22
	v_mul_f32_e32 v26, 0x3b808081, v24
	v_cvt_f32_ubyte1_e32 v24, v22
	v_mul_f32_e32 v27, 0x3b808081, v24
	v_cvt_f32_ubyte2_e32 v24, v22
	v_cvt_f32_ubyte3_e32 v22, v22
	v_mul_f32_e32 v29, 0x3b808081, v22
	v_cvt_f32_ubyte0_e32 v22, v23
	v_mul_f32_e32 v30, 0x3b808081, v22
	v_cvt_f32_ubyte1_e32 v22, v23
	v_mul_f32_e32 v31, 0x3b808081, v22
	v_cvt_f32_ubyte2_e32 v22, v23
	v_mul_f32_e32 v32, 0x3b808081, v22
	v_cvt_f32_ubyte3_e32 v22, v23
	v_mul_f32_e32 v28, 0x3b808081, v24
	v_mul_f32_e32 v33, 0x3b808081, v22
	s_waitcnt vmcnt(8)
	s_nop 1
	v_mov_b32_e32 v22, v238
	v_mov_b32_e32 v23, v239
	v_mov_b32_e32 v24, v240
	v_mov_b32_e32 v25, v241
	v_lshlrev_b32_e32 v34, 16, v22
	v_fmac_f32_e32 v34, v14, v26
	v_and_b32_e32 v14, 0xffff0000, v22
	v_fmac_f32_e32 v14, v15, v27
	v_lshlrev_b32_e32 v15, 16, v23
	v_fmac_f32_e32 v15, v16, v28
	v_and_b32_e32 v16, 0xffff0000, v23
	v_fmac_f32_e32 v16, v17, v29
	v_lshlrev_b32_e32 v17, 16, v24
	v_and_b32_e32 v22, 0xffff0000, v24
	v_lshlrev_b32_e32 v23, 16, v25
	v_and_b32_e32 v24, 0xffff0000, v25
	v_fmac_f32_e32 v17, v10, v30
	v_fmac_f32_e32 v22, v11, v31
	v_fmac_f32_e32 v23, v12, v32
	v_fmac_f32_e32 v24, v13, v33
	v_cvt_pk_bf16_f32 v10, v34, v14
	v_cvt_pk_bf16_f32 v11, v15, v16
	v_cvt_pk_bf16_f32 v12, v17, v22
	v_cvt_pk_bf16_f32 v13, v23, v24
	global_store_dwordx4 v[20:21], v[10:13], off
	s_waitcnt vmcnt(10)
	s_nop 1
	v_mov_b32_e32 v10, v242
	v_mov_b32_e32 v11, v243
	v_cvt_f32_ubyte0_e32 v12, v10
	v_mul_f32_e32 v14, 0x3b808081, v12
	v_cvt_f32_ubyte1_e32 v12, v10
	v_mul_f32_e32 v15, 0x3b808081, v12
	v_cvt_f32_ubyte2_e32 v12, v10
	v_cvt_f32_ubyte3_e32 v10, v10
	v_mul_f32_e32 v17, 0x3b808081, v10
	v_cvt_f32_ubyte0_e32 v10, v11
	v_mul_f32_e32 v18, 0x3b808081, v10
	v_cvt_f32_ubyte1_e32 v10, v11
	v_mul_f32_e32 v19, 0x3b808081, v10
	v_cvt_f32_ubyte2_e32 v10, v11
	v_mul_f32_e32 v22, 0x3b808081, v10
	v_cvt_f32_ubyte3_e32 v10, v11
	v_mul_f32_e32 v16, 0x3b808081, v12
	v_mul_f32_e32 v23, 0x3b808081, v10
	s_waitcnt vmcnt(8)
	s_nop 1
	v_mov_b32_e32 v10, v244
	v_mov_b32_e32 v11, v245
	v_mov_b32_e32 v12, v246
	v_mov_b32_e32 v13, v247
	v_lshlrev_b32_e32 v24, 16, v10
	v_fmac_f32_e32 v24, v6, v14
	v_and_b32_e32 v6, 0xffff0000, v10
	v_fmac_f32_e32 v6, v7, v15
	v_lshlrev_b32_e32 v7, 16, v11
	v_fmac_f32_e32 v7, v8, v16
	v_and_b32_e32 v8, 0xffff0000, v11
	v_fmac_f32_e32 v8, v9, v17
	v_lshlrev_b32_e32 v9, 16, v12
	v_and_b32_e32 v10, 0xffff0000, v12
	v_lshlrev_b32_e32 v11, 16, v13
	v_and_b32_e32 v12, 0xffff0000, v13
	v_fmac_f32_e32 v9, v2, v18
	v_fmac_f32_e32 v10, v3, v19
	v_fmac_f32_e32 v11, v4, v22
	v_fmac_f32_e32 v12, v5, v23
	v_cvt_pk_bf16_f32 v2, v24, v6
	v_cvt_pk_bf16_f32 v3, v7, v8
	v_cvt_pk_bf16_f32 v4, v9, v10
	v_cvt_pk_bf16_f32 v5, v11, v12
	global_store_dwordx4 v[20:21], v[2:5], off offset:256
	s_cbranch_vccnz .LBB0_696
	s_andn2_b64 vcc, exec, s[10:11]
	s_cbranch_vccnz .LBB0_695
	s_barrier
	s_branch .LBB0_695

; __device__ __forceinline__ unsigned cvt_pk_bf16(float lo, float hi) { unsigned r; asm volatile("v_cvt_pk_bf16_f32 %0, %1, %2" : "=v"(r) : "v"(lo), "v"(hi)); return r; }
;     __device__ __forceinline__ void operator()(const f32x4 (&acc)[2][2][4][2], const Unit& u, int wr, int wc, int fr, int fq) const {
;         const int row0 = u.pm * BM + wr * 64 + fr, col0 = u.pn * BM + wc * 32 + 4 * fq;
; #pragma unroll
;         for (int ai = 0; ai < 2; ++ai)
; #pragma unroll
;             for (int m = 0; m < 4; ++m) { const int lrow = row0 + ai * HALF + m * 16; const int grow = grow0 + lrow;
;                 const float* xr = (grow < 65536) ? xp + (size_t)grow * 1024 : xs + (size_t)(grow - 65536) * 1024;
;                 bf16_t* brow = XB + (size_t)lrow * 1024; float ss = 0.f;
; #pragma unroll
;                 for (int bj = 0; bj < 2; ++bj)
; #pragma unroll
;                     for (int n = 0; n < 2; ++n) { const int c = col0 + bj * HALF + n * 16; const f32x4 xv = *(const f32x4*)(xr + c); const f32x4 o = xv + acc[ai][bj][m][n];
;                         ss += (o[0] * o[0] + o[1] * o[1]) + (o[2] * o[2] + o[3] * o[3]);
;                         u32x2 w; w.x = cvt_pk_bf16(o[0], o[1]); w.y = cvt_pk_bf16(o[2], o[3]); *(u32x2*)(brow + c) = w; }
;                 ss += __shfl_xor(ss, 16); ss += __shfl_xor(ss, 32);
;                 if (fq == 0) atomicAdd(SS + grow, ss); }
.LBB0_773:
	v_lshl_add_u32 v144, s64, 8, v1
	v_add_u32_e32 v146, s40, v144
	s_mov_b32 s25, 0x10000
	v_add_u32_e32 v143, 0xffff0000, v146
	v_cmp_gt_i32_e32 vcc, s25, v146
	v_ashrrev_i32_e32 v147, 31, v146
	v_mov_b32_e32 v145, s9
	v_cndmask_b32_e32 v152, v143, v146, vcc
	v_mov_b32_e32 v143, s11
	v_cndmask_b32_e32 v153, 0, v147, vcc
	v_cndmask_b32_e32 v155, v143, v145, vcc
	v_mov_b32_e32 v143, s10
	v_mov_b32_e32 v145, s8
	v_lshl_or_b32 v142, s62, 8, v149
	v_cndmask_b32_e32 v154, v143, v145, vcc
	v_lshlrev_b64 v[152:153], 12, v[152:153]
	v_lshl_add_u64 v[152:153], v[154:155], 0, v[152:153]
	v_ashrrev_i32_e32 v143, 31, v142
	v_lshl_add_u64 v[156:157], v[142:143], 2, v[152:153]
	v_mov_b32_e32 v252, v156
	v_mov_b32_e32 v253, v157
	s_mov_b32 s77, 0
	global_load_dwordx4 v[200:203], v[252:253], off
	global_load_dwordx4 v[204:207], v[252:253], off offset:64
	global_load_dwordx4 v[208:211], v[252:253], off offset:512
	global_load_dwordx4 v[212:215], v[252:253], off offset:576
	s_mov_b32 s76, 0x10000
	v_lshl_add_u64 v[250:251], v[252:253], 0, s[76:77]
	global_load_dwordx4 v[216:219], v[250:251], off
	global_load_dwordx4 v[220:223], v[250:251], off offset:64
	global_load_dwordx4 v[224:227], v[250:251], off offset:512
	global_load_dwordx4 v[228:231], v[250:251], off offset:576
	s_mov_b32 s76, 0x20000
	v_lshl_add_u64 v[250:251], v[252:253], 0, s[76:77]
	global_load_dwordx4 v[232:235], v[250:251], off
	global_load_dwordx4 v[236:239], v[250:251], off offset:64
	global_load_dwordx4 v[240:243], v[250:251], off offset:512
	global_load_dwordx4 v[244:247], v[250:251], off offset:576
	v_ashrrev_i32_e32 v145, 31, v144
	v_lshlrev_b64 v[158:159], 11, v[144:145]
	v_lshl_add_u64 v[158:159], s[14:15], 0, v[158:159]
	v_lshl_add_u64 v[158:159], v[142:143], 1, v[158:159]
	s_waitcnt vmcnt(11)
	v_mov_b32_e32 v152, v200
	v_mov_b32_e32 v153, v201
	v_mov_b32_e32 v154, v202
	v_mov_b32_e32 v155, v203
	v_pk_add_f32 v[154:155], v[132:133], v[154:155]
	v_pk_add_f32 v[152:153], v[130:131], v[152:153]
	v_mul_f32_e32 v151, v155, v155
	v_cvt_pk_bf16_f32 v130, v152, v153
	v_cvt_pk_bf16_f32 v131, v154, v155
	global_store_dwordx2 v[158:159], v[130:131], off
	v_mul_f32_e32 v145, v153, v153
	v_fmac_f32_e32 v145, v152, v152
	v_fmac_f32_e32 v151, v154, v154
	v_add_f32_e32 v145, v145, v151
	s_waitcnt vmcnt(11)
	v_mov_b32_e32 v130, v204
	v_mov_b32_e32 v131, v205
	v_mov_b32_e32 v132, v206
	v_mov_b32_e32 v133, v207
	v_pk_add_f32 v[132:133], v[128:129], v[132:133]
	v_pk_add_f32 v[130:131], v[126:127], v[130:131]
	s_nop 0
	v_cvt_pk_bf16_f32 v126, v130, v131
	v_cvt_pk_bf16_f32 v127, v132, v133
	global_store_dwordx2 v[158:159], v[126:127], off offset:32
	v_mul_f32_e32 v131, v131, v131
	v_mul_f32_e32 v133, v133, v133
	v_fmac_f32_e32 v131, v130, v130
	v_fmac_f32_e32 v133, v132, v132
	v_add_f32_e32 v130, v131, v133
	v_add_f32_e32 v130, v145, v130
	s_waitcnt vmcnt(11)
	v_mov_b32_e32 v126, v208
	v_mov_b32_e32 v127, v209
	v_mov_b32_e32 v128, v210
	v_mov_b32_e32 v129, v211
	v_pk_add_f32 v[128:129], v[124:125], v[128:129]
	v_pk_add_f32 v[160:161], v[122:123], v[126:127]
	s_nop 0
	v_cvt_pk_bf16_f32 v122, v160, v161
	v_cvt_pk_bf16_f32 v123, v128, v129
	global_store_dwordx2 v[158:159], v[122:123], off offset:256
	v_and_b32_e32 v123, 64, v194
	v_mul_f32_e32 v131, v161, v161
	v_mul_f32_e32 v129, v129, v129
	v_xor_b32_e32 v122, 16, v194
	v_add_u32_e32 v123, 64, v123
	v_fmac_f32_e32 v131, v160, v160
	v_fmac_f32_e32 v129, v128, v128
	v_cmp_lt_i32_e32 vcc, v122, v123
	v_add_f32_e32 v128, v131, v129
	v_add_f32_e32 v128, v130, v128
	v_cndmask_b32_e32 v122, v194, v122, vcc
	v_lshlrev_b32_e32 v122, 2, v122
	s_waitcnt vmcnt(11)
	v_mov_b32_e32 v124, v212
	v_mov_b32_e32 v125, v213
	v_mov_b32_e32 v126, v214
	v_mov_b32_e32 v127, v215
	s_mov_b32 s76, 0x30000
	v_lshl_add_u64 v[250:251], v[252:253], 0, s[76:77]
	global_load_dwordx4 v[200:203], v[250:251], off
	global_load_dwordx4 v[204:207], v[250:251], off offset:64
	global_load_dwordx4 v[208:211], v[250:251], off offset:512
	global_load_dwordx4 v[212:215], v[250:251], off offset:576
	v_pk_add_f32 v[126:127], v[120:121], v[126:127]
	v_pk_add_f32 v[124:125], v[118:119], v[124:125]
	v_mul_f32_e32 v119, v127, v127
	v_mul_f32_e32 v118, v125, v125
	v_fmac_f32_e32 v118, v124, v124
	v_fmac_f32_e32 v119, v126, v126
	v_add_f32_e32 v118, v118, v119
	v_add_f32_e32 v118, v128, v118
	ds_bpermute_b32 v119, v122, v118
	v_xor_b32_e32 v120, 32, v194
	v_cmp_lt_i32_e32 vcc, v120, v123
	v_cvt_pk_bf16_f32 v124, v124, v125
	v_cvt_pk_bf16_f32 v125, v126, v127
	s_waitcnt lgkmcnt(0)
	v_add_f32_e32 v118, v118, v119
	global_store_dwordx2 v[158:159], v[124:125], off offset:288
	v_cndmask_b32_e32 v120, v194, v120, vcc
	v_lshlrev_b32_e32 v120, 2, v120
	ds_bpermute_b32 v119, v120, v118
	s_and_saveexec_b64 s[62:63], s[4:5]
	s_cbranch_execz .LBB0_775
	s_waitcnt lgkmcnt(0)
	v_add_f32_e32 v121, v118, v119
	v_lshl_add_u64 v[118:119], v[146:147], 2, s[18:19]
	global_atomic_add_f32 v[118:119], v121, off
; __device__ __forceinline__ unsigned cvt_pk_bf16(float lo, float hi) { unsigned r; asm volatile("v_cvt_pk_bf16_f32 %0, %1, %2" : "=v"(r) : "v"(lo), "v"(hi)); return r; }
;     __device__ __forceinline__ void operator()(const f32x4 (&acc)[2][2][4][2], const Unit& u, int wr, int wc, int fr, int fq) const {
;         const int row0 = u.pm * BM + wr * 64 + fr, col0 = u.pn * BM + wc * 32 + 4 * fq;
; #pragma unroll
;         for (int ai = 0; ai < 2; ++ai)
; #pragma unroll
;             for (int m = 0; m < 4; ++m) { const int lrow = row0 + ai * HALF + m * 16; const int grow = grow0 + lrow;
;                 const float* xr = (grow < 65536) ? xp + (size_t)grow * 1024 : xs + (size_t)(grow - 65536) * 1024;
;                 bf16_t* brow = XB + (size_t)lrow * 1024; float ss = 0.f;
; #pragma unroll
;                 for (int bj = 0; bj < 2; ++bj)
; #pragma unroll
;                     for (int n = 0; n < 2; ++n) { const int c = col0 + bj * HALF + n * 16; const f32x4 xv = *(const f32x4*)(xr + c); const f32x4 o = xv + acc[ai][bj][m][n];
;                         ss += (o[0] * o[0] + o[1] * o[1]) + (o[2] * o[2] + o[3] * o[3]);
;                         u32x2 w; w.x = cvt_pk_bf16(o[0], o[1]); w.y = cvt_pk_bf16(o[2], o[3]); *(u32x2*)(brow + c) = w; }
;                 ss += __shfl_xor(ss, 16); ss += __shfl_xor(ss, 32);
;                 if (fq == 0) atomicAdd(SS + grow, ss); }
.LBB0_775:
	s_or_b64 exec, exec, s[62:63]
	v_or_b32_e32 v128, 16, v144
	v_add_u32_e32 v118, s40, v128
	v_add_u32_e32 v121, 0xffff0000, v118
	v_cmp_gt_i32_e32 vcc, s25, v118
	s_waitcnt lgkmcnt(0)
	v_ashrrev_i32_e32 v119, 31, v118
	v_mov_b32_e32 v123, s9
	v_cndmask_b32_e32 v124, v121, v118, vcc
	v_mov_b32_e32 v121, s11
	v_cndmask_b32_e32 v125, 0, v119, vcc
	v_cndmask_b32_e32 v127, v121, v123, vcc
	v_mov_b32_e32 v121, s10
	v_mov_b32_e32 v123, s8
	v_cndmask_b32_e32 v126, v121, v123, vcc
	v_lshlrev_b64 v[124:125], 12, v[124:125]
	v_lshl_add_u64 v[124:125], v[126:127], 0, v[124:125]
	v_lshl_add_u64 v[130:131], v[142:143], 2, v[124:125]
	v_ashrrev_i32_e32 v129, 31, v128
	v_lshlrev_b64 v[128:129], 11, v[128:129]
	v_lshl_add_u64 v[128:129], s[14:15], 0, v[128:129]
	v_lshl_add_u64 v[128:129], v[142:143], 1, v[128:129]
	s_waitcnt vmcnt(16)
	v_mov_b32_e32 v124, v216
	v_mov_b32_e32 v125, v217
	v_mov_b32_e32 v126, v218
	v_mov_b32_e32 v127, v219
	v_pk_add_f32 v[126:127], v[116:117], v[126:127]
	v_pk_add_f32 v[124:125], v[114:115], v[124:125]
	v_mul_f32_e32 v123, v127, v127
	v_cvt_pk_bf16_f32 v114, v124, v125
	v_cvt_pk_bf16_f32 v115, v126, v127
	global_store_dwordx2 v[128:129], v[114:115], off
	v_mul_f32_e32 v121, v125, v125
	v_fmac_f32_e32 v121, v124, v124
	v_fmac_f32_e32 v123, v126, v126
	v_add_f32_e32 v121, v121, v123
	s_waitcnt vmcnt(16)
	v_mov_b32_e32 v114, v220
	v_mov_b32_e32 v115, v221
	v_mov_b32_e32 v116, v222
	v_mov_b32_e32 v117, v223
	v_pk_add_f32 v[116:117], v[112:113], v[116:117]
	v_pk_add_f32 v[114:115], v[110:111], v[114:115]
	s_nop 0
	v_cvt_pk_bf16_f32 v110, v114, v115
	v_cvt_pk_bf16_f32 v111, v116, v117
	global_store_dwordx2 v[128:129], v[110:111], off offset:32
	v_mul_f32_e32 v115, v115, v115
	v_mul_f32_e32 v117, v117, v117
	v_fmac_f32_e32 v115, v114, v114
	v_fmac_f32_e32 v117, v116, v116
	v_add_f32_e32 v114, v115, v117
	v_add_f32_e32 v114, v121, v114
	s_waitcnt vmcnt(16)
	v_mov_b32_e32 v110, v224
	v_mov_b32_e32 v111, v225
	v_mov_b32_e32 v112, v226
	v_mov_b32_e32 v113, v227
	v_pk_add_f32 v[112:113], v[108:109], v[112:113]
	v_pk_add_f32 v[110:111], v[106:107], v[110:111]
	s_nop 0
	v_cvt_pk_bf16_f32 v106, v110, v111
	v_cvt_pk_bf16_f32 v107, v112, v113
	global_store_dwordx2 v[128:129], v[106:107], off offset:256
	v_mul_f32_e32 v111, v111, v111
	v_mul_f32_e32 v113, v113, v113
	v_fmac_f32_e32 v111, v110, v110
	v_fmac_f32_e32 v113, v112, v112
	v_add_f32_e32 v110, v111, v113
	v_add_f32_e32 v110, v114, v110
	s_waitcnt vmcnt(16)
	v_mov_b32_e32 v106, v228
	v_mov_b32_e32 v107, v229
	v_mov_b32_e32 v108, v230
	v_mov_b32_e32 v109, v231
	s_mov_b32 s76, 0x80000
	v_lshl_add_u64 v[250:251], v[252:253], 0, s[76:77]
	global_load_dwordx4 v[216:219], v[250:251], off
	global_load_dwordx4 v[220:223], v[250:251], off offset:64
	global_load_dwordx4 v[224:227], v[250:251], off offset:512
	global_load_dwordx4 v[228:231], v[250:251], off offset:576
	v_pk_add_f32 v[104:105], v[104:105], v[108:109]
	v_pk_add_f32 v[106:107], v[102:103], v[106:107]
	v_mul_f32_e32 v103, v105, v105
	v_mul_f32_e32 v102, v107, v107
	v_fmac_f32_e32 v102, v106, v106
	v_fmac_f32_e32 v103, v104, v104
	v_add_f32_e32 v102, v102, v103
	v_add_f32_e32 v102, v110, v102
	ds_bpermute_b32 v103, v122, v102
	v_cvt_pk_bf16_f32 v106, v106, v107
	v_cvt_pk_bf16_f32 v107, v104, v105
	global_store_dwordx2 v[128:129], v[106:107], off offset:288
	s_waitcnt lgkmcnt(0)
	v_add_f32_e32 v102, v102, v103
	ds_bpermute_b32 v103, v120, v102
	s_and_saveexec_b64 s[62:63], s[4:5]
	s_cbranch_execz .LBB0_777
	s_waitcnt lgkmcnt(0)
	v_add_f32_e32 v104, v102, v103
	v_lshl_add_u64 v[102:103], v[118:119], 2, s[18:19]
	global_atomic_add_f32 v[102:103], v104, off
.LBB0_777:
	s_or_b64 exec, exec, s[62:63]
	v_or_b32_e32 v108, 32, v144
	v_add_u32_e32 v102, s40, v108
	s_waitcnt lgkmcnt(0)
	v_ashrrev_i32_e32 v103, 31, v102
	v_add_u32_e32 v104, 0xffff0000, v102
	v_cmp_gt_i32_e32 vcc, s25, v102
	v_mov_b32_e32 v106, s11
	v_mov_b32_e32 v107, s9
	v_cndmask_b32_e32 v105, 0, v103, vcc
	v_cndmask_b32_e32 v104, v104, v102, vcc
	v_cndmask_b32_e32 v107, v106, v107, vcc
	v_mov_b32_e32 v106, s10
	v_mov_b32_e32 v109, s8
	v_cndmask_b32_e32 v106, v106, v109, vcc
	v_lshlrev_b64 v[104:105], 12, v[104:105]
	v_lshl_add_u64 v[104:105], v[106:107], 0, v[104:105]
	v_lshl_add_u64 v[110:111], v[142:143], 2, v[104:105]
	v_ashrrev_i32_e32 v109, 31, v108
	v_lshlrev_b64 v[108:109], 11, v[108:109]
	v_lshl_add_u64 v[108:109], s[14:15], 0, v[108:109]
	v_lshl_add_u64 v[108:109], v[142:143], 1, v[108:109]
	s_waitcnt vmcnt(21)
	v_mov_b32_e32 v104, v232
	v_mov_b32_e32 v105, v233
	v_mov_b32_e32 v106, v234
	v_mov_b32_e32 v107, v235
	v_pk_add_f32 v[106:107], v[100:101], v[106:107]
	v_pk_add_f32 v[104:105], v[98:99], v[104:105]
	s_nop 0
	v_cvt_pk_bf16_f32 v98, v104, v105
	v_cvt_pk_bf16_f32 v99, v106, v107
	global_store_dwordx2 v[108:109], v[98:99], off
	v_mul_f32_e32 v105, v105, v105
	v_mul_f32_e32 v107, v107, v107
	v_fmac_f32_e32 v105, v104, v104
	v_fmac_f32_e32 v107, v106, v106
	v_add_f32_e32 v104, v105, v107
	s_waitcnt vmcnt(21)
	v_mov_b32_e32 v98, v236
	v_mov_b32_e32 v99, v237
	v_mov_b32_e32 v100, v238
	v_mov_b32_e32 v101, v239
	v_pk_add_f32 v[100:101], v[96:97], v[100:101]
	v_pk_add_f32 v[98:99], v[94:95], v[98:99]
	s_nop 0
	v_cvt_pk_bf16_f32 v94, v98, v99
	v_cvt_pk_bf16_f32 v95, v100, v101
	global_store_dwordx2 v[108:109], v[94:95], off offset:32
	v_mul_f32_e32 v99, v99, v99
	v_mul_f32_e32 v101, v101, v101
	v_fmac_f32_e32 v99, v98, v98
	v_fmac_f32_e32 v101, v100, v100
	v_add_f32_e32 v98, v99, v101
	v_add_f32_e32 v98, v104, v98
	s_waitcnt vmcnt(21)
	v_mov_b32_e32 v94, v240
	v_mov_b32_e32 v95, v241
	v_mov_b32_e32 v96, v242
	v_mov_b32_e32 v97, v243
	v_pk_add_f32 v[96:97], v[92:93], v[96:97]
	v_pk_add_f32 v[94:95], v[90:91], v[94:95]
	s_nop 0
	v_cvt_pk_bf16_f32 v90, v94, v95
	v_cvt_pk_bf16_f32 v91, v96, v97
	global_store_dwordx2 v[108:109], v[90:91], off offset:256
	v_mul_f32_e32 v95, v95, v95
	v_mul_f32_e32 v97, v97, v97
	v_fmac_f32_e32 v95, v94, v94
	v_fmac_f32_e32 v97, v96, v96
	v_add_f32_e32 v94, v95, v97
	v_add_f32_e32 v94, v98, v94
	s_waitcnt vmcnt(21)
	v_mov_b32_e32 v90, v244
	v_mov_b32_e32 v91, v245
	v_mov_b32_e32 v92, v246
	v_mov_b32_e32 v93, v247
	s_mov_b32 s76, 0x90000
	v_lshl_add_u64 v[250:251], v[252:253], 0, s[76:77]
	global_load_dwordx4 v[232:235], v[250:251], off
	global_load_dwordx4 v[236:239], v[250:251], off offset:64
	global_load_dwordx4 v[240:243], v[250:251], off offset:512
	global_load_dwordx4 v[244:247], v[250:251], off offset:576
	v_pk_add_f32 v[88:89], v[88:89], v[92:93]
	v_pk_add_f32 v[90:91], v[86:87], v[90:91]
	v_mul_f32_e32 v87, v89, v89
	v_mul_f32_e32 v86, v91, v91
	v_fmac_f32_e32 v86, v90, v90
	v_fmac_f32_e32 v87, v88, v88
	v_add_f32_e32 v86, v86, v87
	v_add_f32_e32 v86, v94, v86
	ds_bpermute_b32 v87, v122, v86
	v_cvt_pk_bf16_f32 v90, v90, v91
	v_cvt_pk_bf16_f32 v91, v88, v89
	global_store_dwordx2 v[108:109], v[90:91], off offset:288
	s_waitcnt lgkmcnt(0)
	v_add_f32_e32 v86, v86, v87
	ds_bpermute_b32 v87, v120, v86
	s_and_saveexec_b64 s[62:63], s[4:5]
	s_cbranch_execz .LBB0_779
; __device__ __forceinline__ unsigned cvt_pk_bf16(float lo, float hi) { unsigned r; asm volatile("v_cvt_pk_bf16_f32 %0, %1, %2" : "=v"(r) : "v"(lo), "v"(hi)); return r; }
;     __device__ __forceinline__ void operator()(const f32x4 (&acc)[2][2][4][2], const Unit& u, int wr, int wc, int fr, int fq) const {
;         const int row0 = u.pm * BM + wr * 64 + fr, col0 = u.pn * BM + wc * 32 + 4 * fq;
; #pragma unroll
;         for (int ai = 0; ai < 2; ++ai)
; #pragma unroll
;             for (int m = 0; m < 4; ++m) { const int lrow = row0 + ai * HALF + m * 16; const int grow = grow0 + lrow;
;                 const float* xr = (grow < 65536) ? xp + (size_t)grow * 1024 : xs + (size_t)(grow - 65536) * 1024;
;                 bf16_t* brow = XB + (size_t)lrow * 1024; float ss = 0.f;
; #pragma unroll
;                 for (int bj = 0; bj < 2; ++bj)
; #pragma unroll
;                     for (int n = 0; n < 2; ++n) { const int c = col0 + bj * HALF + n * 16; const f32x4 xv = *(const f32x4*)(xr + c); const f32x4 o = xv + acc[ai][bj][m][n];
;                         ss += (o[0] * o[0] + o[1] * o[1]) + (o[2] * o[2] + o[3] * o[3]);
;                         u32x2 w; w.x = cvt_pk_bf16(o[0], o[1]); w.y = cvt_pk_bf16(o[2], o[3]); *(u32x2*)(brow + c) = w; }
;                 ss += __shfl_xor(ss, 16); ss += __shfl_xor(ss, 32);
;                 if (fq == 0) atomicAdd(SS + grow, ss); }
	s_waitcnt lgkmcnt(0)
	v_add_f32_e32 v88, v86, v87
	v_lshl_add_u64 v[86:87], v[102:103], 2, s[18:19]
	global_atomic_add_f32 v[86:87], v88, off
.LBB0_779:
	s_or_b64 exec, exec, s[62:63]
	v_or_b32_e32 v92, 48, v144
	v_add_u32_e32 v86, s40, v92
	s_waitcnt lgkmcnt(0)
	v_ashrrev_i32_e32 v87, 31, v86
	v_add_u32_e32 v88, 0xffff0000, v86
	v_cmp_gt_i32_e32 vcc, s25, v86
	v_mov_b32_e32 v90, s11
	v_mov_b32_e32 v91, s9
	v_cndmask_b32_e32 v89, 0, v87, vcc
	v_cndmask_b32_e32 v88, v88, v86, vcc
	v_cndmask_b32_e32 v91, v90, v91, vcc
	v_mov_b32_e32 v90, s10
	v_mov_b32_e32 v93, s8
	v_cndmask_b32_e32 v90, v90, v93, vcc
	v_lshlrev_b64 v[88:89], 12, v[88:89]
	v_lshl_add_u64 v[88:89], v[90:91], 0, v[88:89]
	v_lshl_add_u64 v[94:95], v[142:143], 2, v[88:89]
	v_ashrrev_i32_e32 v93, 31, v92
	v_lshlrev_b64 v[92:93], 11, v[92:93]
	v_lshl_add_u64 v[92:93], s[14:15], 0, v[92:93]
	v_lshl_add_u64 v[92:93], v[142:143], 1, v[92:93]
	s_waitcnt vmcnt(23)
	v_mov_b32_e32 v88, v200
	v_mov_b32_e32 v89, v201
	v_mov_b32_e32 v90, v202
	v_mov_b32_e32 v91, v203
	v_pk_add_f32 v[90:91], v[80:81], v[90:91]
	v_pk_add_f32 v[88:89], v[78:79], v[88:89]
	s_nop 0
	v_cvt_pk_bf16_f32 v78, v88, v89
	v_cvt_pk_bf16_f32 v79, v90, v91
	global_store_dwordx2 v[92:93], v[78:79], off
	v_mul_f32_e32 v89, v89, v89
	v_mul_f32_e32 v91, v91, v91
	v_fmac_f32_e32 v89, v88, v88
	v_fmac_f32_e32 v91, v90, v90
	v_add_f32_e32 v88, v89, v91
	s_waitcnt vmcnt(23)
	v_mov_b32_e32 v78, v204
	v_mov_b32_e32 v79, v205
	v_mov_b32_e32 v80, v206
	v_mov_b32_e32 v81, v207
	v_pk_add_f32 v[80:81], v[76:77], v[80:81]
	v_pk_add_f32 v[78:79], v[74:75], v[78:79]
	s_nop 0
	v_cvt_pk_bf16_f32 v74, v78, v79
	v_cvt_pk_bf16_f32 v75, v80, v81
	global_store_dwordx2 v[92:93], v[74:75], off offset:32
	v_mul_f32_e32 v79, v79, v79
	v_mul_f32_e32 v81, v81, v81
	v_fmac_f32_e32 v79, v78, v78
	v_fmac_f32_e32 v81, v80, v80
	v_add_f32_e32 v78, v79, v81
	v_add_f32_e32 v78, v88, v78
	s_waitcnt vmcnt(23)
	v_mov_b32_e32 v74, v208
	v_mov_b32_e32 v75, v209
	v_mov_b32_e32 v76, v210
	v_mov_b32_e32 v77, v211
	v_pk_add_f32 v[76:77], v[72:73], v[76:77]
	v_pk_add_f32 v[74:75], v[70:71], v[74:75]
	s_nop 0
	v_cvt_pk_bf16_f32 v70, v74, v75
	v_cvt_pk_bf16_f32 v71, v76, v77
	global_store_dwordx2 v[92:93], v[70:71], off offset:256
	v_mul_f32_e32 v75, v75, v75
	v_mul_f32_e32 v77, v77, v77
	v_fmac_f32_e32 v75, v74, v74
	v_fmac_f32_e32 v77, v76, v76
	v_add_f32_e32 v74, v75, v77
	v_add_f32_e32 v74, v78, v74
	s_waitcnt vmcnt(23)
	v_mov_b32_e32 v70, v212
	v_mov_b32_e32 v71, v213
	v_mov_b32_e32 v72, v214
	v_mov_b32_e32 v73, v215
	s_mov_b32 s76, 0xa0000
	v_lshl_add_u64 v[250:251], v[252:253], 0, s[76:77]
	global_load_dwordx4 v[200:203], v[250:251], off
	global_load_dwordx4 v[204:207], v[250:251], off offset:64
	global_load_dwordx4 v[208:211], v[250:251], off offset:512
	global_load_dwordx4 v[212:215], v[250:251], off offset:576
	v_pk_add_f32 v[68:69], v[68:69], v[72:73]
	v_pk_add_f32 v[70:71], v[66:67], v[70:71]
	v_mul_f32_e32 v67, v69, v69
	v_mul_f32_e32 v66, v71, v71
	v_fmac_f32_e32 v66, v70, v70
	v_fmac_f32_e32 v67, v68, v68
	v_add_f32_e32 v66, v66, v67
	v_add_f32_e32 v66, v74, v66
	ds_bpermute_b32 v67, v122, v66
	v_cvt_pk_bf16_f32 v70, v70, v71
	v_cvt_pk_bf16_f32 v71, v68, v69
	global_store_dwordx2 v[92:93], v[70:71], off offset:288
	s_waitcnt lgkmcnt(0)
	v_add_f32_e32 v66, v66, v67
	ds_bpermute_b32 v67, v120, v66
	s_and_saveexec_b64 s[62:63], s[4:5]
	s_cbranch_execz .LBB0_781
	s_waitcnt lgkmcnt(0)
	v_add_f32_e32 v68, v66, v67
	v_lshl_add_u64 v[66:67], v[86:87], 2, s[18:19]
	global_atomic_add_f32 v[66:67], v68, off
.LBB0_781:
	s_or_b64 exec, exec, s[62:63]
	v_add_u32_e32 v72, 0x80, v144
	v_add_u32_e32 v66, s40, v72
	s_waitcnt lgkmcnt(0)
	v_ashrrev_i32_e32 v67, 31, v66
	v_add_u32_e32 v68, 0xffff0000, v66
	v_cmp_gt_i32_e32 vcc, s25, v66
	v_mov_b32_e32 v70, s11
	v_mov_b32_e32 v71, s9
	v_cndmask_b32_e32 v69, 0, v67, vcc
	v_cndmask_b32_e32 v68, v68, v66, vcc
	v_cndmask_b32_e32 v71, v70, v71, vcc
	v_mov_b32_e32 v70, s10
	v_mov_b32_e32 v73, s8
	v_cndmask_b32_e32 v70, v70, v73, vcc
	v_lshlrev_b64 v[68:69], 12, v[68:69]
	v_lshl_add_u64 v[68:69], v[70:71], 0, v[68:69]
	v_lshl_add_u64 v[74:75], v[142:143], 2, v[68:69]
	v_ashrrev_i32_e32 v73, 31, v72
	v_lshlrev_b64 v[72:73], 11, v[72:73]
	v_lshl_add_u64 v[72:73], s[14:15], 0, v[72:73]
	v_lshl_add_u64 v[72:73], v[142:143], 1, v[72:73]
	s_waitcnt vmcnt(23)
	v_mov_b32_e32 v68, v216
	v_mov_b32_e32 v69, v217
	v_mov_b32_e32 v70, v218
	v_mov_b32_e32 v71, v219
	v_pk_add_f32 v[70:71], v[64:65], v[70:71]
	v_pk_add_f32 v[68:69], v[62:63], v[68:69]
	s_nop 0
	v_cvt_pk_bf16_f32 v62, v68, v69
	v_cvt_pk_bf16_f32 v63, v70, v71
	global_store_dwordx2 v[72:73], v[62:63], off
	v_mul_f32_e32 v69, v69, v69
	v_mul_f32_e32 v71, v71, v71
	v_fmac_f32_e32 v69, v68, v68
	v_fmac_f32_e32 v71, v70, v70
	v_add_f32_e32 v68, v69, v71
	s_waitcnt vmcnt(23)
	v_mov_b32_e32 v62, v220
	v_mov_b32_e32 v63, v221
	v_mov_b32_e32 v64, v222
	v_mov_b32_e32 v65, v223
	v_pk_add_f32 v[64:65], v[60:61], v[64:65]
	v_pk_add_f32 v[62:63], v[58:59], v[62:63]
	s_nop 0
	v_cvt_pk_bf16_f32 v58, v62, v63
	v_cvt_pk_bf16_f32 v59, v64, v65
	global_store_dwordx2 v[72:73], v[58:59], off offset:32
	v_mul_f32_e32 v63, v63, v63
	v_mul_f32_e32 v65, v65, v65
	v_fmac_f32_e32 v63, v62, v62
	v_fmac_f32_e32 v65, v64, v64
	v_add_f32_e32 v62, v63, v65
	v_add_f32_e32 v62, v68, v62
	s_waitcnt vmcnt(23)
	v_mov_b32_e32 v58, v224
	v_mov_b32_e32 v59, v225
	v_mov_b32_e32 v60, v226
	v_mov_b32_e32 v61, v227
	v_pk_add_f32 v[60:61], v[56:57], v[60:61]
	v_pk_add_f32 v[58:59], v[54:55], v[58:59]
	s_nop 0
	v_cvt_pk_bf16_f32 v54, v58, v59
	v_cvt_pk_bf16_f32 v55, v60, v61
	global_store_dwordx2 v[72:73], v[54:55], off offset:256
	v_mul_f32_e32 v59, v59, v59
	v_mul_f32_e32 v61, v61, v61
	v_fmac_f32_e32 v59, v58, v58
	v_fmac_f32_e32 v61, v60, v60
	v_add_f32_e32 v58, v59, v61
	v_add_f32_e32 v58, v62, v58
	s_waitcnt vmcnt(23)
	v_mov_b32_e32 v54, v228
	v_mov_b32_e32 v55, v229
	v_mov_b32_e32 v56, v230
	v_mov_b32_e32 v57, v231
	s_mov_b32 s76, 0xb0000
	v_lshl_add_u64 v[250:251], v[252:253], 0, s[76:77]
	global_load_dwordx4 v[216:219], v[250:251], off
	global_load_dwordx4 v[220:223], v[250:251], off offset:64
	global_load_dwordx4 v[224:227], v[250:251], off offset:512
	global_load_dwordx4 v[228:231], v[250:251], off offset:576
	v_pk_add_f32 v[52:53], v[52:53], v[56:57]
	v_pk_add_f32 v[54:55], v[50:51], v[54:55]
	v_mul_f32_e32 v51, v53, v53
	v_mul_f32_e32 v50, v55, v55
	v_fmac_f32_e32 v50, v54, v54
	v_fmac_f32_e32 v51, v52, v52
	v_add_f32_e32 v50, v50, v51
	v_add_f32_e32 v50, v58, v50
	ds_bpermute_b32 v51, v122, v50
	v_cvt_pk_bf16_f32 v54, v54, v55
	v_cvt_pk_bf16_f32 v55, v52, v53
	global_store_dwordx2 v[72:73], v[54:55], off offset:288
	s_waitcnt lgkmcnt(0)
	v_add_f32_e32 v50, v50, v51
	ds_bpermute_b32 v51, v120, v50
	s_and_saveexec_b64 s[62:63], s[4:5]
	s_cbranch_execz .LBB0_783
	s_waitcnt lgkmcnt(0)
	v_add_f32_e32 v52, v50, v51
	v_lshl_add_u64 v[50:51], v[66:67], 2, s[18:19]
	global_atomic_add_f32 v[50:51], v52, off
; __device__ __forceinline__ unsigned cvt_pk_bf16(float lo, float hi) { unsigned r; asm volatile("v_cvt_pk_bf16_f32 %0, %1, %2" : "=v"(r) : "v"(lo), "v"(hi)); return r; }
;     __device__ __forceinline__ void operator()(const f32x4 (&acc)[2][2][4][2], const Unit& u, int wr, int wc, int fr, int fq) const {
;         const int row0 = u.pm * BM + wr * 64 + fr, col0 = u.pn * BM + wc * 32 + 4 * fq;
; #pragma unroll
;         for (int ai = 0; ai < 2; ++ai)
; #pragma unroll
;             for (int m = 0; m < 4; ++m) { const int lrow = row0 + ai * HALF + m * 16; const int grow = grow0 + lrow;
;                 const float* xr = (grow < 65536) ? xp + (size_t)grow * 1024 : xs + (size_t)(grow - 65536) * 1024;
;                 bf16_t* brow = XB + (size_t)lrow * 1024; float ss = 0.f;
; #pragma unroll
;                 for (int bj = 0; bj < 2; ++bj)
; #pragma unroll
;                     for (int n = 0; n < 2; ++n) { const int c = col0 + bj * HALF + n * 16; const f32x4 xv = *(const f32x4*)(xr + c); const f32x4 o = xv + acc[ai][bj][m][n];
;                         ss += (o[0] * o[0] + o[1] * o[1]) + (o[2] * o[2] + o[3] * o[3]);
;                         u32x2 w; w.x = cvt_pk_bf16(o[0], o[1]); w.y = cvt_pk_bf16(o[2], o[3]); *(u32x2*)(brow + c) = w; }
;                 ss += __shfl_xor(ss, 16); ss += __shfl_xor(ss, 32);
;                 if (fq == 0) atomicAdd(SS + grow, ss); }
.LBB0_783:
	s_or_b64 exec, exec, s[62:63]
	v_add_u32_e32 v56, 0x90, v144
	v_add_u32_e32 v50, s40, v56
	s_waitcnt lgkmcnt(0)
	v_ashrrev_i32_e32 v51, 31, v50
	v_add_u32_e32 v52, 0xffff0000, v50
	v_cmp_gt_i32_e32 vcc, s25, v50
	v_mov_b32_e32 v54, s11
	v_mov_b32_e32 v55, s9
	v_cndmask_b32_e32 v53, 0, v51, vcc
	v_cndmask_b32_e32 v52, v52, v50, vcc
	v_cndmask_b32_e32 v55, v54, v55, vcc
	v_mov_b32_e32 v54, s10
	v_mov_b32_e32 v57, s8
	v_cndmask_b32_e32 v54, v54, v57, vcc
	v_lshlrev_b64 v[52:53], 12, v[52:53]
	v_lshl_add_u64 v[52:53], v[54:55], 0, v[52:53]
	v_lshl_add_u64 v[58:59], v[142:143], 2, v[52:53]
	v_ashrrev_i32_e32 v57, 31, v56
	v_lshlrev_b64 v[56:57], 11, v[56:57]
	v_lshl_add_u64 v[56:57], s[14:15], 0, v[56:57]
	v_lshl_add_u64 v[56:57], v[142:143], 1, v[56:57]
	s_waitcnt vmcnt(23)
	v_mov_b32_e32 v52, v232
	v_mov_b32_e32 v53, v233
	v_mov_b32_e32 v54, v234
	v_mov_b32_e32 v55, v235
	v_pk_add_f32 v[54:55], v[48:49], v[54:55]
	v_pk_add_f32 v[52:53], v[46:47], v[52:53]
	s_nop 0
	v_cvt_pk_bf16_f32 v46, v52, v53
	v_cvt_pk_bf16_f32 v47, v54, v55
	global_store_dwordx2 v[56:57], v[46:47], off
	v_mul_f32_e32 v53, v53, v53
	v_mul_f32_e32 v55, v55, v55
	v_fmac_f32_e32 v53, v52, v52
	v_fmac_f32_e32 v55, v54, v54
	v_add_f32_e32 v52, v53, v55
	s_waitcnt vmcnt(23)
	v_mov_b32_e32 v46, v236
	v_mov_b32_e32 v47, v237
	v_mov_b32_e32 v48, v238
	v_mov_b32_e32 v49, v239
	v_pk_add_f32 v[48:49], v[44:45], v[48:49]
	v_pk_add_f32 v[46:47], v[42:43], v[46:47]
	s_nop 0
	v_cvt_pk_bf16_f32 v42, v46, v47
	v_cvt_pk_bf16_f32 v43, v48, v49
	global_store_dwordx2 v[56:57], v[42:43], off offset:32
	v_mul_f32_e32 v47, v47, v47
	v_mul_f32_e32 v49, v49, v49
	v_fmac_f32_e32 v47, v46, v46
	v_fmac_f32_e32 v49, v48, v48
	v_add_f32_e32 v46, v47, v49
	v_add_f32_e32 v46, v52, v46
	s_waitcnt vmcnt(23)
	v_mov_b32_e32 v42, v240
	v_mov_b32_e32 v43, v241
	v_mov_b32_e32 v44, v242
	v_mov_b32_e32 v45, v243
	v_pk_add_f32 v[44:45], v[40:41], v[44:45]
	v_pk_add_f32 v[42:43], v[38:39], v[42:43]
	s_nop 0
	v_cvt_pk_bf16_f32 v38, v42, v43
	v_cvt_pk_bf16_f32 v39, v44, v45
	global_store_dwordx2 v[56:57], v[38:39], off offset:256
	v_mul_f32_e32 v43, v43, v43
	v_mul_f32_e32 v45, v45, v45
	v_fmac_f32_e32 v43, v42, v42
	v_fmac_f32_e32 v45, v44, v44
	v_add_f32_e32 v42, v43, v45
	v_add_f32_e32 v42, v46, v42
	s_waitcnt vmcnt(23)
	v_mov_b32_e32 v38, v244
	v_mov_b32_e32 v39, v245
	v_mov_b32_e32 v40, v246
	v_mov_b32_e32 v41, v247
	v_pk_add_f32 v[36:37], v[36:37], v[40:41]
	v_pk_add_f32 v[38:39], v[34:35], v[38:39]
	v_mul_f32_e32 v35, v37, v37
	v_mul_f32_e32 v34, v39, v39
	v_fmac_f32_e32 v34, v38, v38
	v_fmac_f32_e32 v35, v36, v36
	v_add_f32_e32 v34, v34, v35
	v_add_f32_e32 v34, v42, v34
	ds_bpermute_b32 v35, v122, v34
	v_cvt_pk_bf16_f32 v38, v38, v39
	v_cvt_pk_bf16_f32 v39, v36, v37
	global_store_dwordx2 v[56:57], v[38:39], off offset:288
	s_waitcnt lgkmcnt(0)
	v_add_f32_e32 v34, v34, v35
	ds_bpermute_b32 v35, v120, v34
	s_and_saveexec_b64 s[62:63], s[4:5]
	s_cbranch_execz .LBB0_785
	s_waitcnt lgkmcnt(0)
	v_add_f32_e32 v36, v34, v35
	v_lshl_add_u64 v[34:35], v[50:51], 2, s[18:19]
	global_atomic_add_f32 v[34:35], v36, off
; __device__ __forceinline__ unsigned cvt_pk_bf16(float lo, float hi) { unsigned r; asm volatile("v_cvt_pk_bf16_f32 %0, %1, %2" : "=v"(r) : "v"(lo), "v"(hi)); return r; }
;     __device__ __forceinline__ void operator()(const f32x4 (&acc)[2][2][4][2], const Unit& u, int wr, int wc, int fr, int fq) const {
;         const int row0 = u.pm * BM + wr * 64 + fr, col0 = u.pn * BM + wc * 32 + 4 * fq;
; #pragma unroll
;         for (int ai = 0; ai < 2; ++ai)
; #pragma unroll
;             for (int m = 0; m < 4; ++m) { const int lrow = row0 + ai * HALF + m * 16; const int grow = grow0 + lrow;
;                 const float* xr = (grow < 65536) ? xp + (size_t)grow * 1024 : xs + (size_t)(grow - 65536) * 1024;
;                 bf16_t* brow = XB + (size_t)lrow * 1024; float ss = 0.f;
; #pragma unroll
;                 for (int bj = 0; bj < 2; ++bj)
; #pragma unroll
;                     for (int n = 0; n < 2; ++n) { const int c = col0 + bj * HALF + n * 16; const f32x4 xv = *(const f32x4*)(xr + c); const f32x4 o = xv + acc[ai][bj][m][n];
;                         ss += (o[0] * o[0] + o[1] * o[1]) + (o[2] * o[2] + o[3] * o[3]);
;                         u32x2 w; w.x = cvt_pk_bf16(o[0], o[1]); w.y = cvt_pk_bf16(o[2], o[3]); *(u32x2*)(brow + c) = w; }
;                 ss += __shfl_xor(ss, 16); ss += __shfl_xor(ss, 32);
;                 if (fq == 0) atomicAdd(SS + grow, ss); }
.LBB0_785:
	s_or_b64 exec, exec, s[62:63]
	v_add_u32_e32 v40, 0xa0, v144
	v_add_u32_e32 v34, s40, v40
	s_waitcnt lgkmcnt(0)
	v_ashrrev_i32_e32 v35, 31, v34
	v_add_u32_e32 v36, 0xffff0000, v34
	v_cmp_gt_i32_e32 vcc, s25, v34
	v_mov_b32_e32 v38, s11
	v_mov_b32_e32 v39, s9
	v_cndmask_b32_e32 v37, 0, v35, vcc
	v_cndmask_b32_e32 v36, v36, v34, vcc
	v_cndmask_b32_e32 v39, v38, v39, vcc
	v_mov_b32_e32 v38, s10
	v_mov_b32_e32 v41, s8
	v_cndmask_b32_e32 v38, v38, v41, vcc
	v_lshlrev_b64 v[36:37], 12, v[36:37]
	v_lshl_add_u64 v[36:37], v[38:39], 0, v[36:37]
	v_lshl_add_u64 v[42:43], v[142:143], 2, v[36:37]
	v_ashrrev_i32_e32 v41, 31, v40
	v_lshlrev_b64 v[40:41], 11, v[40:41]
	v_lshl_add_u64 v[40:41], s[14:15], 0, v[40:41]
	v_lshl_add_u64 v[40:41], v[142:143], 1, v[40:41]
	s_waitcnt vmcnt(19)
	v_mov_b32_e32 v36, v200
	v_mov_b32_e32 v37, v201
	v_mov_b32_e32 v38, v202
	v_mov_b32_e32 v39, v203
	v_pk_add_f32 v[38:39], v[32:33], v[38:39]
	v_pk_add_f32 v[36:37], v[30:31], v[36:37]
	s_nop 0
	v_cvt_pk_bf16_f32 v30, v36, v37
	v_cvt_pk_bf16_f32 v31, v38, v39
	global_store_dwordx2 v[40:41], v[30:31], off
	v_mul_f32_e32 v37, v37, v37
	v_mul_f32_e32 v39, v39, v39
	v_fmac_f32_e32 v37, v36, v36
	v_fmac_f32_e32 v39, v38, v38
	v_add_f32_e32 v36, v37, v39
	s_waitcnt vmcnt(19)
	v_mov_b32_e32 v30, v204
	v_mov_b32_e32 v31, v205
	v_mov_b32_e32 v32, v206
	v_mov_b32_e32 v33, v207
	v_pk_add_f32 v[32:33], v[28:29], v[32:33]
	v_pk_add_f32 v[30:31], v[26:27], v[30:31]
	s_nop 0
	v_cvt_pk_bf16_f32 v26, v30, v31
	v_cvt_pk_bf16_f32 v27, v32, v33
	global_store_dwordx2 v[40:41], v[26:27], off offset:32
	v_mul_f32_e32 v31, v31, v31
	v_mul_f32_e32 v33, v33, v33
	v_fmac_f32_e32 v31, v30, v30
	v_fmac_f32_e32 v33, v32, v32
	v_add_f32_e32 v30, v31, v33
	v_add_f32_e32 v30, v36, v30
	s_waitcnt vmcnt(19)
	v_mov_b32_e32 v26, v208
	v_mov_b32_e32 v27, v209
	v_mov_b32_e32 v28, v210
	v_mov_b32_e32 v29, v211
	v_pk_add_f32 v[28:29], v[24:25], v[28:29]
	v_pk_add_f32 v[26:27], v[22:23], v[26:27]
	s_nop 0
	v_cvt_pk_bf16_f32 v22, v26, v27
	v_cvt_pk_bf16_f32 v23, v28, v29
	global_store_dwordx2 v[40:41], v[22:23], off offset:256
	v_mul_f32_e32 v27, v27, v27
	v_mul_f32_e32 v29, v29, v29
	v_fmac_f32_e32 v27, v26, v26
	v_fmac_f32_e32 v29, v28, v28
	v_add_f32_e32 v26, v27, v29
	v_add_f32_e32 v26, v30, v26
	s_waitcnt vmcnt(19)
	v_mov_b32_e32 v22, v212
	v_mov_b32_e32 v23, v213
	v_mov_b32_e32 v24, v214
	v_mov_b32_e32 v25, v215
	v_pk_add_f32 v[20:21], v[20:21], v[24:25]
	v_pk_add_f32 v[22:23], v[18:19], v[22:23]
	v_mul_f32_e32 v19, v21, v21
	v_mul_f32_e32 v18, v23, v23
	v_fmac_f32_e32 v18, v22, v22
	v_fmac_f32_e32 v19, v20, v20
	v_add_f32_e32 v18, v18, v19
	v_add_f32_e32 v18, v26, v18
	ds_bpermute_b32 v19, v122, v18
	v_cvt_pk_bf16_f32 v22, v22, v23
	v_cvt_pk_bf16_f32 v23, v20, v21
	global_store_dwordx2 v[40:41], v[22:23], off offset:288
	s_waitcnt lgkmcnt(0)
	v_add_f32_e32 v18, v18, v19
	ds_bpermute_b32 v19, v120, v18
	s_and_saveexec_b64 s[62:63], s[4:5]
	s_cbranch_execz .LBB0_787
	s_waitcnt lgkmcnt(0)
	v_add_f32_e32 v20, v18, v19
	v_lshl_add_u64 v[18:19], v[34:35], 2, s[18:19]
	global_atomic_add_f32 v[18:19], v20, off
.LBB0_787:
	s_or_b64 exec, exec, s[62:63]
	v_add_u32_e32 v24, 0xb0, v144
	v_add_u32_e32 v18, s40, v24
	s_waitcnt lgkmcnt(0)
	v_ashrrev_i32_e32 v19, 31, v18
	v_add_u32_e32 v20, 0xffff0000, v18
	v_cmp_gt_i32_e32 vcc, s25, v18
	v_mov_b32_e32 v22, s11
	v_mov_b32_e32 v23, s9
	v_cndmask_b32_e32 v21, 0, v19, vcc
	v_cndmask_b32_e32 v20, v20, v18, vcc
	v_cndmask_b32_e32 v23, v22, v23, vcc
	v_mov_b32_e32 v22, s10
	v_mov_b32_e32 v25, s8
	v_cndmask_b32_e32 v22, v22, v25, vcc
	v_lshlrev_b64 v[20:21], 12, v[20:21]
	v_lshl_add_u64 v[20:21], v[22:23], 0, v[20:21]
	v_lshl_add_u64 v[26:27], v[142:143], 2, v[20:21]
	v_ashrrev_i32_e32 v25, 31, v24
	v_lshlrev_b64 v[24:25], 11, v[24:25]
	v_lshl_add_u64 v[24:25], s[14:15], 0, v[24:25]
	v_lshl_add_u64 v[24:25], v[142:143], 1, v[24:25]
	s_waitcnt vmcnt(15)
	v_mov_b32_e32 v20, v216
	v_mov_b32_e32 v21, v217
	v_mov_b32_e32 v22, v218
	v_mov_b32_e32 v23, v219
	v_pk_add_f32 v[22:23], v[16:17], v[22:23]
	v_pk_add_f32 v[20:21], v[14:15], v[20:21]
	s_nop 0
	v_cvt_pk_bf16_f32 v14, v20, v21
	v_cvt_pk_bf16_f32 v15, v22, v23
	global_store_dwordx2 v[24:25], v[14:15], off
	v_mul_f32_e32 v21, v21, v21
	v_mul_f32_e32 v23, v23, v23
	v_fmac_f32_e32 v21, v20, v20
	v_fmac_f32_e32 v23, v22, v22
	v_add_f32_e32 v20, v21, v23
	s_waitcnt vmcnt(15)
	v_mov_b32_e32 v14, v220
	v_mov_b32_e32 v15, v221
	v_mov_b32_e32 v16, v222
	v_mov_b32_e32 v17, v223
	v_pk_add_f32 v[16:17], v[12:13], v[16:17]
	v_pk_add_f32 v[14:15], v[10:11], v[14:15]
	s_nop 0
	v_cvt_pk_bf16_f32 v10, v14, v15
	v_cvt_pk_bf16_f32 v11, v16, v17
	global_store_dwordx2 v[24:25], v[10:11], off offset:32
	v_mul_f32_e32 v15, v15, v15
	v_mul_f32_e32 v17, v17, v17
	v_fmac_f32_e32 v15, v14, v14
	v_fmac_f32_e32 v17, v16, v16
	v_add_f32_e32 v14, v15, v17
	v_add_f32_e32 v14, v20, v14
	s_waitcnt vmcnt(15)
	v_mov_b32_e32 v10, v224
	v_mov_b32_e32 v11, v225
	v_mov_b32_e32 v12, v226
	v_mov_b32_e32 v13, v227
	v_pk_add_f32 v[12:13], v[8:9], v[12:13]
	v_pk_add_f32 v[10:11], v[6:7], v[10:11]
	s_nop 0
	v_cvt_pk_bf16_f32 v6, v10, v11
	v_cvt_pk_bf16_f32 v7, v12, v13
	global_store_dwordx2 v[24:25], v[6:7], off offset:256
	v_mul_f32_e32 v11, v11, v11
	v_mul_f32_e32 v13, v13, v13
	v_fmac_f32_e32 v11, v10, v10
	v_fmac_f32_e32 v13, v12, v12
	v_add_f32_e32 v10, v11, v13
	v_add_f32_e32 v10, v14, v10
	s_waitcnt vmcnt(15)
	v_mov_b32_e32 v6, v228
	v_mov_b32_e32 v7, v229
	v_mov_b32_e32 v8, v230
	v_mov_b32_e32 v9, v231
	v_pk_add_f32 v[4:5], v[4:5], v[8:9]
	v_pk_add_f32 v[6:7], v[2:3], v[6:7]
	v_mul_f32_e32 v3, v5, v5
	v_mul_f32_e32 v2, v7, v7
	v_fmac_f32_e32 v2, v6, v6
	v_fmac_f32_e32 v3, v4, v4
	v_add_f32_e32 v2, v2, v3
	v_add_f32_e32 v2, v10, v2
	ds_bpermute_b32 v3, v122, v2
	v_cvt_pk_bf16_f32 v6, v6, v7
	v_cvt_pk_bf16_f32 v7, v4, v5
	global_store_dwordx2 v[24:25], v[6:7], off offset:288
	s_waitcnt lgkmcnt(0)
	v_add_f32_e32 v2, v2, v3
	ds_bpermute_b32 v3, v120, v2
	s_and_saveexec_b64 s[62:63], s[4:5]
	s_cbranch_execz .LBB0_789
	s_waitcnt lgkmcnt(0)
	v_add_f32_e32 v4, v2, v3
	v_lshl_add_u64 v[2:3], v[18:19], 2, s[18:19]
	global_atomic_add_f32 v[2:3], v4, off

; __device__ __forceinline__ float bf_lo(unsigned w) { return __uint_as_float(w << 16); }
; __device__ __forceinline__ float bf_hi(unsigned w) { return __uint_as_float(w & 0xffff0000u); }
;     __device__ __forceinline__ void operator()(const f32x4 (&acc)[2][2][4][2], const Unit& u, int wr, int wc, int fr, int fq) const {
;         const int row0 = u.pm * BM + wr * 64 + fr, col0 = u.pn * BM + wc * 32 + 4 * fq;
; #pragma unroll
;         for (int ai = 0; ai < 2; ++ai)
; #pragma unroll
;             for (int m = 0; m < 4; ++m) { const int lrow = row0 + ai * HALF + m * 16; float* orow = OUT + (size_t)(grow0 + lrow) * 1024; const bf16_t* brow = XB + (size_t)lrow * 1024;
; #pragma unroll
;                 for (int bj = 0; bj < 2; ++bj)
; #pragma unroll
;                     for (int n = 0; n < 2; ++n) { const int c = col0 + bj * HALF + n * 16; const u32x2 xw = *(const u32x2*)(brow + c);
;                         const f32x4 xv = (f32x4){bf_lo(xw.x), bf_hi(xw.x), bf_lo(xw.y), bf_hi(xw.y)}; *(f32x4*)(orow + c) = xv + acc[ai][bj][m][n]; } }
.LBB0_1038:
	v_lshl_add_u32 v144, s60, 8, v1
	v_lshl_or_b32 v142, s56, 8, v149
	v_ashrrev_i32_e32 v145, 31, v144
	v_lshlrev_b64 v[146:147], 11, v[144:145]
	v_ashrrev_i32_e32 v143, 31, v142
	v_lshl_add_u64 v[152:153], s[14:15], 0, v[146:147]
	v_lshlrev_b64 v[146:147], 1, v[142:143]
	v_lshl_add_u64 v[152:153], v[152:153], 0, v[146:147]
	v_mov_b32_e32 v252, v152
	v_mov_b32_e32 v253, v153
	s_mov_b32 s77, 0
	global_load_dwordx2 v[200:201], v[252:253], off
	global_load_dwordx2 v[202:203], v[252:253], off offset:32
	global_load_dwordx2 v[204:205], v[252:253], off offset:256
	global_load_dwordx2 v[206:207], v[252:253], off offset:288
	s_mov_b32 s76, 0x8000
	v_lshl_add_u64 v[250:251], v[252:253], 0, s[76:77]
	global_load_dwordx2 v[208:209], v[250:251], off
	global_load_dwordx2 v[210:211], v[250:251], off offset:32
	global_load_dwordx2 v[212:213], v[250:251], off offset:256
	global_load_dwordx2 v[214:215], v[250:251], off offset:288
	s_mov_b32 s76, 0x10000
	v_lshl_add_u64 v[250:251], v[252:253], 0, s[76:77]
	global_load_dwordx2 v[216:217], v[250:251], off
	global_load_dwordx2 v[218:219], v[250:251], off offset:32
	global_load_dwordx2 v[220:221], v[250:251], off offset:256
	global_load_dwordx2 v[222:223], v[250:251], off offset:288
	s_mov_b32 s76, 0x18000
	v_lshl_add_u64 v[250:251], v[252:253], 0, s[76:77]
	global_load_dwordx2 v[224:225], v[250:251], off
	global_load_dwordx2 v[226:227], v[250:251], off offset:32
	global_load_dwordx2 v[228:229], v[250:251], off offset:256
	global_load_dwordx2 v[230:231], v[250:251], off offset:288
	s_mov_b32 s76, 0x40000
	v_lshl_add_u64 v[250:251], v[252:253], 0, s[76:77]
	global_load_dwordx2 v[232:233], v[250:251], off
	global_load_dwordx2 v[234:235], v[250:251], off offset:32
	global_load_dwordx2 v[236:237], v[250:251], off offset:256
	global_load_dwordx2 v[238:239], v[250:251], off offset:288
	s_mov_b32 s76, 0x48000
	v_lshl_add_u64 v[250:251], v[252:253], 0, s[76:77]
	global_load_dwordx2 v[240:241], v[250:251], off
	global_load_dwordx2 v[242:243], v[250:251], off offset:32
	global_load_dwordx2 v[244:245], v[250:251], off offset:256
	global_load_dwordx2 v[246:247], v[250:251], off offset:288
	v_add_u32_e32 v156, s48, v144
	v_ashrrev_i32_e32 v157, 31, v156
	v_lshlrev_b64 v[156:157], 12, v[156:157]
	v_lshlrev_b64 v[142:143], 2, v[142:143]
	v_lshl_add_u64 v[156:157], s[8:9], 0, v[156:157]
	v_lshl_add_u64 v[156:157], v[156:157], 0, v[142:143]
	s_and_b64 vcc, exec, s[4:5]
	s_mov_b64 s[4:5], -1
	s_waitcnt vmcnt(23)
	s_nop 1
	v_mov_b32_e32 v154, v200
	v_mov_b32_e32 v155, v201
	v_lshlrev_b32_e32 v158, 16, v154
	v_and_b32_e32 v159, 0xffff0000, v154
	v_lshlrev_b32_e32 v154, 16, v155
	v_and_b32_e32 v155, 0xffff0000, v155
	v_pk_add_f32 v[132:133], v[132:133], v[154:155]
	v_pk_add_f32 v[130:131], v[130:131], v[158:159]
	global_store_dwordx4 v[156:157], v[130:133], off
	s_waitcnt vmcnt(23)
	s_nop 1
	v_mov_b32_e32 v130, v202
	v_mov_b32_e32 v131, v203
	v_lshlrev_b32_e32 v132, 16, v130
	v_and_b32_e32 v133, 0xffff0000, v130
	v_lshlrev_b32_e32 v130, 16, v131
	v_and_b32_e32 v131, 0xffff0000, v131
	v_pk_add_f32 v[128:129], v[128:129], v[130:131]
	v_pk_add_f32 v[126:127], v[126:127], v[132:133]
	global_store_dwordx4 v[156:157], v[126:129], off offset:64
	s_waitcnt vmcnt(23)
	s_nop 1
	v_mov_b32_e32 v126, v204
	v_mov_b32_e32 v127, v205
	v_lshlrev_b32_e32 v128, 16, v126
	v_and_b32_e32 v129, 0xffff0000, v126
	v_lshlrev_b32_e32 v126, 16, v127
	v_and_b32_e32 v127, 0xffff0000, v127
	v_pk_add_f32 v[124:125], v[124:125], v[126:127]
	v_pk_add_f32 v[122:123], v[122:123], v[128:129]
	global_store_dwordx4 v[156:157], v[122:125], off offset:512
	s_waitcnt vmcnt(23)
	s_nop 1
	v_mov_b32_e32 v122, v206
	v_mov_b32_e32 v123, v207
	s_mov_b32 s76, 0x50000
	v_lshl_add_u64 v[250:251], v[252:253], 0, s[76:77]
	global_load_dwordx2 v[200:201], v[250:251], off
	global_load_dwordx2 v[202:203], v[250:251], off offset:32
	global_load_dwordx2 v[204:205], v[250:251], off offset:256
	global_load_dwordx2 v[206:207], v[250:251], off offset:288
	v_lshlrev_b32_e32 v128, 16, v122
	v_or_b32_e32 v124, 16, v144
	v_ashrrev_i32_e32 v125, 31, v124
	v_lshlrev_b64 v[126:127], 11, v[124:125]
	v_and_b32_e32 v129, 0xffff0000, v122
	v_lshlrev_b32_e32 v122, 16, v123
	v_and_b32_e32 v123, 0xffff0000, v123
	v_lshl_add_u64 v[126:127], s[14:15], 0, v[126:127]
	v_pk_add_f32 v[116:117], v[116:117], v[122:123]
	v_pk_add_f32 v[114:115], v[114:115], v[128:129]
	v_lshl_add_u64 v[126:127], v[126:127], 0, v[146:147]
	global_store_dwordx4 v[156:157], v[114:117], off offset:576
	s_waitcnt vmcnt(27)
	s_nop 1
	v_mov_b32_e32 v114, v208
	v_mov_b32_e32 v115, v209
	v_and_b32_e32 v125, 0xffff0000, v114
	v_add_u32_e32 v116, s48, v124
	v_ashrrev_i32_e32 v117, 31, v116
	v_lshlrev_b64 v[116:117], 12, v[116:117]
	v_lshl_add_u64 v[116:117], s[8:9], 0, v[116:117]
	v_lshlrev_b32_e32 v124, 16, v114
	v_lshlrev_b32_e32 v114, 16, v115
	v_and_b32_e32 v115, 0xffff0000, v115
	v_lshl_add_u64 v[122:123], v[116:117], 0, v[142:143]
	v_pk_add_f32 v[116:117], v[120:121], v[114:115]
	v_pk_add_f32 v[114:115], v[118:119], v[124:125]
	global_store_dwordx4 v[122:123], v[114:117], off
	s_waitcnt vmcnt(27)
	s_nop 1
	v_mov_b32_e32 v114, v210
	v_mov_b32_e32 v115, v211
	v_lshlrev_b32_e32 v116, 16, v114
	v_and_b32_e32 v117, 0xffff0000, v114
	v_lshlrev_b32_e32 v114, 16, v115
	v_and_b32_e32 v115, 0xffff0000, v115
	v_pk_add_f32 v[112:113], v[112:113], v[114:115]
	v_pk_add_f32 v[110:111], v[110:111], v[116:117]
	global_store_dwordx4 v[122:123], v[110:113], off offset:64
	s_waitcnt vmcnt(27)
; __device__ __forceinline__ float bf_lo(unsigned w) { return __uint_as_float(w << 16); }
; __device__ __forceinline__ float bf_hi(unsigned w) { return __uint_as_float(w & 0xffff0000u); }
;     __device__ __forceinline__ void operator()(const f32x4 (&acc)[2][2][4][2], const Unit& u, int wr, int wc, int fr, int fq) const {
;         const int row0 = u.pm * BM + wr * 64 + fr, col0 = u.pn * BM + wc * 32 + 4 * fq;
; #pragma unroll
;         for (int ai = 0; ai < 2; ++ai)
; #pragma unroll
;             for (int m = 0; m < 4; ++m) { const int lrow = row0 + ai * HALF + m * 16; float* orow = OUT + (size_t)(grow0 + lrow) * 1024; const bf16_t* brow = XB + (size_t)lrow * 1024;
; #pragma unroll
;                 for (int bj = 0; bj < 2; ++bj)
; #pragma unroll
;                     for (int n = 0; n < 2; ++n) { const int c = col0 + bj * HALF + n * 16; const u32x2 xw = *(const u32x2*)(brow + c);
;                         const f32x4 xv = (f32x4){bf_lo(xw.x), bf_hi(xw.x), bf_lo(xw.y), bf_hi(xw.y)}; *(f32x4*)(orow + c) = xv + acc[ai][bj][m][n]; } }
	s_nop 1
	v_mov_b32_e32 v110, v212
	v_mov_b32_e32 v111, v213
	v_lshlrev_b32_e32 v112, 16, v110
	v_and_b32_e32 v113, 0xffff0000, v110
	v_lshlrev_b32_e32 v110, 16, v111
	v_and_b32_e32 v111, 0xffff0000, v111
	v_pk_add_f32 v[108:109], v[108:109], v[110:111]
	v_pk_add_f32 v[106:107], v[106:107], v[112:113]
	global_store_dwordx4 v[122:123], v[106:109], off offset:512
	s_waitcnt vmcnt(27)
	s_nop 1
	v_mov_b32_e32 v106, v214
	v_mov_b32_e32 v107, v215
	s_mov_b32 s76, 0x58000
	v_lshl_add_u64 v[250:251], v[252:253], 0, s[76:77]
	global_load_dwordx2 v[208:209], v[250:251], off
	global_load_dwordx2 v[210:211], v[250:251], off offset:32
	global_load_dwordx2 v[212:213], v[250:251], off offset:256
	global_load_dwordx2 v[214:215], v[250:251], off offset:288
	v_lshlrev_b32_e32 v112, 16, v106
	v_or_b32_e32 v108, 32, v144
	v_ashrrev_i32_e32 v109, 31, v108
	v_lshlrev_b64 v[110:111], 11, v[108:109]
	v_and_b32_e32 v113, 0xffff0000, v106
	v_lshlrev_b32_e32 v106, 16, v107
	v_and_b32_e32 v107, 0xffff0000, v107
	v_lshl_add_u64 v[110:111], s[14:15], 0, v[110:111]
	v_pk_add_f32 v[100:101], v[100:101], v[106:107]
	v_pk_add_f32 v[98:99], v[98:99], v[112:113]
	v_lshl_add_u64 v[110:111], v[110:111], 0, v[146:147]
	global_store_dwordx4 v[122:123], v[98:101], off offset:576
	s_waitcnt vmcnt(31)
	s_nop 1
	v_mov_b32_e32 v98, v216
	v_mov_b32_e32 v99, v217
	v_and_b32_e32 v109, 0xffff0000, v98
	v_add_u32_e32 v100, s48, v108
	v_ashrrev_i32_e32 v101, 31, v100
	v_lshlrev_b64 v[100:101], 12, v[100:101]
	v_lshl_add_u64 v[100:101], s[8:9], 0, v[100:101]
	v_lshlrev_b32_e32 v108, 16, v98
	v_lshlrev_b32_e32 v98, 16, v99
	v_and_b32_e32 v99, 0xffff0000, v99
	v_lshl_add_u64 v[106:107], v[100:101], 0, v[142:143]
	v_pk_add_f32 v[100:101], v[104:105], v[98:99]
	v_pk_add_f32 v[98:99], v[102:103], v[108:109]
	global_store_dwordx4 v[106:107], v[98:101], off
	s_waitcnt vmcnt(31)
	s_nop 1
	v_mov_b32_e32 v98, v218
	v_mov_b32_e32 v99, v219
	v_lshlrev_b32_e32 v100, 16, v98
	v_and_b32_e32 v101, 0xffff0000, v98
	v_lshlrev_b32_e32 v98, 16, v99
	v_and_b32_e32 v99, 0xffff0000, v99
	v_pk_add_f32 v[96:97], v[96:97], v[98:99]
	v_pk_add_f32 v[94:95], v[94:95], v[100:101]
	global_store_dwordx4 v[106:107], v[94:97], off offset:64
	s_waitcnt vmcnt(31)
	s_nop 1
	v_mov_b32_e32 v94, v220
	v_mov_b32_e32 v95, v221
	v_lshlrev_b32_e32 v96, 16, v94
	v_and_b32_e32 v97, 0xffff0000, v94
	v_lshlrev_b32_e32 v94, 16, v95
	v_and_b32_e32 v95, 0xffff0000, v95
	v_pk_add_f32 v[92:93], v[92:93], v[94:95]
	v_pk_add_f32 v[90:91], v[90:91], v[96:97]
	global_store_dwordx4 v[106:107], v[90:93], off offset:512
	s_waitcnt vmcnt(31)
	s_nop 1
	v_mov_b32_e32 v90, v222
	v_mov_b32_e32 v91, v223
	v_lshlrev_b32_e32 v96, 16, v90
	v_or_b32_e32 v92, 48, v144
	v_ashrrev_i32_e32 v93, 31, v92
	v_lshlrev_b64 v[94:95], 11, v[92:93]
	v_and_b32_e32 v97, 0xffff0000, v90
	v_lshlrev_b32_e32 v90, 16, v91
	v_and_b32_e32 v91, 0xffff0000, v91
	v_lshl_add_u64 v[94:95], s[14:15], 0, v[94:95]
	v_pk_add_f32 v[80:81], v[80:81], v[90:91]
	v_pk_add_f32 v[78:79], v[78:79], v[96:97]
	v_lshl_add_u64 v[94:95], v[94:95], 0, v[146:147]
	global_store_dwordx4 v[106:107], v[78:81], off offset:576
	s_waitcnt vmcnt(31)
	s_nop 1
	v_mov_b32_e32 v78, v224
	v_mov_b32_e32 v79, v225
	v_and_b32_e32 v93, 0xffff0000, v78
	v_add_u32_e32 v80, s48, v92
	v_ashrrev_i32_e32 v81, 31, v80
	v_lshlrev_b64 v[80:81], 12, v[80:81]
	v_lshl_add_u64 v[80:81], s[8:9], 0, v[80:81]
	v_lshlrev_b32_e32 v92, 16, v78
	v_lshlrev_b32_e32 v78, 16, v79
	v_and_b32_e32 v79, 0xffff0000, v79
	v_lshl_add_u64 v[90:91], v[80:81], 0, v[142:143]
	v_pk_add_f32 v[80:81], v[88:89], v[78:79]
	v_pk_add_f32 v[78:79], v[86:87], v[92:93]
	global_store_dwordx4 v[90:91], v[78:81], off
	s_waitcnt vmcnt(31)
	s_nop 1
	v_mov_b32_e32 v78, v226
	v_mov_b32_e32 v79, v227
	v_lshlrev_b32_e32 v80, 16, v78
	v_and_b32_e32 v81, 0xffff0000, v78
	v_lshlrev_b32_e32 v78, 16, v79
	v_and_b32_e32 v79, 0xffff0000, v79
	v_pk_add_f32 v[76:77], v[76:77], v[78:79]
	v_pk_add_f32 v[74:75], v[74:75], v[80:81]
	global_store_dwordx4 v[90:91], v[74:77], off offset:64
	s_waitcnt vmcnt(31)
	s_nop 1
	v_mov_b32_e32 v74, v228
	v_mov_b32_e32 v75, v229
	v_lshlrev_b32_e32 v76, 16, v74
	v_and_b32_e32 v77, 0xffff0000, v74
	v_lshlrev_b32_e32 v74, 16, v75
	v_and_b32_e32 v75, 0xffff0000, v75
	v_pk_add_f32 v[72:73], v[72:73], v[74:75]
	v_pk_add_f32 v[70:71], v[70:71], v[76:77]
	global_store_dwordx4 v[90:91], v[70:73], off offset:512
	s_waitcnt vmcnt(31)
	s_nop 1
	v_mov_b32_e32 v70, v230
	v_mov_b32_e32 v71, v231
	v_lshlrev_b32_e32 v76, 16, v70
	v_add_u32_e32 v72, 0x80, v144
	v_ashrrev_i32_e32 v73, 31, v72
	v_lshlrev_b64 v[74:75], 11, v[72:73]
	v_and_b32_e32 v77, 0xffff0000, v70
	v_lshlrev_b32_e32 v70, 16, v71
	v_and_b32_e32 v71, 0xffff0000, v71
	v_lshl_add_u64 v[74:75], s[14:15], 0, v[74:75]
	v_pk_add_f32 v[68:69], v[68:69], v[70:71]
	v_pk_add_f32 v[66:67], v[66:67], v[76:77]
	v_lshl_add_u64 v[74:75], v[74:75], 0, v[146:147]
	global_store_dwordx4 v[90:91], v[66:69], off offset:576
	s_waitcnt vmcnt(31)
	s_nop 1
	v_mov_b32_e32 v66, v232
	v_mov_b32_e32 v67, v233
	v_lshlrev_b32_e32 v70, 16, v66
	v_add_u32_e32 v68, s48, v72
	v_ashrrev_i32_e32 v69, 31, v68
	v_lshlrev_b64 v[68:69], 12, v[68:69]
	v_lshl_add_u64 v[68:69], s[8:9], 0, v[68:69]
	v_and_b32_e32 v71, 0xffff0000, v66
	v_lshlrev_b32_e32 v66, 16, v67
	v_and_b32_e32 v67, 0xffff0000, v67
	v_lshl_add_u64 v[68:69], v[68:69], 0, v[142:143]
	v_pk_add_f32 v[64:65], v[64:65], v[66:67]
	v_pk_add_f32 v[62:63], v[62:63], v[70:71]
	global_store_dwordx4 v[68:69], v[62:65], off
	s_waitcnt vmcnt(31)
; __device__ __forceinline__ float bf_lo(unsigned w) { return __uint_as_float(w << 16); }
; __device__ __forceinline__ float bf_hi(unsigned w) { return __uint_as_float(w & 0xffff0000u); }
; #define PG8_BAR __builtin_amdgcn_s_barrier()
;     __device__ __forceinline__ void operator()(const f32x4 (&acc)[2][2][4][2], const Unit& u, int wr, int wc, int fr, int fq) const {
;         const int row0 = u.pm * BM + wr * 64 + fr, col0 = u.pn * BM + wc * 32 + 4 * fq;
; #pragma unroll
;         for (int ai = 0; ai < 2; ++ai)
; #pragma unroll
;             for (int m = 0; m < 4; ++m) { const int lrow = row0 + ai * HALF + m * 16; float* orow = OUT + (size_t)(grow0 + lrow) * 1024; const bf16_t* brow = XB + (size_t)lrow * 1024;
; #pragma unroll
;                 for (int bj = 0; bj < 2; ++bj)
; #pragma unroll
;                     for (int n = 0; n < 2; ++n) { const int c = col0 + bj * HALF + n * 16; const u32x2 xw = *(const u32x2*)(brow + c);
;                         const f32x4 xv = (f32x4){bf_lo(xw.x), bf_hi(xw.x), bf_lo(xw.y), bf_hi(xw.y)}; *(f32x4*)(orow + c) = xv + acc[ai][bj][m][n]; } }
; template <class Epi, class Sched, bool ALIGN_EPI = false, bool SP2 = false>
; __device__ __forceinline__ void gemm_phase(PG8_LAS unsigned char* lds, const Gemm g, const Sched& S, const Epi& E) {
;     ...
;         if (!has_next) break;
; #pragma unroll
;         for (int a = 0; a < 2; ++a)
; #pragma unroll
;             for (int b = 0; b < 2; ++b)
; #pragma unroll
;                 for (int m = 0; m < 4; ++m)
; #pragma unroll
;                     for (int n = 0; n < 2; ++n) acc[a][b][m][n] = (f32x4){0.f, 0.f, 0.f, 0.f};
;         cur = nxt; cA = nA; cB = nB; ++ui;
;         if constexpr (ALIGN_EPI) { if (wr == 1) PG8_BAR; }
	s_nop 1
	v_mov_b32_e32 v62, v234
	v_mov_b32_e32 v63, v235
	v_lshlrev_b32_e32 v64, 16, v62
	v_and_b32_e32 v65, 0xffff0000, v62
	v_lshlrev_b32_e32 v62, 16, v63
	v_and_b32_e32 v63, 0xffff0000, v63
	v_pk_add_f32 v[60:61], v[60:61], v[62:63]
	v_pk_add_f32 v[58:59], v[58:59], v[64:65]
	global_store_dwordx4 v[68:69], v[58:61], off offset:64
	s_waitcnt vmcnt(31)
	s_nop 1
	v_mov_b32_e32 v58, v236
	v_mov_b32_e32 v59, v237
	v_lshlrev_b32_e32 v60, 16, v58
	v_and_b32_e32 v61, 0xffff0000, v58
	v_lshlrev_b32_e32 v58, 16, v59
	v_and_b32_e32 v59, 0xffff0000, v59
	v_pk_add_f32 v[56:57], v[56:57], v[58:59]
	v_pk_add_f32 v[54:55], v[54:55], v[60:61]
	global_store_dwordx4 v[68:69], v[54:57], off offset:512
	s_waitcnt vmcnt(31)
	s_nop 1
	v_mov_b32_e32 v54, v238
	v_mov_b32_e32 v55, v239
	v_lshlrev_b32_e32 v60, 16, v54
	v_add_u32_e32 v56, 0x90, v144
	v_ashrrev_i32_e32 v57, 31, v56
	v_lshlrev_b64 v[58:59], 11, v[56:57]
	v_and_b32_e32 v61, 0xffff0000, v54
	v_lshlrev_b32_e32 v54, 16, v55
	v_and_b32_e32 v55, 0xffff0000, v55
	v_lshl_add_u64 v[58:59], s[14:15], 0, v[58:59]
	v_pk_add_f32 v[48:49], v[48:49], v[54:55]
	v_pk_add_f32 v[46:47], v[46:47], v[60:61]
	v_lshl_add_u64 v[58:59], v[58:59], 0, v[146:147]
	global_store_dwordx4 v[68:69], v[46:49], off offset:576
	s_waitcnt vmcnt(31)
	s_nop 1
	v_mov_b32_e32 v46, v240
	v_mov_b32_e32 v47, v241
	v_and_b32_e32 v57, 0xffff0000, v46
	v_add_u32_e32 v48, s48, v56
	v_ashrrev_i32_e32 v49, 31, v48
	v_lshlrev_b64 v[48:49], 12, v[48:49]
	v_lshl_add_u64 v[48:49], s[8:9], 0, v[48:49]
	v_lshlrev_b32_e32 v56, 16, v46
	v_lshlrev_b32_e32 v46, 16, v47
	v_and_b32_e32 v47, 0xffff0000, v47
	v_lshl_add_u64 v[54:55], v[48:49], 0, v[142:143]
	v_pk_add_f32 v[48:49], v[52:53], v[46:47]
	v_pk_add_f32 v[46:47], v[50:51], v[56:57]
	global_store_dwordx4 v[54:55], v[46:49], off
	s_waitcnt vmcnt(31)
	s_nop 1
	v_mov_b32_e32 v46, v242
	v_mov_b32_e32 v47, v243
	v_lshlrev_b32_e32 v48, 16, v46
	v_and_b32_e32 v49, 0xffff0000, v46
	v_lshlrev_b32_e32 v46, 16, v47
	v_and_b32_e32 v47, 0xffff0000, v47
	v_pk_add_f32 v[44:45], v[44:45], v[46:47]
	v_pk_add_f32 v[42:43], v[42:43], v[48:49]
	global_store_dwordx4 v[54:55], v[42:45], off offset:64
	s_waitcnt vmcnt(31)
	s_nop 1
	v_mov_b32_e32 v42, v244
	v_mov_b32_e32 v43, v245
	v_lshlrev_b32_e32 v44, 16, v42
	v_and_b32_e32 v45, 0xffff0000, v42
	v_lshlrev_b32_e32 v42, 16, v43
	v_and_b32_e32 v43, 0xffff0000, v43
	v_pk_add_f32 v[40:41], v[40:41], v[42:43]
	v_pk_add_f32 v[38:39], v[38:39], v[44:45]
	global_store_dwordx4 v[54:55], v[38:41], off offset:512
	s_waitcnt vmcnt(31)
	s_nop 1
	v_mov_b32_e32 v38, v246
	v_mov_b32_e32 v39, v247
	v_lshlrev_b32_e32 v44, 16, v38
	v_add_u32_e32 v40, 0xa0, v144
	v_ashrrev_i32_e32 v41, 31, v40
	v_lshlrev_b64 v[42:43], 11, v[40:41]
	v_and_b32_e32 v45, 0xffff0000, v38
	v_lshlrev_b32_e32 v38, 16, v39
	v_and_b32_e32 v39, 0xffff0000, v39
	v_lshl_add_u64 v[42:43], s[14:15], 0, v[42:43]
	v_pk_add_f32 v[32:33], v[32:33], v[38:39]
	v_pk_add_f32 v[30:31], v[30:31], v[44:45]
	v_lshl_add_u64 v[42:43], v[42:43], 0, v[146:147]
	global_store_dwordx4 v[54:55], v[30:33], off offset:576
	s_waitcnt vmcnt(28)
	s_nop 1
	v_mov_b32_e32 v30, v200
	v_mov_b32_e32 v31, v201
	v_and_b32_e32 v41, 0xffff0000, v30
	v_add_u32_e32 v32, s48, v40
	v_ashrrev_i32_e32 v33, 31, v32
	v_lshlrev_b64 v[32:33], 12, v[32:33]
	v_lshl_add_u64 v[32:33], s[8:9], 0, v[32:33]
	v_lshlrev_b32_e32 v40, 16, v30
	v_lshlrev_b32_e32 v30, 16, v31
	v_and_b32_e32 v31, 0xffff0000, v31
	v_lshl_add_u64 v[38:39], v[32:33], 0, v[142:143]
	v_pk_add_f32 v[32:33], v[36:37], v[30:31]
	v_pk_add_f32 v[30:31], v[34:35], v[40:41]
	global_store_dwordx4 v[38:39], v[30:33], off
	s_waitcnt vmcnt(28)
	s_nop 1
	v_mov_b32_e32 v30, v202
	v_mov_b32_e32 v31, v203
	v_lshlrev_b32_e32 v32, 16, v30
	v_and_b32_e32 v33, 0xffff0000, v30
	v_lshlrev_b32_e32 v30, 16, v31
	v_and_b32_e32 v31, 0xffff0000, v31
	v_pk_add_f32 v[28:29], v[28:29], v[30:31]
	v_pk_add_f32 v[26:27], v[26:27], v[32:33]
	global_store_dwordx4 v[38:39], v[26:29], off offset:64
	s_waitcnt vmcnt(28)
	s_nop 1
	v_mov_b32_e32 v26, v204
	v_mov_b32_e32 v27, v205
	v_lshlrev_b32_e32 v28, 16, v26
	v_and_b32_e32 v29, 0xffff0000, v26
	v_lshlrev_b32_e32 v26, 16, v27
	v_and_b32_e32 v27, 0xffff0000, v27
	v_pk_add_f32 v[24:25], v[24:25], v[26:27]
	v_pk_add_f32 v[22:23], v[22:23], v[28:29]
	global_store_dwordx4 v[38:39], v[22:25], off offset:512
	s_waitcnt vmcnt(28)
	s_nop 1
	v_mov_b32_e32 v22, v206
	v_mov_b32_e32 v23, v207
	v_lshlrev_b32_e32 v28, 16, v22
	v_add_u32_e32 v24, 0xb0, v144
	v_ashrrev_i32_e32 v25, 31, v24
	v_lshlrev_b64 v[26:27], 11, v[24:25]
	v_and_b32_e32 v29, 0xffff0000, v22
	v_lshlrev_b32_e32 v22, 16, v23
	v_and_b32_e32 v23, 0xffff0000, v23
	v_lshl_add_u64 v[26:27], s[14:15], 0, v[26:27]
	v_pk_add_f32 v[16:17], v[16:17], v[22:23]
	v_pk_add_f32 v[14:15], v[14:15], v[28:29]
	v_lshl_add_u64 v[26:27], v[26:27], 0, v[146:147]
	global_store_dwordx4 v[38:39], v[14:17], off offset:576
	s_waitcnt vmcnt(24)
	s_nop 1
	v_mov_b32_e32 v14, v208
	v_mov_b32_e32 v15, v209
	v_and_b32_e32 v25, 0xffff0000, v14
	v_add_u32_e32 v16, s48, v24
	v_ashrrev_i32_e32 v17, 31, v16
	v_lshlrev_b64 v[16:17], 12, v[16:17]
	v_lshl_add_u64 v[16:17], s[8:9], 0, v[16:17]
	v_lshlrev_b32_e32 v24, 16, v14
	v_lshlrev_b32_e32 v14, 16, v15
	v_and_b32_e32 v15, 0xffff0000, v15
	v_lshl_add_u64 v[22:23], v[16:17], 0, v[142:143]
	v_pk_add_f32 v[16:17], v[20:21], v[14:15]
	v_pk_add_f32 v[14:15], v[18:19], v[24:25]
	global_store_dwordx4 v[22:23], v[14:17], off
	s_waitcnt vmcnt(24)
	s_nop 1
	v_mov_b32_e32 v14, v210
	v_mov_b32_e32 v15, v211
	v_lshlrev_b32_e32 v16, 16, v14
	v_and_b32_e32 v17, 0xffff0000, v14
	v_lshlrev_b32_e32 v14, 16, v15
	v_and_b32_e32 v15, 0xffff0000, v15
	v_pk_add_f32 v[12:13], v[12:13], v[14:15]
	v_pk_add_f32 v[10:11], v[10:11], v[16:17]
	global_store_dwordx4 v[22:23], v[10:13], off offset:64
	s_waitcnt vmcnt(24)
	s_nop 1
	v_mov_b32_e32 v10, v212
	v_mov_b32_e32 v11, v213
	v_lshlrev_b32_e32 v12, 16, v10
	v_and_b32_e32 v13, 0xffff0000, v10
	v_lshlrev_b32_e32 v10, 16, v11
	v_and_b32_e32 v11, 0xffff0000, v11
	v_pk_add_f32 v[8:9], v[8:9], v[10:11]
	v_pk_add_f32 v[6:7], v[6:7], v[12:13]
	global_store_dwordx4 v[22:23], v[6:9], off offset:512
	s_waitcnt vmcnt(24)
	s_nop 1
	v_mov_b32_e32 v6, v214
	v_mov_b32_e32 v7, v215
	v_lshlrev_b32_e32 v8, 16, v6
	v_and_b32_e32 v9, 0xffff0000, v6
	v_lshlrev_b32_e32 v6, 16, v7
	v_and_b32_e32 v7, 0xffff0000, v7
	v_pk_add_f32 v[4:5], v[4:5], v[6:7]
	v_pk_add_f32 v[2:3], v[2:3], v[8:9]
	global_store_dwordx4 v[22:23], v[2:5], off offset:576
	s_cbranch_vccnz .LBB0_1027
	s_andn2_b64 vcc, exec, s[10:11]
	s_cbranch_vccnz .LBB0_1026
	s_barrier
	s_branch .LBB0_1026
